# write-through (sc1) 16-byte epilogue stores in P3-P9 GEMM phases so the grid-barrier release fence finds a clean L2
# baseline (speedup 1.0000x reference)
.LBB0_643:
	s_add_u32 s14, s10, s12
	ds_read_b128 v[144:147], v138
	ds_read_b128 v[148:151], v138 offset:1024
	ds_read_b128 v[152:155], v138 offset:2048
	ds_read_b128 v[156:159], v138 offset:3072
	s_addc_u32 s15, s11, s13
	s_add_u32 s14, s14, 0x159a4100
	s_addc_u32 s15, s15, 0
	s_add_u32 s47, s42, s12
	s_addc_u32 s48, s43, s13
	s_cmpk_eq_i32 s12, 0x700
	s_cselect_b32 s17, s5, s15
	s_cselect_b32 s16, s4, s14
	s_cselect_b32 s15, s7, s48
	s_cselect_b32 s14, s6, s47
	s_mov_b32 m0, s45
	v_lshl_add_u64 v[192:193], v[132:133], 0, s[12:13]
	ds_read_b128 v[160:163], v139
	ds_read_b128 v[164:167], v139 offset:1024
	ds_read_b128 v[168:171], v139 offset:2048
	ds_read_b128 v[172:175], v139 offset:3072
	ds_read_b128 v[176:179], v139 offset:4096
	ds_read_b128 v[180:183], v139 offset:5120
	ds_read_b128 v[184:187], v139 offset:6144
	ds_read_b128 v[188:191], v139 offset:7168
	global_load_lds_dwordx4 v[192:193], off
	v_lshl_add_u64 v[192:193], v[134:135], 0, s[12:13]
	s_mov_b32 m0, s46
	s_nop 0
	global_load_lds_dwordx4 v[192:193], off
	ds_read_b128 v[192:195], v140
	ds_read_b128 v[196:199], v140 offset:1024
	ds_read_b128 v[204:207], v140 offset:2048
	ds_read_b128 v[208:211], v140 offset:3072
	s_waitcnt lgkmcnt(0)
	s_waitcnt vmcnt(8)
	s_barrier
	s_setprio 1
	v_mfma_f32_16x16x32_bf16 v[124:127], v[144:147], v[160:163], v[124:127]
	v_mfma_f32_16x16x32_bf16 v[120:123], v[152:155], v[160:163], v[120:123]
	v_mfma_f32_16x16x32_bf16 v[108:111], v[144:147], v[168:171], v[108:111]
	v_mfma_f32_16x16x32_bf16 v[104:107], v[152:155], v[168:171], v[104:107]
	v_mfma_f32_16x16x32_bf16 v[92:95], v[144:147], v[176:179], v[92:95]
	v_mfma_f32_16x16x32_bf16 v[88:91], v[152:155], v[176:179], v[88:91]
	v_mfma_f32_16x16x32_bf16 v[76:79], v[144:147], v[184:187], v[76:79]
	v_mfma_f32_16x16x32_bf16 v[72:75], v[152:155], v[184:187], v[72:75]
	v_mfma_f32_16x16x32_bf16 v[124:127], v[148:151], v[164:167], v[124:127]
	v_mfma_f32_16x16x32_bf16 v[120:123], v[156:159], v[164:167], v[120:123]
	v_mfma_f32_16x16x32_bf16 v[108:111], v[148:151], v[172:175], v[108:111]
	v_mfma_f32_16x16x32_bf16 v[104:107], v[156:159], v[172:175], v[104:107]
	v_mfma_f32_16x16x32_bf16 v[92:95], v[148:151], v[180:183], v[92:95]
	v_mfma_f32_16x16x32_bf16 v[88:91], v[156:159], v[180:183], v[88:91]
	v_mfma_f32_16x16x32_bf16 v[76:79], v[148:151], v[188:191], v[76:79]
	v_mfma_f32_16x16x32_bf16 v[72:75], v[156:159], v[188:191], v[72:75]
	v_mfma_f32_16x16x32_bf16 v[116:119], v[192:195], v[160:163], v[116:119]
	v_mfma_f32_16x16x32_bf16 v[112:115], v[204:207], v[160:163], v[112:115]
	v_mfma_f32_16x16x32_bf16 v[100:103], v[192:195], v[168:171], v[100:103]
	v_mfma_f32_16x16x32_bf16 v[96:99], v[204:207], v[168:171], v[96:99]
	v_mfma_f32_16x16x32_bf16 v[84:87], v[192:195], v[176:179], v[84:87]
	v_mfma_f32_16x16x32_bf16 v[80:83], v[204:207], v[176:179], v[80:83]
	v_mfma_f32_16x16x32_bf16 v[68:71], v[192:195], v[184:187], v[68:71]
	v_mfma_f32_16x16x32_bf16 v[64:67], v[204:207], v[184:187], v[64:67]
	v_mfma_f32_16x16x32_bf16 v[116:119], v[196:199], v[164:167], v[116:119]
	v_mfma_f32_16x16x32_bf16 v[112:115], v[208:211], v[164:167], v[112:115]
	v_mfma_f32_16x16x32_bf16 v[100:103], v[196:199], v[172:175], v[100:103]
	v_mfma_f32_16x16x32_bf16 v[96:99], v[208:211], v[172:175], v[96:99]
	v_mfma_f32_16x16x32_bf16 v[84:87], v[196:199], v[180:183], v[84:87]
	v_mfma_f32_16x16x32_bf16 v[80:83], v[208:211], v[180:183], v[80:83]
	v_mfma_f32_16x16x32_bf16 v[68:71], v[196:199], v[188:191], v[68:71]
	v_mfma_f32_16x16x32_bf16 v[64:67], v[208:211], v[188:191], v[64:67]
	s_setprio 0
	s_barrier
	ds_read_b128 v[160:163], v139 offset:16384
	ds_read_b128 v[164:167], v139 offset:17408
	ds_read_b128 v[168:171], v139 offset:18432
	ds_read_b128 v[172:175], v139 offset:19456
	ds_read_b128 v[176:179], v139 offset:20480
	ds_read_b128 v[180:183], v139 offset:21504
	ds_read_b128 v[184:187], v139 offset:22528
	ds_read_b128 v[188:191], v139 offset:23552
	s_mov_b32 m0, s1
	v_lshl_add_u64 v[200:201], s[14:15], 0, v[130:131]
	global_load_lds_dwordx4 v[200:201], off
	v_lshl_add_u64 v[212:213], s[14:15], 0, v[128:129]
	s_mov_b32 m0, s28
	s_nop 0
	global_load_lds_dwordx4 v[212:213], off
	s_mov_b32 m0, s29
	v_lshl_add_u64 v[214:215], s[16:17], 0, v[130:131]
	global_load_lds_dwordx4 v[214:215], off
	v_lshl_add_u64 v[216:217], s[16:17], 0, v[128:129]
	s_mov_b32 m0, s30
	s_nop 0
	global_load_lds_dwordx4 v[216:217], off
	s_add_u32 s48, s14, 0x40000
	s_addc_u32 s49, s15, 0
	s_mov_b32 m0, s31
	v_lshl_add_u64 v[248:249], s[48:49], 0, v[130:131]
	global_load_lds_dwordx4 v[248:249], off
	v_lshl_add_u64 v[248:249], s[48:49], 0, v[128:129]
	s_mov_b32 m0, s33
	s_nop 0
	global_load_lds_dwordx4 v[248:249], off
	s_waitcnt lgkmcnt(0)
	s_waitcnt vmcnt(8)
	s_barrier
	s_setprio 1
	v_mfma_f32_16x16x32_bf16 v[60:63], v[144:147], v[160:163], v[60:63]
	v_mfma_f32_16x16x32_bf16 v[56:59], v[152:155], v[160:163], v[56:59]
	v_mfma_f32_16x16x32_bf16 v[44:47], v[144:147], v[168:171], v[44:47]
	v_mfma_f32_16x16x32_bf16 v[40:43], v[152:155], v[168:171], v[40:43]
	v_mfma_f32_16x16x32_bf16 v[28:31], v[144:147], v[176:179], v[28:31]
	v_mfma_f32_16x16x32_bf16 v[24:27], v[152:155], v[176:179], v[24:27]
	v_mfma_f32_16x16x32_bf16 v[12:15], v[144:147], v[184:187], v[12:15]
	v_mfma_f32_16x16x32_bf16 v[8:11], v[152:155], v[184:187], v[8:11]
	v_mfma_f32_16x16x32_bf16 v[60:63], v[148:151], v[164:167], v[60:63]
	v_mfma_f32_16x16x32_bf16 v[56:59], v[156:159], v[164:167], v[56:59]
	v_mfma_f32_16x16x32_bf16 v[44:47], v[148:151], v[172:175], v[44:47]
	v_mfma_f32_16x16x32_bf16 v[40:43], v[156:159], v[172:175], v[40:43]
	v_mfma_f32_16x16x32_bf16 v[28:31], v[148:151], v[180:183], v[28:31]
	v_mfma_f32_16x16x32_bf16 v[24:27], v[156:159], v[180:183], v[24:27]
	v_mfma_f32_16x16x32_bf16 v[12:15], v[148:151], v[188:191], v[12:15]
	v_mfma_f32_16x16x32_bf16 v[8:11], v[156:159], v[188:191], v[8:11]
	v_mfma_f32_16x16x32_bf16 v[52:55], v[192:195], v[160:163], v[52:55]
	v_mfma_f32_16x16x32_bf16 v[48:51], v[204:207], v[160:163], v[48:51]
	v_mfma_f32_16x16x32_bf16 v[36:39], v[192:195], v[168:171], v[36:39]
	v_mfma_f32_16x16x32_bf16 v[32:35], v[204:207], v[168:171], v[32:35]
	v_mfma_f32_16x16x32_bf16 v[20:23], v[192:195], v[176:179], v[20:23]
	v_mfma_f32_16x16x32_bf16 v[16:19], v[204:207], v[176:179], v[16:19]
	v_mfma_f32_16x16x32_bf16 v[4:7], v[192:195], v[184:187], v[4:7]
	v_mfma_f32_16x16x32_bf16 v[0:3], v[204:207], v[184:187], v[0:3]
	v_mfma_f32_16x16x32_bf16 v[52:55], v[196:199], v[164:167], v[52:55]
	v_mfma_f32_16x16x32_bf16 v[48:51], v[208:211], v[164:167], v[48:51]
	v_mfma_f32_16x16x32_bf16 v[36:39], v[196:199], v[172:175], v[36:39]
	v_mfma_f32_16x16x32_bf16 v[32:35], v[208:211], v[172:175], v[32:35]
	v_mfma_f32_16x16x32_bf16 v[20:23], v[196:199], v[180:183], v[20:23]
	v_mfma_f32_16x16x32_bf16 v[16:19], v[208:211], v[180:183], v[16:19]
	v_mfma_f32_16x16x32_bf16 v[4:7], v[196:199], v[188:191], v[4:7]
	v_mfma_f32_16x16x32_bf16 v[0:3], v[208:211], v[188:191], v[0:3]
	s_setprio 0
	s_barrier
	ds_read_b128 v[144:147], v141
	ds_read_b128 v[148:151], v141 offset:1024
	ds_read_b128 v[152:155], v141 offset:2048
	ds_read_b128 v[156:159], v141 offset:3072
	s_add_u32 s16, s16, 0x40000
	s_addc_u32 s17, s17, 0
	s_mov_b32 m0, s34
	v_lshl_add_u64 v[192:193], s[16:17], 0, v[130:131]
	ds_read_b128 v[160:163], v139 offset:32768
	ds_read_b128 v[164:167], v139 offset:33792
	ds_read_b128 v[168:171], v139 offset:34816
	ds_read_b128 v[172:175], v139 offset:35840
	ds_read_b128 v[176:179], v139 offset:36864
	ds_read_b128 v[180:183], v139 offset:37888
	ds_read_b128 v[184:187], v139 offset:38912
	ds_read_b128 v[188:191], v139 offset:39936
	global_load_lds_dwordx4 v[192:193], off
	v_lshl_add_u64 v[192:193], s[16:17], 0, v[128:129]
	s_mov_b32 m0, s35
	s_nop 0
	global_load_lds_dwordx4 v[192:193], off
	ds_read_b128 v[192:195], v142
	ds_read_b128 v[196:199], v142 offset:1024
	ds_read_b128 v[204:207], v142 offset:2048
	ds_read_b128 v[208:211], v142 offset:3072
	s_waitcnt lgkmcnt(0)
	s_waitcnt vmcnt(8)
	s_barrier
	s_setprio 1
	v_mfma_f32_16x16x32_bf16 v[124:127], v[144:147], v[160:163], v[124:127]
	v_mfma_f32_16x16x32_bf16 v[120:123], v[152:155], v[160:163], v[120:123]
	v_mfma_f32_16x16x32_bf16 v[108:111], v[144:147], v[168:171], v[108:111]
	v_mfma_f32_16x16x32_bf16 v[104:107], v[152:155], v[168:171], v[104:107]
	v_mfma_f32_16x16x32_bf16 v[92:95], v[144:147], v[176:179], v[92:95]
	v_mfma_f32_16x16x32_bf16 v[88:91], v[152:155], v[176:179], v[88:91]
	v_mfma_f32_16x16x32_bf16 v[76:79], v[144:147], v[184:187], v[76:79]
	v_mfma_f32_16x16x32_bf16 v[72:75], v[152:155], v[184:187], v[72:75]
	v_mfma_f32_16x16x32_bf16 v[124:127], v[148:151], v[164:167], v[124:127]
	v_mfma_f32_16x16x32_bf16 v[120:123], v[156:159], v[164:167], v[120:123]
	v_mfma_f32_16x16x32_bf16 v[108:111], v[148:151], v[172:175], v[108:111]
	v_mfma_f32_16x16x32_bf16 v[104:107], v[156:159], v[172:175], v[104:107]
	v_mfma_f32_16x16x32_bf16 v[92:95], v[148:151], v[180:183], v[92:95]
	v_mfma_f32_16x16x32_bf16 v[88:91], v[156:159], v[180:183], v[88:91]
	v_mfma_f32_16x16x32_bf16 v[76:79], v[148:151], v[188:191], v[76:79]
	v_mfma_f32_16x16x32_bf16 v[72:75], v[156:159], v[188:191], v[72:75]
	v_mfma_f32_16x16x32_bf16 v[116:119], v[192:195], v[160:163], v[116:119]
	v_mfma_f32_16x16x32_bf16 v[112:115], v[204:207], v[160:163], v[112:115]
	v_mfma_f32_16x16x32_bf16 v[100:103], v[192:195], v[168:171], v[100:103]
	v_mfma_f32_16x16x32_bf16 v[96:99], v[204:207], v[168:171], v[96:99]
	v_mfma_f32_16x16x32_bf16 v[84:87], v[192:195], v[176:179], v[84:87]
	v_mfma_f32_16x16x32_bf16 v[80:83], v[204:207], v[176:179], v[80:83]
	v_mfma_f32_16x16x32_bf16 v[68:71], v[192:195], v[184:187], v[68:71]
	v_mfma_f32_16x16x32_bf16 v[64:67], v[204:207], v[184:187], v[64:67]
	v_mfma_f32_16x16x32_bf16 v[116:119], v[196:199], v[164:167], v[116:119]
	v_mfma_f32_16x16x32_bf16 v[112:115], v[208:211], v[164:167], v[112:115]
	v_mfma_f32_16x16x32_bf16 v[100:103], v[196:199], v[172:175], v[100:103]
	v_mfma_f32_16x16x32_bf16 v[96:99], v[208:211], v[172:175], v[96:99]
	v_mfma_f32_16x16x32_bf16 v[84:87], v[196:199], v[180:183], v[84:87]
	v_mfma_f32_16x16x32_bf16 v[80:83], v[208:211], v[180:183], v[80:83]
	v_mfma_f32_16x16x32_bf16 v[68:71], v[196:199], v[188:191], v[68:71]
	v_mfma_f32_16x16x32_bf16 v[64:67], v[208:211], v[188:191], v[64:67]
	s_setprio 0
	s_barrier
	ds_read_b128 v[160:163], v139 offset:49152
	ds_read_b128 v[164:167], v139 offset:50176
	ds_read_b128 v[168:171], v139 offset:51200
	ds_read_b128 v[172:175], v139 offset:52224
	ds_read_b128 v[176:179], v139 offset:53248
	ds_read_b128 v[180:183], v139 offset:54272
	ds_read_b128 v[184:187], v139 offset:55296
	ds_read_b128 v[188:191], v139 offset:56320
	s_mov_b32 m0, s36
	v_lshl_add_u64 v[200:201], v[200:201], 0, s[8:9]
	global_load_lds_dwordx4 v[200:201], off
	v_lshl_add_u64 v[200:201], v[212:213], 0, s[8:9]
	s_mov_b32 m0, s37
	s_nop 0
	global_load_lds_dwordx4 v[200:201], off
	s_mov_b32 m0, s38
	v_lshl_add_u64 v[200:201], v[214:215], 0, s[8:9]
	global_load_lds_dwordx4 v[200:201], off
	v_lshl_add_u64 v[200:201], v[216:217], 0, s[8:9]
	s_mov_b32 m0, s39
	s_nop 0
	global_load_lds_dwordx4 v[200:201], off
	s_add_u32 s14, s14, 0x40080
	s_addc_u32 s15, s15, 0
	s_mov_b32 m0, s40
	v_lshl_add_u64 v[248:249], s[14:15], 0, v[130:131]
	global_load_lds_dwordx4 v[248:249], off
	v_lshl_add_u64 v[248:249], s[14:15], 0, v[128:129]
	s_mov_b32 m0, s41
	s_nop 0
	global_load_lds_dwordx4 v[248:249], off
	s_waitcnt lgkmcnt(0)
	s_waitcnt vmcnt(8)
	s_barrier
	s_setprio 1
	v_mfma_f32_16x16x32_bf16 v[60:63], v[144:147], v[160:163], v[60:63]
	v_mfma_f32_16x16x32_bf16 v[56:59], v[152:155], v[160:163], v[56:59]
	v_mfma_f32_16x16x32_bf16 v[44:47], v[144:147], v[168:171], v[44:47]
	v_mfma_f32_16x16x32_bf16 v[40:43], v[152:155], v[168:171], v[40:43]
	v_mfma_f32_16x16x32_bf16 v[28:31], v[144:147], v[176:179], v[28:31]
	v_mfma_f32_16x16x32_bf16 v[24:27], v[152:155], v[176:179], v[24:27]
	v_mfma_f32_16x16x32_bf16 v[12:15], v[144:147], v[184:187], v[12:15]
	v_mfma_f32_16x16x32_bf16 v[8:11], v[152:155], v[184:187], v[8:11]
	v_mfma_f32_16x16x32_bf16 v[60:63], v[148:151], v[164:167], v[60:63]
	v_mfma_f32_16x16x32_bf16 v[56:59], v[156:159], v[164:167], v[56:59]
	v_mfma_f32_16x16x32_bf16 v[44:47], v[148:151], v[172:175], v[44:47]
	v_mfma_f32_16x16x32_bf16 v[40:43], v[156:159], v[172:175], v[40:43]
	v_mfma_f32_16x16x32_bf16 v[28:31], v[148:151], v[180:183], v[28:31]
	v_mfma_f32_16x16x32_bf16 v[24:27], v[156:159], v[180:183], v[24:27]
	v_mfma_f32_16x16x32_bf16 v[12:15], v[148:151], v[188:191], v[12:15]
	v_mfma_f32_16x16x32_bf16 v[8:11], v[156:159], v[188:191], v[8:11]
	v_mfma_f32_16x16x32_bf16 v[52:55], v[192:195], v[160:163], v[52:55]
	v_mfma_f32_16x16x32_bf16 v[48:51], v[204:207], v[160:163], v[48:51]
	v_mfma_f32_16x16x32_bf16 v[36:39], v[192:195], v[168:171], v[36:39]
	v_mfma_f32_16x16x32_bf16 v[32:35], v[204:207], v[168:171], v[32:35]
	v_mfma_f32_16x16x32_bf16 v[20:23], v[192:195], v[176:179], v[20:23]
	v_mfma_f32_16x16x32_bf16 v[16:19], v[204:207], v[176:179], v[16:19]
	v_mfma_f32_16x16x32_bf16 v[4:7], v[192:195], v[184:187], v[4:7]
	v_mfma_f32_16x16x32_bf16 v[0:3], v[204:207], v[184:187], v[0:3]
	v_mfma_f32_16x16x32_bf16 v[52:55], v[196:199], v[164:167], v[52:55]
	v_mfma_f32_16x16x32_bf16 v[48:51], v[208:211], v[164:167], v[48:51]
	v_mfma_f32_16x16x32_bf16 v[36:39], v[196:199], v[172:175], v[36:39]
	v_mfma_f32_16x16x32_bf16 v[32:35], v[208:211], v[172:175], v[32:35]
	v_mfma_f32_16x16x32_bf16 v[20:23], v[196:199], v[180:183], v[20:23]
	v_mfma_f32_16x16x32_bf16 v[16:19], v[208:211], v[180:183], v[16:19]
	v_mfma_f32_16x16x32_bf16 v[4:7], v[196:199], v[188:191], v[4:7]
	v_mfma_f32_16x16x32_bf16 v[0:3], v[208:211], v[188:191], v[0:3]
	s_setprio 0
	s_add_i32 s44, s44, 2
	s_add_u32 s12, s12, 0x100
	s_addc_u32 s13, s13, 0
	s_cmp_gt_u32 s44, 13
	s_barrier
	s_cbranch_scc0 .LBB0_643
	v_lshlrev_b32_e32 v128, 3, v136
	v_lshl_or_b32 v128, s26, 6, v128
	s_add_u32 s4, s22, 0x1c00000
	v_lshl_or_b32 v128, s0, 8, v128
	v_mov_b32_e32 v165, 0
	s_addc_u32 s5, s23, 0
	v_lshl_add_u32 v160, s27, 8, v137
	v_lshlrev_b32_e32 v164, 1, v128
	v_mov_b32_e32 v161, v165
	v_lshl_add_u64 v[128:129], s[4:5], 0, v[164:165]
	v_lshlrev_b64 v[174:175], 11, v[160:161]
	v_lshl_add_u64 v[130:131], v[128:129], 0, v[174:175]
	global_load_dwordx4 v[176:179], v[130:131], off
	global_load_dwordx4 v[180:183], v[130:131], off offset:64
	v_or_b32_e32 v130, 16, v160
	v_mov_b32_e32 v131, v165
	v_add_u32_e32 v168, 0x80, v160
	v_mov_b32_e32 v169, v165
	v_or_b32_e32 v132, 32, v160
	v_mov_b32_e32 v133, v165
	v_lshlrev_b64 v[172:173], 11, v[130:131]
	v_lshlrev_b64 v[130:131], 11, v[168:169]
	v_or_b32_e32 v134, 48, v160
	v_mov_b32_e32 v135, v165
	v_lshlrev_b64 v[170:171], 11, v[132:133]
	v_lshl_add_u64 v[130:131], s[4:5], 0, v[130:131]
	v_cmp_eq_u32_e32 vcc, 0, v136
	v_lshlrev_b64 v[166:167], 11, v[134:135]
	v_lshl_add_u64 v[162:163], v[130:131], 0, v[164:165]
	v_lshl_add_u64 v[136:137], v[128:129], 0, v[172:173]
	v_lshl_add_u64 v[138:139], v[128:129], 0, v[170:171]
	v_lshl_add_u64 v[184:185], v[128:129], 0, v[166:167]
	global_load_dwordx4 v[132:135], v[162:163], off
	global_load_dwordx4 v[128:131], v[162:163], off offset:64
	global_load_dwordx4 v[156:159], v[136:137], off
	global_load_dwordx4 v[152:155], v[136:137], off offset:64
	global_load_dwordx4 v[148:151], v[138:139], off
	global_load_dwordx4 v[144:147], v[138:139], off offset:64
	global_load_dwordx4 v[140:143], v[184:185], off
	s_nop 0
	global_load_dwordx4 v[136:139], v[184:185], off offset:64
	v_mbcnt_lo_u32_b32 v186, -1, 0
	v_mbcnt_hi_u32_b32 v169, -1, v186
	v_and_b32_e32 v185, 64, v169
	v_xor_b32_e32 v184, 16, v169
	v_add_u32_e32 v185, 64, v185
	v_xor_b32_e32 v186, 32, v169
	v_cmp_lt_i32_e64 s[0:1], v184, v185
	v_lshl_add_u64 v[174:175], s[4:5], 0, v[174:175]
	s_add_u32 s6, s22, 0x18ba4000
	v_cndmask_b32_e64 v187, v169, v184, s[0:1]
	v_cmp_lt_i32_e64 s[0:1], v186, v185
	v_lshl_add_u64 v[184:185], v[174:175], 0, v[164:165]
	v_lshlrev_b32_e32 v174, 2, v187
	v_cndmask_b32_e64 v169, v169, v186, s[0:1]
	v_lshlrev_b32_e32 v169, 2, v169
	s_addc_u32 s7, s23, 0
	s_and_b32 s8, s25, -4
	s_or_b32 s9, s26, s8
	s_mul_hi_u32 s8, s9, 0x21000
	s_mul_i32 s9, s9, 0x21000
	s_waitcnt vmcnt(0)
	v_lshlrev_b32_e32 v186, 16, v176
	v_and_b32_e32 v187, 0xffff0000, v176
	v_lshlrev_b32_e32 v176, 16, v177
	v_and_b32_e32 v177, 0xffff0000, v177
	v_lshlrev_b32_e32 v192, 16, v182
	v_and_b32_e32 v193, 0xffff0000, v182
	v_lshlrev_b32_e32 v182, 16, v183
	v_and_b32_e32 v183, 0xffff0000, v183
	v_pk_add_f32 v[126:127], v[126:127], v[176:177]
	v_pk_add_f32 v[124:125], v[124:125], v[186:187]
	v_lshlrev_b32_e32 v188, 16, v178
	v_and_b32_e32 v189, 0xffff0000, v178
	v_lshlrev_b32_e32 v178, 16, v179
	v_and_b32_e32 v179, 0xffff0000, v179
	v_pk_add_f32 v[176:177], v[114:115], v[182:183]
	v_mul_f32_e32 v114, v125, v125
	v_mul_f32_e32 v115, v127, v127
	v_pk_add_f32 v[122:123], v[122:123], v[178:179]
	v_pk_add_f32 v[120:121], v[120:121], v[188:189]
	v_fmac_f32_e32 v114, v124, v124
	v_fmac_f32_e32 v115, v126, v126
	v_pk_add_f32 v[178:179], v[112:113], v[192:193]
	v_cvt_pk_bf16_f32 v112, v124, v125
	v_add_f32_e32 v114, v114, v115
	v_mul_f32_e32 v115, v121, v121
	v_mul_f32_e32 v124, v123, v123
	v_lshlrev_b32_e32 v190, 16, v180
	v_and_b32_e32 v191, 0xffff0000, v180
	v_lshlrev_b32_e32 v180, 16, v181
	v_and_b32_e32 v181, 0xffff0000, v181
	v_fmac_f32_e32 v115, v120, v120
	v_fmac_f32_e32 v124, v122, v122
	v_pk_add_f32 v[118:119], v[118:119], v[180:181]
	v_pk_add_f32 v[116:117], v[116:117], v[190:191]
	v_add_f32_e32 v115, v115, v124
	v_add_f32_e32 v114, v114, v115
	v_mul_f32_e32 v115, v117, v117
	v_mul_f32_e32 v124, v119, v119
	v_fmac_f32_e32 v115, v116, v116
	v_fmac_f32_e32 v124, v118, v118
	v_add_f32_e32 v115, v115, v124
	v_mul_f32_e32 v124, v179, v179
	v_mul_f32_e32 v125, v177, v177
	v_fmac_f32_e32 v124, v178, v178
	v_fmac_f32_e32 v125, v176, v176
	v_add_f32_e32 v124, v124, v125
	v_add_f32_e32 v115, v115, v124
	v_add_f32_e32 v124, v114, v115
	ds_bpermute_b32 v125, v174, v124
	v_cvt_pk_bf16_f32 v113, v126, v127
	v_cvt_pk_bf16_f32 v114, v120, v121
	v_cvt_pk_bf16_f32 v115, v122, v123
	global_store_dwordx4 v[184:185], v[112:115], off sc1
	s_waitcnt lgkmcnt(0)
	s_nop 0
	v_add_f32_e32 v112, v124, v125
	ds_bpermute_b32 v113, v169, v112
	v_cvt_pk_bf16_f32 v114, v116, v117
	v_cvt_pk_bf16_f32 v115, v118, v119
	v_cvt_pk_bf16_f32 v116, v178, v179
	v_cvt_pk_bf16_f32 v117, v176, v177
	global_store_dwordx4 v[184:185], v[114:117], off offset:64 sc1
	s_and_saveexec_b64 s[0:1], vcc
	s_cbranch_execz .LBB0_646
	s_add_u32 s10, s6, s9
	s_addc_u32 s11, s7, s8
	s_waitcnt lgkmcnt(0)
	v_add_f32_e32 v114, v112, v113
	v_lshl_add_u64 v[112:113], v[160:161], 2, s[10:11]
	global_store_dword v[112:113], v114, off
.LBB0_646:
	s_or_b64 exec, exec, s[0:1]
	v_or_b32_e32 v112, 16, v168
	s_waitcnt lgkmcnt(0)
	v_mov_b32_e32 v113, v165
	v_lshlrev_b64 v[112:113], 11, v[112:113]
	v_lshl_add_u64 v[112:113], s[4:5], 0, v[112:113]
	v_lshl_add_u64 v[120:121], v[112:113], 0, v[164:165]
	global_load_dwordx4 v[116:119], v[120:121], off
	global_load_dwordx4 v[112:115], v[120:121], off offset:64
	v_lshlrev_b32_e32 v124, 16, v157
	v_and_b32_e32 v125, 0xffff0000, v157
	v_lshlrev_b32_e32 v122, 16, v156
	v_and_b32_e32 v123, 0xffff0000, v156
	v_pk_add_f32 v[110:111], v[110:111], v[124:125]
	v_lshlrev_b32_e32 v124, 16, v159
	v_and_b32_e32 v125, 0xffff0000, v159
	v_pk_add_f32 v[108:109], v[108:109], v[122:123]
	v_lshlrev_b32_e32 v122, 16, v158
	v_and_b32_e32 v123, 0xffff0000, v158
	v_pk_add_f32 v[106:107], v[106:107], v[124:125]
	v_lshlrev_b32_e32 v124, 16, v153
	v_and_b32_e32 v125, 0xffff0000, v153
	v_pk_add_f32 v[104:105], v[104:105], v[122:123]
	v_lshlrev_b32_e32 v122, 16, v152
	v_and_b32_e32 v123, 0xffff0000, v152
	v_pk_add_f32 v[102:103], v[102:103], v[124:125]
	v_lshlrev_b32_e32 v124, 16, v155
	v_and_b32_e32 v125, 0xffff0000, v155
	v_pk_add_f32 v[100:101], v[100:101], v[122:123]
	v_lshlrev_b32_e32 v122, 16, v154
	v_and_b32_e32 v123, 0xffff0000, v154
	v_pk_add_f32 v[124:125], v[98:99], v[124:125]
	v_mul_f32_e32 v98, v109, v109
	v_mul_f32_e32 v99, v111, v111
	v_pk_add_f32 v[122:123], v[96:97], v[122:123]
	v_lshl_add_u64 v[96:97], s[4:5], 0, v[172:173]
	v_fmac_f32_e32 v98, v108, v108
	v_fmac_f32_e32 v99, v110, v110
	v_lshl_add_u64 v[126:127], v[96:97], 0, v[164:165]
	v_cvt_pk_bf16_f32 v96, v108, v109
	v_add_f32_e32 v98, v98, v99
	v_mul_f32_e32 v99, v105, v105
	v_mul_f32_e32 v108, v107, v107
	v_fmac_f32_e32 v99, v104, v104
	v_fmac_f32_e32 v108, v106, v106
	v_add_f32_e32 v99, v99, v108
	v_add_f32_e32 v98, v98, v99
	v_mul_f32_e32 v99, v101, v101
	v_mul_f32_e32 v108, v103, v103
	v_fmac_f32_e32 v99, v100, v100
	v_fmac_f32_e32 v108, v102, v102
	v_add_f32_e32 v99, v99, v108
	v_mul_f32_e32 v108, v123, v123
	v_mul_f32_e32 v109, v125, v125
	v_fmac_f32_e32 v108, v122, v122
	v_fmac_f32_e32 v109, v124, v124
	v_add_f32_e32 v108, v108, v109
	v_add_f32_e32 v99, v99, v108
	v_add_f32_e32 v108, v98, v99
	ds_bpermute_b32 v109, v174, v108
	v_cvt_pk_bf16_f32 v97, v110, v111
	v_cvt_pk_bf16_f32 v98, v104, v105
	v_cvt_pk_bf16_f32 v99, v106, v107
	global_store_dwordx4 v[126:127], v[96:99], off sc1
	s_waitcnt lgkmcnt(0)
	s_nop 0
	v_add_f32_e32 v96, v108, v109
	ds_bpermute_b32 v97, v169, v96
	v_cvt_pk_bf16_f32 v98, v100, v101
	v_cvt_pk_bf16_f32 v99, v102, v103
	v_cvt_pk_bf16_f32 v100, v122, v123
	v_cvt_pk_bf16_f32 v101, v124, v125
	global_store_dwordx4 v[126:127], v[98:101], off offset:64 sc1
	s_and_saveexec_b64 s[0:1], vcc
	v_readlane_b32 s30, v246, 60
	v_readlane_b32 s31, v246, 61
	s_cbranch_execz .LBB0_648
	s_add_u32 s10, s6, s9
	s_addc_u32 s11, s7, s8
	s_waitcnt lgkmcnt(0)
	v_add_f32_e32 v98, v96, v97
	v_lshl_add_u64 v[96:97], v[160:161], 2, s[10:11]
	global_store_dword v[96:97], v98, off offset:64
.LBB0_648:
	s_or_b64 exec, exec, s[0:1]
	v_mov_b32_e32 v165, 0
	v_or_b32_e32 v96, 32, v168
	s_waitcnt lgkmcnt(0)
	v_mov_b32_e32 v97, v165
	v_lshlrev_b64 v[96:97], 11, v[96:97]
	v_lshl_add_u64 v[96:97], s[4:5], 0, v[96:97]
	v_lshl_add_u64 v[104:105], v[96:97], 0, v[164:165]
	global_load_dwordx4 v[100:103], v[104:105], off
	global_load_dwordx4 v[96:99], v[104:105], off offset:64
	v_lshlrev_b32_e32 v108, 16, v149
	v_and_b32_e32 v109, 0xffff0000, v149
	v_lshlrev_b32_e32 v106, 16, v148
	v_and_b32_e32 v107, 0xffff0000, v148
	v_pk_add_f32 v[94:95], v[94:95], v[108:109]
	v_lshlrev_b32_e32 v108, 16, v151
	v_and_b32_e32 v109, 0xffff0000, v151
	v_pk_add_f32 v[92:93], v[92:93], v[106:107]
	v_lshlrev_b32_e32 v106, 16, v150
	v_and_b32_e32 v107, 0xffff0000, v150
	v_pk_add_f32 v[90:91], v[90:91], v[108:109]
	v_lshlrev_b32_e32 v108, 16, v145
	v_and_b32_e32 v109, 0xffff0000, v145
	v_pk_add_f32 v[88:89], v[88:89], v[106:107]
	v_lshlrev_b32_e32 v106, 16, v144
	v_and_b32_e32 v107, 0xffff0000, v144
	v_pk_add_f32 v[86:87], v[86:87], v[108:109]
	v_lshlrev_b32_e32 v108, 16, v147
	v_and_b32_e32 v109, 0xffff0000, v147
	v_pk_add_f32 v[84:85], v[84:85], v[106:107]
	v_lshlrev_b32_e32 v106, 16, v146
	v_and_b32_e32 v107, 0xffff0000, v146
	v_pk_add_f32 v[108:109], v[82:83], v[108:109]
	v_mul_f32_e32 v82, v93, v93
	v_mul_f32_e32 v83, v95, v95
	v_pk_add_f32 v[106:107], v[80:81], v[106:107]
	v_lshl_add_u64 v[80:81], s[4:5], 0, v[170:171]
	v_fmac_f32_e32 v82, v92, v92
	v_fmac_f32_e32 v83, v94, v94
	v_lshl_add_u64 v[110:111], v[80:81], 0, v[164:165]
	v_cvt_pk_bf16_f32 v80, v92, v93
	v_add_f32_e32 v82, v82, v83
	v_mul_f32_e32 v83, v89, v89
	v_mul_f32_e32 v92, v91, v91
	v_fmac_f32_e32 v83, v88, v88
	v_fmac_f32_e32 v92, v90, v90
	v_add_f32_e32 v83, v83, v92
	v_add_f32_e32 v82, v82, v83
	v_mul_f32_e32 v83, v85, v85
	v_mul_f32_e32 v92, v87, v87
	v_fmac_f32_e32 v83, v84, v84
	v_fmac_f32_e32 v92, v86, v86
	v_add_f32_e32 v83, v83, v92
	v_mul_f32_e32 v92, v107, v107
	v_mul_f32_e32 v93, v109, v109
	v_fmac_f32_e32 v92, v106, v106
	v_fmac_f32_e32 v93, v108, v108
	v_add_f32_e32 v92, v92, v93
	v_add_f32_e32 v83, v83, v92
	v_add_f32_e32 v92, v82, v83
	ds_bpermute_b32 v93, v174, v92
	v_cvt_pk_bf16_f32 v81, v94, v95
	v_cvt_pk_bf16_f32 v82, v88, v89
	v_cvt_pk_bf16_f32 v83, v90, v91
	global_store_dwordx4 v[110:111], v[80:83], off sc1
	s_waitcnt lgkmcnt(0)
	s_nop 0
	v_add_f32_e32 v80, v92, v93
	ds_bpermute_b32 v81, v169, v80
	v_cvt_pk_bf16_f32 v82, v84, v85
	v_cvt_pk_bf16_f32 v83, v86, v87
	v_cvt_pk_bf16_f32 v84, v106, v107
	v_cvt_pk_bf16_f32 v85, v108, v109
	global_store_dwordx4 v[110:111], v[82:85], off offset:64 sc1
	s_and_saveexec_b64 s[0:1], vcc
	s_cbranch_execz .LBB0_650
	s_add_u32 s10, s6, s9
	s_addc_u32 s11, s7, s8
	s_waitcnt lgkmcnt(0)
	v_add_f32_e32 v82, v80, v81
	v_lshl_add_u64 v[80:81], v[160:161], 2, s[10:11]
	global_store_dword v[80:81], v82, off offset:128
.LBB0_650:
	s_or_b64 exec, exec, s[0:1]
	v_or_b32_e32 v80, 48, v168
	s_waitcnt lgkmcnt(0)
	v_mov_b32_e32 v81, v165
	v_lshlrev_b64 v[80:81], 11, v[80:81]
	v_lshl_add_u64 v[80:81], s[4:5], 0, v[80:81]
	v_lshl_add_u64 v[88:89], v[80:81], 0, v[164:165]
	global_load_dwordx4 v[84:87], v[88:89], off
	global_load_dwordx4 v[80:83], v[88:89], off offset:64
	v_lshlrev_b32_e32 v92, 16, v141
	v_and_b32_e32 v93, 0xffff0000, v141
	v_lshlrev_b32_e32 v90, 16, v140
	v_and_b32_e32 v91, 0xffff0000, v140
	v_pk_add_f32 v[78:79], v[78:79], v[92:93]
	v_lshlrev_b32_e32 v92, 16, v143
	v_and_b32_e32 v93, 0xffff0000, v143
	v_pk_add_f32 v[76:77], v[76:77], v[90:91]
	v_lshlrev_b32_e32 v90, 16, v142
	v_and_b32_e32 v91, 0xffff0000, v142
	v_pk_add_f32 v[74:75], v[74:75], v[92:93]
	v_lshlrev_b32_e32 v92, 16, v137
	v_and_b32_e32 v93, 0xffff0000, v137
	v_pk_add_f32 v[72:73], v[72:73], v[90:91]
	v_lshlrev_b32_e32 v90, 16, v136
	v_and_b32_e32 v91, 0xffff0000, v136
	v_pk_add_f32 v[70:71], v[70:71], v[92:93]
	v_lshlrev_b32_e32 v92, 16, v139
	v_and_b32_e32 v93, 0xffff0000, v139
	v_pk_add_f32 v[68:69], v[68:69], v[90:91]
	v_lshlrev_b32_e32 v90, 16, v138
	v_and_b32_e32 v91, 0xffff0000, v138
	v_pk_add_f32 v[92:93], v[66:67], v[92:93]
	v_mul_f32_e32 v66, v77, v77
	v_mul_f32_e32 v67, v79, v79
	v_pk_add_f32 v[90:91], v[64:65], v[90:91]
	v_lshl_add_u64 v[64:65], s[4:5], 0, v[166:167]
	v_fmac_f32_e32 v66, v76, v76
	v_fmac_f32_e32 v67, v78, v78
	v_lshl_add_u64 v[94:95], v[64:65], 0, v[164:165]
	v_cvt_pk_bf16_f32 v64, v76, v77
	v_add_f32_e32 v66, v66, v67
	v_mul_f32_e32 v67, v73, v73
	v_mul_f32_e32 v76, v75, v75
	v_fmac_f32_e32 v67, v72, v72
	v_fmac_f32_e32 v76, v74, v74
	v_add_f32_e32 v67, v67, v76
	v_add_f32_e32 v66, v66, v67
	v_mul_f32_e32 v67, v69, v69
	v_mul_f32_e32 v76, v71, v71
	v_fmac_f32_e32 v67, v68, v68
	v_fmac_f32_e32 v76, v70, v70
	v_add_f32_e32 v67, v67, v76
	v_mul_f32_e32 v76, v91, v91
	v_mul_f32_e32 v77, v93, v93
	v_fmac_f32_e32 v76, v90, v90
	v_fmac_f32_e32 v77, v92, v92
	v_add_f32_e32 v76, v76, v77
	v_add_f32_e32 v67, v67, v76
	v_add_f32_e32 v76, v66, v67
	ds_bpermute_b32 v77, v174, v76
	v_cvt_pk_bf16_f32 v65, v78, v79
	v_cvt_pk_bf16_f32 v66, v72, v73
	v_cvt_pk_bf16_f32 v67, v74, v75
	global_store_dwordx4 v[94:95], v[64:67], off sc1
	s_waitcnt lgkmcnt(0)
	s_nop 0
	v_add_f32_e32 v64, v76, v77
	ds_bpermute_b32 v65, v169, v64
	v_cvt_pk_bf16_f32 v66, v68, v69
	v_cvt_pk_bf16_f32 v67, v70, v71
	v_cvt_pk_bf16_f32 v68, v90, v91
	v_cvt_pk_bf16_f32 v69, v92, v93
	global_store_dwordx4 v[94:95], v[66:69], off offset:64 sc1
	s_and_saveexec_b64 s[0:1], vcc
	s_cbranch_execz .LBB0_652
	s_add_u32 s4, s6, s9
	s_addc_u32 s5, s7, s8
	s_waitcnt lgkmcnt(0)
	v_add_f32_e32 v66, v64, v65
	v_lshl_add_u64 v[64:65], v[160:161], 2, s[4:5]
	global_store_dword v[64:65], v66, off offset:192
.LBB0_652:
	s_or_b64 exec, exec, s[0:1]
	v_lshlrev_b32_e32 v66, 16, v133
	v_and_b32_e32 v67, 0xffff0000, v133
	v_pk_add_f32 v[62:63], v[62:63], v[66:67]
	v_lshlrev_b32_e32 v66, 16, v135
	v_and_b32_e32 v67, 0xffff0000, v135
	v_lshlrev_b32_e32 v64, 16, v132
	s_waitcnt lgkmcnt(0)
	v_and_b32_e32 v65, 0xffff0000, v132
	v_pk_add_f32 v[58:59], v[58:59], v[66:67]
	v_lshlrev_b32_e32 v66, 16, v129
	v_and_b32_e32 v67, 0xffff0000, v129
	v_pk_add_f32 v[60:61], v[60:61], v[64:65]
	v_lshlrev_b32_e32 v64, 16, v134
	v_and_b32_e32 v65, 0xffff0000, v134
	v_pk_add_f32 v[54:55], v[54:55], v[66:67]
	v_lshlrev_b32_e32 v66, 16, v131
	v_and_b32_e32 v67, 0xffff0000, v131
	v_pk_add_f32 v[56:57], v[56:57], v[64:65]
	v_lshlrev_b32_e32 v64, 16, v128
	v_and_b32_e32 v65, 0xffff0000, v128
	v_pk_add_f32 v[66:67], v[50:51], v[66:67]
	v_mul_f32_e32 v50, v61, v61
	v_mul_f32_e32 v51, v63, v63
	v_pk_add_f32 v[52:53], v[52:53], v[64:65]
	v_lshlrev_b32_e32 v64, 16, v130
	v_and_b32_e32 v65, 0xffff0000, v130
	v_fmac_f32_e32 v50, v60, v60
	v_fmac_f32_e32 v51, v62, v62
	v_pk_add_f32 v[64:65], v[48:49], v[64:65]
	v_cvt_pk_bf16_f32 v48, v60, v61
	v_add_f32_e32 v50, v50, v51
	v_mul_f32_e32 v51, v57, v57
	v_mul_f32_e32 v60, v59, v59
	v_fmac_f32_e32 v51, v56, v56
	v_fmac_f32_e32 v60, v58, v58
	v_add_f32_e32 v51, v51, v60
	v_add_f32_e32 v50, v50, v51
	v_mul_f32_e32 v51, v53, v53
	v_mul_f32_e32 v60, v55, v55
	v_fmac_f32_e32 v51, v52, v52
	v_fmac_f32_e32 v60, v54, v54
	v_add_f32_e32 v51, v51, v60
	v_mul_f32_e32 v60, v65, v65
	v_mul_f32_e32 v61, v67, v67
	v_fmac_f32_e32 v60, v64, v64
	v_fmac_f32_e32 v61, v66, v66
	v_add_f32_e32 v60, v60, v61
	v_add_f32_e32 v51, v51, v60
	v_add_f32_e32 v60, v50, v51
	ds_bpermute_b32 v61, v174, v60
	v_cvt_pk_bf16_f32 v49, v62, v63
	v_cvt_pk_bf16_f32 v50, v56, v57
	v_cvt_pk_bf16_f32 v51, v58, v59
	global_store_dwordx4 v[162:163], v[48:51], off sc1
	s_waitcnt lgkmcnt(0)
	s_nop 0
	v_add_f32_e32 v48, v60, v61
	ds_bpermute_b32 v49, v169, v48
	v_cvt_pk_bf16_f32 v50, v52, v53
	v_cvt_pk_bf16_f32 v51, v54, v55
	v_cvt_pk_bf16_f32 v52, v64, v65
	v_cvt_pk_bf16_f32 v53, v66, v67
	global_store_dwordx4 v[162:163], v[50:53], off offset:64 sc1
	s_and_saveexec_b64 s[0:1], vcc
	s_cbranch_execz .LBB0_654
	s_add_u32 s4, s6, s9
	s_addc_u32 s5, s7, s8
	s_waitcnt lgkmcnt(0)
	v_add_f32_e32 v50, v48, v49
	v_lshl_add_u64 v[48:49], v[160:161], 2, s[4:5]
	global_store_dword v[48:49], v50, off offset:512
.LBB0_654:
	s_or_b64 exec, exec, s[0:1]
	s_waitcnt vmcnt(13)
	v_lshlrev_b32_e32 v50, 16, v117
	v_and_b32_e32 v51, 0xffff0000, v117
	v_pk_add_f32 v[46:47], v[46:47], v[50:51]
	v_lshlrev_b32_e32 v50, 16, v119
	v_and_b32_e32 v51, 0xffff0000, v119
	v_lshlrev_b32_e32 v48, 16, v116
	s_waitcnt lgkmcnt(0)
	v_and_b32_e32 v49, 0xffff0000, v116
	v_pk_add_f32 v[42:43], v[42:43], v[50:51]
	s_waitcnt vmcnt(12)
	v_lshlrev_b32_e32 v50, 16, v113
	v_and_b32_e32 v51, 0xffff0000, v113
	v_pk_add_f32 v[44:45], v[44:45], v[48:49]
	v_lshlrev_b32_e32 v48, 16, v118
	v_and_b32_e32 v49, 0xffff0000, v118
	v_pk_add_f32 v[38:39], v[38:39], v[50:51]
	v_lshlrev_b32_e32 v50, 16, v115
	v_and_b32_e32 v51, 0xffff0000, v115
	v_pk_add_f32 v[40:41], v[40:41], v[48:49]
	v_lshlrev_b32_e32 v48, 16, v112
	v_and_b32_e32 v49, 0xffff0000, v112
	v_pk_add_f32 v[50:51], v[34:35], v[50:51]
	v_mul_f32_e32 v34, v45, v45
	v_mul_f32_e32 v35, v47, v47
	v_pk_add_f32 v[36:37], v[36:37], v[48:49]
	v_lshlrev_b32_e32 v48, 16, v114
	v_and_b32_e32 v49, 0xffff0000, v114
	v_fmac_f32_e32 v34, v44, v44
	v_fmac_f32_e32 v35, v46, v46
	v_pk_add_f32 v[48:49], v[32:33], v[48:49]
	v_cvt_pk_bf16_f32 v32, v44, v45
	v_add_f32_e32 v34, v34, v35
	v_mul_f32_e32 v35, v41, v41
	v_mul_f32_e32 v44, v43, v43
	v_fmac_f32_e32 v35, v40, v40
	v_fmac_f32_e32 v44, v42, v42
	v_add_f32_e32 v35, v35, v44
	v_add_f32_e32 v34, v34, v35
	v_mul_f32_e32 v35, v37, v37
	v_mul_f32_e32 v44, v39, v39
	v_fmac_f32_e32 v35, v36, v36
	v_fmac_f32_e32 v44, v38, v38
	v_add_f32_e32 v35, v35, v44
	v_mul_f32_e32 v44, v49, v49
	v_mul_f32_e32 v45, v51, v51
	v_fmac_f32_e32 v44, v48, v48
	v_fmac_f32_e32 v45, v50, v50
	v_add_f32_e32 v44, v44, v45
	v_add_f32_e32 v35, v35, v44
	v_add_f32_e32 v44, v34, v35
	ds_bpermute_b32 v45, v174, v44
	v_cvt_pk_bf16_f32 v33, v46, v47
	v_cvt_pk_bf16_f32 v34, v40, v41
	v_cvt_pk_bf16_f32 v35, v42, v43
	global_store_dwordx4 v[120:121], v[32:35], off sc1
	s_waitcnt lgkmcnt(0)
	s_nop 0
	v_add_f32_e32 v32, v44, v45
	ds_bpermute_b32 v33, v169, v32
	v_cvt_pk_bf16_f32 v34, v36, v37
	v_cvt_pk_bf16_f32 v35, v38, v39
	v_cvt_pk_bf16_f32 v36, v48, v49
	v_cvt_pk_bf16_f32 v37, v50, v51
	global_store_dwordx4 v[120:121], v[34:37], off offset:64 sc1
	s_and_saveexec_b64 s[0:1], vcc
	s_cbranch_execz .LBB0_656
	s_add_u32 s4, s6, s9
	s_waitcnt lgkmcnt(0)
	v_add_f32_e32 v34, v32, v33
	s_addc_u32 s5, s7, s8
	v_add_u32_e32 v32, 16, v160
	v_mov_b32_e32 v33, 0
	v_lshl_add_u64 v[32:33], v[32:33], 2, s[4:5]
	global_store_dword v[32:33], v34, off offset:512
.LBB0_656:
	s_or_b64 exec, exec, s[0:1]
	s_waitcnt vmcnt(11)
	v_lshlrev_b32_e32 v34, 16, v101
	v_and_b32_e32 v35, 0xffff0000, v101
	v_pk_add_f32 v[30:31], v[30:31], v[34:35]
	v_lshlrev_b32_e32 v34, 16, v103
	v_and_b32_e32 v35, 0xffff0000, v103
	v_lshlrev_b32_e32 v32, 16, v100
	s_waitcnt lgkmcnt(0)
	v_and_b32_e32 v33, 0xffff0000, v100
	v_pk_add_f32 v[26:27], v[26:27], v[34:35]
	s_waitcnt vmcnt(10)
	v_lshlrev_b32_e32 v34, 16, v97
	v_and_b32_e32 v35, 0xffff0000, v97
	v_pk_add_f32 v[28:29], v[28:29], v[32:33]
	v_lshlrev_b32_e32 v32, 16, v102
	v_and_b32_e32 v33, 0xffff0000, v102
	v_pk_add_f32 v[22:23], v[22:23], v[34:35]
	v_lshlrev_b32_e32 v34, 16, v99
	v_and_b32_e32 v35, 0xffff0000, v99
	v_pk_add_f32 v[24:25], v[24:25], v[32:33]
	v_lshlrev_b32_e32 v32, 16, v96
	v_and_b32_e32 v33, 0xffff0000, v96
	v_pk_add_f32 v[34:35], v[18:19], v[34:35]
	v_mul_f32_e32 v18, v29, v29
	v_mul_f32_e32 v19, v31, v31
	v_pk_add_f32 v[20:21], v[20:21], v[32:33]
	v_lshlrev_b32_e32 v32, 16, v98
	v_and_b32_e32 v33, 0xffff0000, v98
	v_fmac_f32_e32 v18, v28, v28
	v_fmac_f32_e32 v19, v30, v30
	v_pk_add_f32 v[32:33], v[16:17], v[32:33]
	v_cvt_pk_bf16_f32 v16, v28, v29
	v_add_f32_e32 v18, v18, v19
	v_mul_f32_e32 v19, v25, v25
	v_mul_f32_e32 v28, v27, v27
	v_fmac_f32_e32 v19, v24, v24
	v_fmac_f32_e32 v28, v26, v26
	v_add_f32_e32 v19, v19, v28
	v_add_f32_e32 v18, v18, v19
	v_mul_f32_e32 v19, v21, v21
	v_mul_f32_e32 v28, v23, v23
	v_fmac_f32_e32 v19, v20, v20
	v_fmac_f32_e32 v28, v22, v22
	v_add_f32_e32 v19, v19, v28
	v_mul_f32_e32 v28, v33, v33
	v_mul_f32_e32 v29, v35, v35
	v_fmac_f32_e32 v28, v32, v32
	v_fmac_f32_e32 v29, v34, v34
	v_add_f32_e32 v28, v28, v29
	v_add_f32_e32 v19, v19, v28
	v_add_f32_e32 v28, v18, v19
	ds_bpermute_b32 v29, v174, v28
	v_cvt_pk_bf16_f32 v17, v30, v31
	v_cvt_pk_bf16_f32 v18, v24, v25
	v_cvt_pk_bf16_f32 v19, v26, v27
	global_store_dwordx4 v[104:105], v[16:19], off sc1
	s_waitcnt lgkmcnt(0)
	s_nop 0
	v_add_f32_e32 v16, v28, v29
	ds_bpermute_b32 v17, v169, v16
	v_cvt_pk_bf16_f32 v18, v20, v21
	v_cvt_pk_bf16_f32 v19, v22, v23
	v_cvt_pk_bf16_f32 v20, v32, v33
	v_cvt_pk_bf16_f32 v21, v34, v35
	global_store_dwordx4 v[104:105], v[18:21], off offset:64 sc1
	s_and_saveexec_b64 s[0:1], vcc
	s_cbranch_execz .LBB0_658
	s_add_u32 s4, s6, s9
	s_waitcnt lgkmcnt(0)
	v_add_f32_e32 v18, v16, v17
	s_addc_u32 s5, s7, s8
	v_add_u32_e32 v16, 32, v160
	v_mov_b32_e32 v17, 0
	v_lshl_add_u64 v[16:17], v[16:17], 2, s[4:5]
	global_store_dword v[16:17], v18, off offset:512
.LBB0_658:
	s_or_b64 exec, exec, s[0:1]
	s_waitcnt vmcnt(9)
	v_lshlrev_b32_e32 v18, 16, v85
	v_and_b32_e32 v19, 0xffff0000, v85
	v_pk_add_f32 v[14:15], v[14:15], v[18:19]
	v_lshlrev_b32_e32 v18, 16, v87
	v_and_b32_e32 v19, 0xffff0000, v87
	v_lshlrev_b32_e32 v16, 16, v84
	s_waitcnt lgkmcnt(0)
	v_and_b32_e32 v17, 0xffff0000, v84
	v_pk_add_f32 v[10:11], v[10:11], v[18:19]
	s_waitcnt vmcnt(8)
	v_lshlrev_b32_e32 v18, 16, v81
	v_and_b32_e32 v19, 0xffff0000, v81
	v_pk_add_f32 v[12:13], v[12:13], v[16:17]
	v_lshlrev_b32_e32 v16, 16, v86
	v_and_b32_e32 v17, 0xffff0000, v86
	v_pk_add_f32 v[6:7], v[6:7], v[18:19]
	v_lshlrev_b32_e32 v18, 16, v83
	v_and_b32_e32 v19, 0xffff0000, v83
	v_pk_add_f32 v[8:9], v[8:9], v[16:17]
	v_lshlrev_b32_e32 v16, 16, v80
	v_and_b32_e32 v17, 0xffff0000, v80
	v_pk_add_f32 v[18:19], v[2:3], v[18:19]
	v_mul_f32_e32 v2, v13, v13
	v_mul_f32_e32 v3, v15, v15
	v_pk_add_f32 v[4:5], v[4:5], v[16:17]
	v_lshlrev_b32_e32 v16, 16, v82
	v_and_b32_e32 v17, 0xffff0000, v82
	v_fmac_f32_e32 v2, v12, v12
	v_fmac_f32_e32 v3, v14, v14
	v_pk_add_f32 v[16:17], v[0:1], v[16:17]
	v_cvt_pk_bf16_f32 v0, v12, v13
	v_add_f32_e32 v2, v2, v3
	v_mul_f32_e32 v3, v9, v9
	v_mul_f32_e32 v12, v11, v11
	v_fmac_f32_e32 v3, v8, v8
	v_fmac_f32_e32 v12, v10, v10
	v_add_f32_e32 v3, v3, v12
	v_add_f32_e32 v2, v2, v3
	v_mul_f32_e32 v3, v5, v5
	v_mul_f32_e32 v12, v7, v7
	v_fmac_f32_e32 v3, v4, v4
	v_fmac_f32_e32 v12, v6, v6
	v_add_f32_e32 v3, v3, v12
	v_mul_f32_e32 v12, v17, v17
	v_mul_f32_e32 v13, v19, v19
	v_fmac_f32_e32 v12, v16, v16
	v_fmac_f32_e32 v13, v18, v18
	v_add_f32_e32 v12, v12, v13
	v_add_f32_e32 v3, v3, v12
	v_add_f32_e32 v12, v2, v3
	ds_bpermute_b32 v13, v174, v12
	v_cvt_pk_bf16_f32 v1, v14, v15
	v_cvt_pk_bf16_f32 v2, v8, v9
	v_cvt_pk_bf16_f32 v3, v10, v11
	global_store_dwordx4 v[88:89], v[0:3], off sc1
	s_waitcnt lgkmcnt(0)
	s_nop 0
	v_add_f32_e32 v0, v12, v13
	ds_bpermute_b32 v1, v169, v0
	v_cvt_pk_bf16_f32 v2, v4, v5
	v_cvt_pk_bf16_f32 v3, v6, v7
	v_cvt_pk_bf16_f32 v4, v16, v17
	v_cvt_pk_bf16_f32 v5, v18, v19
	global_store_dwordx4 v[88:89], v[2:5], off offset:64 sc1
	s_and_saveexec_b64 s[0:1], vcc
	s_cbranch_execz .LBB0_660
	s_add_u32 s4, s6, s9
	s_waitcnt lgkmcnt(0)
	v_add_f32_e32 v2, v0, v1
	s_addc_u32 s5, s7, s8
	v_add_u32_e32 v0, 48, v160
	v_mov_b32_e32 v1, 0
	v_lshl_add_u64 v[0:1], v[0:1], 2, s[4:5]
	global_store_dword v[0:1], v2, off offset:512

.LBB0_774:
	s_add_u32 s12, s8, s10
	ds_read_b128 v[148:151], v143
	ds_read_b128 v[152:155], v143 offset:1024
	ds_read_b128 v[156:159], v143 offset:2048
	ds_read_b128 v[160:163], v143 offset:3072
	s_addc_u32 s13, s9, s11
	s_add_u32 s12, s12, 0x5c00100
	s_addc_u32 s13, s13, 0
	s_add_u32 s43, s38, s10
	s_addc_u32 s44, s39, s11
	s_cmpk_eq_i32 s10, 0x700
	s_cselect_b32 s15, s1, s13
	s_cselect_b32 s14, s0, s12
	s_cselect_b32 s13, s5, s44
	s_cselect_b32 s12, s4, s43
	s_mov_b32 m0, s41
	v_lshl_add_u64 v[196:197], v[134:135], 0, s[10:11]
	ds_read_b128 v[164:167], v144
	ds_read_b128 v[168:171], v144 offset:1024
	ds_read_b128 v[172:175], v144 offset:2048
	ds_read_b128 v[176:179], v144 offset:3072
	ds_read_b128 v[180:183], v144 offset:4096
	ds_read_b128 v[184:187], v144 offset:5120
	ds_read_b128 v[188:191], v144 offset:6144
	ds_read_b128 v[192:195], v144 offset:7168
	global_load_lds_dwordx4 v[196:197], off
	v_lshl_add_u64 v[196:197], v[136:137], 0, s[10:11]
	s_mov_b32 m0, s42
	s_nop 0
	global_load_lds_dwordx4 v[196:197], off
	ds_read_b128 v[196:199], v145
	ds_read_b128 v[204:207], v145 offset:1024
	ds_read_b128 v[208:211], v145 offset:2048
	ds_read_b128 v[212:215], v145 offset:3072
	s_waitcnt lgkmcnt(0)
	s_waitcnt vmcnt(8)
	s_barrier
	s_setprio 1
	v_mfma_f32_16x16x32_bf16 v[124:127], v[148:151], v[164:167], v[124:127]
	v_mfma_f32_16x16x32_bf16 v[120:123], v[156:159], v[164:167], v[120:123]
	v_mfma_f32_16x16x32_bf16 v[108:111], v[148:151], v[172:175], v[108:111]
	v_mfma_f32_16x16x32_bf16 v[104:107], v[156:159], v[172:175], v[104:107]
	v_mfma_f32_16x16x32_bf16 v[92:95], v[148:151], v[180:183], v[92:95]
	v_mfma_f32_16x16x32_bf16 v[88:91], v[156:159], v[180:183], v[88:91]
	v_mfma_f32_16x16x32_bf16 v[76:79], v[148:151], v[188:191], v[76:79]
	v_mfma_f32_16x16x32_bf16 v[72:75], v[156:159], v[188:191], v[72:75]
	v_mfma_f32_16x16x32_bf16 v[124:127], v[152:155], v[168:171], v[124:127]
	v_mfma_f32_16x16x32_bf16 v[120:123], v[160:163], v[168:171], v[120:123]
	v_mfma_f32_16x16x32_bf16 v[108:111], v[152:155], v[176:179], v[108:111]
	v_mfma_f32_16x16x32_bf16 v[104:107], v[160:163], v[176:179], v[104:107]
	v_mfma_f32_16x16x32_bf16 v[92:95], v[152:155], v[184:187], v[92:95]
	v_mfma_f32_16x16x32_bf16 v[88:91], v[160:163], v[184:187], v[88:91]
	v_mfma_f32_16x16x32_bf16 v[76:79], v[152:155], v[192:195], v[76:79]
	v_mfma_f32_16x16x32_bf16 v[72:75], v[160:163], v[192:195], v[72:75]
	v_mfma_f32_16x16x32_bf16 v[116:119], v[196:199], v[164:167], v[116:119]
	v_mfma_f32_16x16x32_bf16 v[112:115], v[208:211], v[164:167], v[112:115]
	v_mfma_f32_16x16x32_bf16 v[100:103], v[196:199], v[172:175], v[100:103]
	v_mfma_f32_16x16x32_bf16 v[96:99], v[208:211], v[172:175], v[96:99]
	v_mfma_f32_16x16x32_bf16 v[84:87], v[196:199], v[180:183], v[84:87]
	v_mfma_f32_16x16x32_bf16 v[80:83], v[208:211], v[180:183], v[80:83]
	v_mfma_f32_16x16x32_bf16 v[68:71], v[196:199], v[188:191], v[68:71]
	v_mfma_f32_16x16x32_bf16 v[64:67], v[208:211], v[188:191], v[64:67]
	v_mfma_f32_16x16x32_bf16 v[116:119], v[204:207], v[168:171], v[116:119]
	v_mfma_f32_16x16x32_bf16 v[112:115], v[212:215], v[168:171], v[112:115]
	v_mfma_f32_16x16x32_bf16 v[100:103], v[204:207], v[176:179], v[100:103]
	v_mfma_f32_16x16x32_bf16 v[96:99], v[212:215], v[176:179], v[96:99]
	v_mfma_f32_16x16x32_bf16 v[84:87], v[204:207], v[184:187], v[84:87]
	v_mfma_f32_16x16x32_bf16 v[80:83], v[212:215], v[184:187], v[80:83]
	v_mfma_f32_16x16x32_bf16 v[68:71], v[204:207], v[192:195], v[68:71]
	v_mfma_f32_16x16x32_bf16 v[64:67], v[212:215], v[192:195], v[64:67]
	s_setprio 0
	s_barrier
	ds_read_b128 v[164:167], v144 offset:16384
	ds_read_b128 v[168:171], v144 offset:17408
	ds_read_b128 v[172:175], v144 offset:18432
	ds_read_b128 v[176:179], v144 offset:19456
	ds_read_b128 v[180:183], v144 offset:20480
	ds_read_b128 v[184:187], v144 offset:21504
	ds_read_b128 v[188:191], v144 offset:22528
	ds_read_b128 v[192:195], v144 offset:23552
	s_mov_b32 m0, s19
	v_lshl_add_u64 v[200:201], s[12:13], 0, v[132:133]
	global_load_lds_dwordx4 v[200:201], off
	v_lshl_add_u64 v[216:217], s[12:13], 0, v[130:131]
	s_mov_b32 m0, s24
	s_nop 0
	global_load_lds_dwordx4 v[216:217], off
	s_mov_b32 m0, s25
	v_lshl_add_u64 v[218:219], s[14:15], 0, v[132:133]
	global_load_lds_dwordx4 v[218:219], off
	v_lshl_add_u64 v[220:221], s[14:15], 0, v[130:131]
	s_mov_b32 m0, s26
	s_nop 0
	global_load_lds_dwordx4 v[220:221], off
	s_add_u32 s44, s12, 0x40000
	s_addc_u32 s45, s13, 0
	s_mov_b32 m0, s27
	v_lshl_add_u64 v[248:249], s[44:45], 0, v[132:133]
	global_load_lds_dwordx4 v[248:249], off
	v_lshl_add_u64 v[248:249], s[44:45], 0, v[130:131]
	s_mov_b32 m0, s28
	s_nop 0
	global_load_lds_dwordx4 v[248:249], off
	s_waitcnt lgkmcnt(0)
	s_waitcnt vmcnt(8)
	s_barrier
	s_setprio 1
	v_mfma_f32_16x16x32_bf16 v[60:63], v[148:151], v[164:167], v[60:63]
	v_mfma_f32_16x16x32_bf16 v[56:59], v[156:159], v[164:167], v[56:59]
	v_mfma_f32_16x16x32_bf16 v[44:47], v[148:151], v[172:175], v[44:47]
	v_mfma_f32_16x16x32_bf16 v[40:43], v[156:159], v[172:175], v[40:43]
	v_mfma_f32_16x16x32_bf16 v[28:31], v[148:151], v[180:183], v[28:31]
	v_mfma_f32_16x16x32_bf16 v[24:27], v[156:159], v[180:183], v[24:27]
	v_mfma_f32_16x16x32_bf16 v[12:15], v[148:151], v[188:191], v[12:15]
	v_mfma_f32_16x16x32_bf16 v[8:11], v[156:159], v[188:191], v[8:11]
	v_mfma_f32_16x16x32_bf16 v[60:63], v[152:155], v[168:171], v[60:63]
	v_mfma_f32_16x16x32_bf16 v[56:59], v[160:163], v[168:171], v[56:59]
	v_mfma_f32_16x16x32_bf16 v[44:47], v[152:155], v[176:179], v[44:47]
	v_mfma_f32_16x16x32_bf16 v[40:43], v[160:163], v[176:179], v[40:43]
	v_mfma_f32_16x16x32_bf16 v[28:31], v[152:155], v[184:187], v[28:31]
	v_mfma_f32_16x16x32_bf16 v[24:27], v[160:163], v[184:187], v[24:27]
	v_mfma_f32_16x16x32_bf16 v[12:15], v[152:155], v[192:195], v[12:15]
	v_mfma_f32_16x16x32_bf16 v[8:11], v[160:163], v[192:195], v[8:11]
	v_mfma_f32_16x16x32_bf16 v[52:55], v[196:199], v[164:167], v[52:55]
	v_mfma_f32_16x16x32_bf16 v[48:51], v[208:211], v[164:167], v[48:51]
	v_mfma_f32_16x16x32_bf16 v[36:39], v[196:199], v[172:175], v[36:39]
	v_mfma_f32_16x16x32_bf16 v[32:35], v[208:211], v[172:175], v[32:35]
	v_mfma_f32_16x16x32_bf16 v[20:23], v[196:199], v[180:183], v[20:23]
	v_mfma_f32_16x16x32_bf16 v[16:19], v[208:211], v[180:183], v[16:19]
	v_mfma_f32_16x16x32_bf16 v[4:7], v[196:199], v[188:191], v[4:7]
	v_mfma_f32_16x16x32_bf16 v[0:3], v[208:211], v[188:191], v[0:3]
	v_mfma_f32_16x16x32_bf16 v[52:55], v[204:207], v[168:171], v[52:55]
	v_mfma_f32_16x16x32_bf16 v[48:51], v[212:215], v[168:171], v[48:51]
	v_mfma_f32_16x16x32_bf16 v[36:39], v[204:207], v[176:179], v[36:39]
	v_mfma_f32_16x16x32_bf16 v[32:35], v[212:215], v[176:179], v[32:35]
	v_mfma_f32_16x16x32_bf16 v[20:23], v[204:207], v[184:187], v[20:23]
	v_mfma_f32_16x16x32_bf16 v[16:19], v[212:215], v[184:187], v[16:19]
	v_mfma_f32_16x16x32_bf16 v[4:7], v[204:207], v[192:195], v[4:7]
	v_mfma_f32_16x16x32_bf16 v[0:3], v[212:215], v[192:195], v[0:3]
	s_setprio 0
	s_barrier
	ds_read_b128 v[148:151], v146
	ds_read_b128 v[152:155], v146 offset:1024
	ds_read_b128 v[156:159], v146 offset:2048
	ds_read_b128 v[160:163], v146 offset:3072
	s_add_u32 s14, s14, 0x40000
	s_addc_u32 s15, s15, 0
	s_mov_b32 m0, s29
	v_lshl_add_u64 v[196:197], s[14:15], 0, v[132:133]
	ds_read_b128 v[164:167], v144 offset:32768
	ds_read_b128 v[168:171], v144 offset:33792
	ds_read_b128 v[172:175], v144 offset:34816
	ds_read_b128 v[176:179], v144 offset:35840
	ds_read_b128 v[180:183], v144 offset:36864
	ds_read_b128 v[184:187], v144 offset:37888
	ds_read_b128 v[188:191], v144 offset:38912
	ds_read_b128 v[192:195], v144 offset:39936
	global_load_lds_dwordx4 v[196:197], off
	v_lshl_add_u64 v[196:197], s[14:15], 0, v[130:131]
	s_mov_b32 m0, s30
	s_nop 0
	global_load_lds_dwordx4 v[196:197], off
	ds_read_b128 v[196:199], v147
	ds_read_b128 v[204:207], v147 offset:1024
	ds_read_b128 v[208:211], v147 offset:2048
	ds_read_b128 v[212:215], v147 offset:3072
	s_waitcnt lgkmcnt(0)
	s_waitcnt vmcnt(8)
	s_barrier
	s_setprio 1
	v_mfma_f32_16x16x32_bf16 v[124:127], v[148:151], v[164:167], v[124:127]
	v_mfma_f32_16x16x32_bf16 v[120:123], v[156:159], v[164:167], v[120:123]
	v_mfma_f32_16x16x32_bf16 v[108:111], v[148:151], v[172:175], v[108:111]
	v_mfma_f32_16x16x32_bf16 v[104:107], v[156:159], v[172:175], v[104:107]
	v_mfma_f32_16x16x32_bf16 v[92:95], v[148:151], v[180:183], v[92:95]
	v_mfma_f32_16x16x32_bf16 v[88:91], v[156:159], v[180:183], v[88:91]
	v_mfma_f32_16x16x32_bf16 v[76:79], v[148:151], v[188:191], v[76:79]
	v_mfma_f32_16x16x32_bf16 v[72:75], v[156:159], v[188:191], v[72:75]
	v_mfma_f32_16x16x32_bf16 v[124:127], v[152:155], v[168:171], v[124:127]
	v_mfma_f32_16x16x32_bf16 v[120:123], v[160:163], v[168:171], v[120:123]
	v_mfma_f32_16x16x32_bf16 v[108:111], v[152:155], v[176:179], v[108:111]
	v_mfma_f32_16x16x32_bf16 v[104:107], v[160:163], v[176:179], v[104:107]
	v_mfma_f32_16x16x32_bf16 v[92:95], v[152:155], v[184:187], v[92:95]
	v_mfma_f32_16x16x32_bf16 v[88:91], v[160:163], v[184:187], v[88:91]
	v_mfma_f32_16x16x32_bf16 v[76:79], v[152:155], v[192:195], v[76:79]
	v_mfma_f32_16x16x32_bf16 v[72:75], v[160:163], v[192:195], v[72:75]
	v_mfma_f32_16x16x32_bf16 v[116:119], v[196:199], v[164:167], v[116:119]
	v_mfma_f32_16x16x32_bf16 v[112:115], v[208:211], v[164:167], v[112:115]
	v_mfma_f32_16x16x32_bf16 v[100:103], v[196:199], v[172:175], v[100:103]
	v_mfma_f32_16x16x32_bf16 v[96:99], v[208:211], v[172:175], v[96:99]
	v_mfma_f32_16x16x32_bf16 v[84:87], v[196:199], v[180:183], v[84:87]
	v_mfma_f32_16x16x32_bf16 v[80:83], v[208:211], v[180:183], v[80:83]
	v_mfma_f32_16x16x32_bf16 v[68:71], v[196:199], v[188:191], v[68:71]
	v_mfma_f32_16x16x32_bf16 v[64:67], v[208:211], v[188:191], v[64:67]
	v_mfma_f32_16x16x32_bf16 v[116:119], v[204:207], v[168:171], v[116:119]
	v_mfma_f32_16x16x32_bf16 v[112:115], v[212:215], v[168:171], v[112:115]
	v_mfma_f32_16x16x32_bf16 v[100:103], v[204:207], v[176:179], v[100:103]
	v_mfma_f32_16x16x32_bf16 v[96:99], v[212:215], v[176:179], v[96:99]
	v_mfma_f32_16x16x32_bf16 v[84:87], v[204:207], v[184:187], v[84:87]
	v_mfma_f32_16x16x32_bf16 v[80:83], v[212:215], v[184:187], v[80:83]
	v_mfma_f32_16x16x32_bf16 v[68:71], v[204:207], v[192:195], v[68:71]
	v_mfma_f32_16x16x32_bf16 v[64:67], v[212:215], v[192:195], v[64:67]
	s_setprio 0
	s_barrier
	ds_read_b128 v[164:167], v144 offset:49152
	ds_read_b128 v[168:171], v144 offset:50176
	ds_read_b128 v[172:175], v144 offset:51200
	ds_read_b128 v[176:179], v144 offset:52224
	ds_read_b128 v[180:183], v144 offset:53248
	ds_read_b128 v[184:187], v144 offset:54272
	ds_read_b128 v[188:191], v144 offset:55296
	ds_read_b128 v[192:195], v144 offset:56320
	s_mov_b32 m0, s31
	v_lshl_add_u64 v[200:201], v[200:201], 0, s[6:7]
	global_load_lds_dwordx4 v[200:201], off
	v_lshl_add_u64 v[200:201], v[216:217], 0, s[6:7]
	s_mov_b32 m0, s33
	s_nop 0
	global_load_lds_dwordx4 v[200:201], off
	s_mov_b32 m0, s34
	v_lshl_add_u64 v[200:201], v[218:219], 0, s[6:7]
	global_load_lds_dwordx4 v[200:201], off
	v_lshl_add_u64 v[200:201], v[220:221], 0, s[6:7]
	s_mov_b32 m0, s35
	s_nop 0
	global_load_lds_dwordx4 v[200:201], off
	s_add_u32 s12, s12, 0x40080
	s_addc_u32 s13, s13, 0
	s_mov_b32 m0, s36
	v_lshl_add_u64 v[248:249], s[12:13], 0, v[132:133]
	global_load_lds_dwordx4 v[248:249], off
	v_lshl_add_u64 v[248:249], s[12:13], 0, v[130:131]
	s_mov_b32 m0, s37
	s_nop 0
	global_load_lds_dwordx4 v[248:249], off
	s_waitcnt lgkmcnt(0)
	s_waitcnt vmcnt(8)
	s_barrier
	s_setprio 1
	v_mfma_f32_16x16x32_bf16 v[60:63], v[148:151], v[164:167], v[60:63]
	v_mfma_f32_16x16x32_bf16 v[56:59], v[156:159], v[164:167], v[56:59]
	v_mfma_f32_16x16x32_bf16 v[44:47], v[148:151], v[172:175], v[44:47]
	v_mfma_f32_16x16x32_bf16 v[40:43], v[156:159], v[172:175], v[40:43]
	v_mfma_f32_16x16x32_bf16 v[28:31], v[148:151], v[180:183], v[28:31]
	v_mfma_f32_16x16x32_bf16 v[24:27], v[156:159], v[180:183], v[24:27]
	v_mfma_f32_16x16x32_bf16 v[12:15], v[148:151], v[188:191], v[12:15]
	v_mfma_f32_16x16x32_bf16 v[8:11], v[156:159], v[188:191], v[8:11]
	v_mfma_f32_16x16x32_bf16 v[60:63], v[152:155], v[168:171], v[60:63]
	v_mfma_f32_16x16x32_bf16 v[56:59], v[160:163], v[168:171], v[56:59]
	v_mfma_f32_16x16x32_bf16 v[44:47], v[152:155], v[176:179], v[44:47]
	v_mfma_f32_16x16x32_bf16 v[40:43], v[160:163], v[176:179], v[40:43]
	v_mfma_f32_16x16x32_bf16 v[28:31], v[152:155], v[184:187], v[28:31]
	v_mfma_f32_16x16x32_bf16 v[24:27], v[160:163], v[184:187], v[24:27]
	v_mfma_f32_16x16x32_bf16 v[12:15], v[152:155], v[192:195], v[12:15]
	v_mfma_f32_16x16x32_bf16 v[8:11], v[160:163], v[192:195], v[8:11]
	v_mfma_f32_16x16x32_bf16 v[52:55], v[196:199], v[164:167], v[52:55]
	v_mfma_f32_16x16x32_bf16 v[48:51], v[208:211], v[164:167], v[48:51]
	v_mfma_f32_16x16x32_bf16 v[36:39], v[196:199], v[172:175], v[36:39]
	v_mfma_f32_16x16x32_bf16 v[32:35], v[208:211], v[172:175], v[32:35]
	v_mfma_f32_16x16x32_bf16 v[20:23], v[196:199], v[180:183], v[20:23]
	v_mfma_f32_16x16x32_bf16 v[16:19], v[208:211], v[180:183], v[16:19]
	v_mfma_f32_16x16x32_bf16 v[4:7], v[196:199], v[188:191], v[4:7]
	v_mfma_f32_16x16x32_bf16 v[0:3], v[208:211], v[188:191], v[0:3]
	v_mfma_f32_16x16x32_bf16 v[52:55], v[204:207], v[168:171], v[52:55]
	v_mfma_f32_16x16x32_bf16 v[48:51], v[212:215], v[168:171], v[48:51]
	v_mfma_f32_16x16x32_bf16 v[36:39], v[204:207], v[176:179], v[36:39]
	v_mfma_f32_16x16x32_bf16 v[32:35], v[212:215], v[176:179], v[32:35]
	v_mfma_f32_16x16x32_bf16 v[20:23], v[204:207], v[184:187], v[20:23]
	v_mfma_f32_16x16x32_bf16 v[16:19], v[212:215], v[184:187], v[16:19]
	v_mfma_f32_16x16x32_bf16 v[4:7], v[204:207], v[192:195], v[4:7]
	v_mfma_f32_16x16x32_bf16 v[0:3], v[212:215], v[192:195], v[0:3]
	s_setprio 0
	s_add_i32 s40, s40, 2
	s_add_u32 s10, s10, 0x100
	s_addc_u32 s11, s11, 0
	s_cmp_gt_u32 s40, 13
	s_barrier
	s_cbranch_scc0 .LBB0_774
	v_mul_u32_u24_e32 v130, 0x21000, v141
	v_mov_b32_e32 v133, 0
	v_lshlrev_b32_e32 v130, 2, v130
	v_mov_b32_e32 v131, v133
	v_lshl_add_u32 v132, s18, 8, v142
	v_lshl_add_u64 v[130:131], s[22:23], 0, v[130:131]
	v_lshl_add_u64 v[130:131], v[132:133], 2, v[130:131]
	s_mov_b64 s[0:1], 0x18ba4000
	v_lshl_add_u64 v[134:135], v[130:131], 0, s[0:1]
	s_mov_b32 s0, 0x18ba4000
	v_add_co_u32_e32 v136, vcc, s0, v130
	s_mov_b32 s0, 0x18bc5000
	s_nop 0
	v_addc_co_u32_e32 v137, vcc, 0, v131, vcc
	v_add_co_u32_e32 v142, vcc, s0, v130
	s_mov_b32 s0, 0x18be6000
	s_nop 0
	v_addc_co_u32_e32 v143, vcc, 0, v131, vcc
	v_add_co_u32_e32 v144, vcc, s0, v130
	s_mov_b32 s0, 0x18c07000
	s_nop 0
	v_addc_co_u32_e32 v145, vcc, 0, v131, vcc
	v_add_co_u32_e32 v130, vcc, s0, v130
	v_mov_b32_e32 v151, 0x358637bd
	s_nop 0
	v_addc_co_u32_e32 v131, vcc, 0, v131, vcc
	global_load_dword v146, v[142:143], off
	global_load_dword v150, v[142:143], off offset:64
	global_load_dword v149, v[144:145], off
	global_load_dword v152, v[144:145], off offset:64
	global_load_dword v147, v[130:131], off
	global_load_dword v153, v[130:131], off offset:64
	global_load_dword v148, v[136:137], off
	global_load_dword v154, v[134:135], off offset:64
	global_load_dword v155, v[134:135], off offset:128
	global_load_dword v156, v[142:143], off offset:128
	global_load_dword v157, v[144:145], off offset:128
	global_load_dword v158, v[130:131], off offset:128
	global_load_dword v159, v[134:135], off offset:192
	global_load_dword v160, v[142:143], off offset:192
	global_load_dword v161, v[144:145], off offset:192
	global_load_dword v162, v[130:131], off offset:192
	global_load_dword v163, v[134:135], off offset:512
	global_load_dword v164, v[142:143], off offset:512
	global_load_dword v165, v[144:145], off offset:512
	global_load_dword v166, v[130:131], off offset:512
	global_load_dword v167, v[134:135], off offset:576
	global_load_dword v168, v[142:143], off offset:576
	global_load_dword v169, v[144:145], off offset:576
	global_load_dword v170, v[130:131], off offset:576
	global_load_dword v171, v[134:135], off offset:640
	global_load_dword v172, v[142:143], off offset:640
	global_load_dword v173, v[144:145], off offset:640
	global_load_dword v174, v[130:131], off offset:640
	s_nop 0
	global_load_dword v135, v[134:135], off offset:704
	s_nop 0
	global_load_dword v142, v[142:143], off offset:704
	s_nop 0
	global_load_dword v143, v[144:145], off offset:704
	s_nop 0
	global_load_dword v144, v[130:131], off offset:704
	v_mbcnt_lo_u32_b32 v131, -1, 0
	v_mbcnt_hi_u32_b32 v131, -1, v131
	v_and_b32_e32 v136, 64, v131
	v_xor_b32_e32 v134, 16, v131
	v_add_u32_e32 v136, 64, v136
	v_xor_b32_e32 v137, 32, v131
	v_cmp_lt_i32_e64 s[0:1], v134, v136
	s_add_u32 s4, s22, 0x195cc000
	s_addc_u32 s5, s23, 0
	v_cndmask_b32_e64 v134, v131, v134, s[0:1]
	v_cmp_lt_i32_e64 s[0:1], v137, v136
	s_add_u32 s6, s22, 0x18fc4000
	s_addc_u32 s7, s23, 0
	v_cndmask_b32_e64 v136, v131, v137, s[0:1]
	v_lshlrev_b32_e32 v131, 2, v134
	v_lshlrev_b32_e32 v134, 2, v136
	s_lshl_b32 s8, s17, 6
	s_lshl_b32 s0, s2, 8
	v_lshlrev_b32_e32 v130, 3, v141
	s_or_b32 s0, s8, s0
	v_cmp_eq_u32_e32 vcc, 0, v141
	s_waitcnt vmcnt(0)
	v_pk_add_f32 v[136:137], v[148:149], v[146:147]
	s_nop 0
	v_add_f32_e32 v136, v136, v137
	ds_bpermute_b32 v137, v131, v136
	v_add_f32_e32 v145, v154, v150
	v_add_f32_e32 v147, v155, v156
	v_add_f32_e32 v148, v157, v158
	v_add_f32_e32 v147, v147, v148
	s_waitcnt lgkmcnt(0)
	v_add_f32_e32 v136, v136, v137
	ds_bpermute_b32 v137, v134, v136
	v_add_f32_e32 v149, v159, v160
	ds_bpermute_b32 v148, v131, v147
	v_or_b32_e32 v160, s0, v130
	v_add_f32_e32 v146, v152, v153
	s_waitcnt lgkmcnt(1)
	v_add_f32_e32 v136, v136, v137
	v_fmamk_f32 v136, v136, 0x3a800000, v151
	v_rsq_f32_e32 v154, v136
	v_add_f32_e32 v136, v161, v162
	v_add_f32_e32 v136, v149, v136
	ds_bpermute_b32 v137, v131, v136
	s_waitcnt lgkmcnt(1)
	v_add_f32_e32 v149, v147, v148
	v_add_f32_e32 v155, v171, v172
	v_add_f32_e32 v156, v173, v174
	v_add_f32_e32 v155, v155, v156
	s_waitcnt lgkmcnt(0)
	v_add_f32_e32 v147, v136, v137
	v_add_f32_e32 v136, v167, v168
	v_add_f32_e32 v137, v169, v170
	v_add_f32_e32 v135, v135, v142
	v_add_f32_e32 v142, v143, v144
	v_add_f32_e32 v136, v136, v137
	v_add_f32_e32 v135, v135, v142
	ds_bpermute_b32 v137, v131, v136
	ds_bpermute_b32 v156, v131, v155
	ds_bpermute_b32 v157, v131, v135
	v_pk_mul_f32 v[126:127], v[126:127], v[154:155] op_sel_hi:[1,0]
	v_pk_mul_f32 v[124:125], v[124:125], v[154:155] op_sel_hi:[1,0]
	s_waitcnt lgkmcnt(2)
	v_add_f32_e32 v143, v136, v137
	s_waitcnt lgkmcnt(1)
	v_add_f32_e32 v137, v155, v156
	s_waitcnt lgkmcnt(0)
	v_add_f32_e32 v135, v135, v157
	v_pk_mul_f32 v[122:123], v[122:123], v[154:155] op_sel_hi:[1,0]
	v_pk_mul_f32 v[120:121], v[120:121], v[154:155] op_sel_hi:[1,0]
	v_pk_mul_f32 v[118:119], v[118:119], v[154:155] op_sel_hi:[1,0]
	v_pk_mul_f32 v[156:157], v[116:117], v[154:155] op_sel_hi:[1,0]
	v_pk_mul_f32 v[158:159], v[114:115], v[154:155] op_sel_hi:[1,0]
	v_pk_mul_f32 v[154:155], v[112:113], v[154:155] op_sel_hi:[1,0]
	v_lshlrev_b64 v[112:113], 10, v[132:133]
	v_mul_f32_e32 v116, v125, v125
	v_mul_f32_e32 v117, v127, v127
	v_lshl_add_u64 v[114:115], s[4:5], 0, v[112:113]
	v_lshlrev_b32_e32 v112, 1, v160
	v_mov_b32_e32 v113, v133
	v_fmac_f32_e32 v116, v124, v124
	v_fmac_f32_e32 v117, v126, v126
	v_lshl_add_u64 v[160:161], v[114:115], 0, v[112:113]
	v_cvt_pk_bf16_f32 v114, v124, v125
	v_add_f32_e32 v116, v116, v117
	v_mul_f32_e32 v117, v121, v121
	v_mul_f32_e32 v124, v123, v123
	v_fmac_f32_e32 v117, v120, v120
	v_fmac_f32_e32 v124, v122, v122
	v_add_f32_e32 v145, v145, v146
	v_add_f32_e32 v117, v117, v124
	ds_bpermute_b32 v146, v131, v145
	v_add_f32_e32 v116, v116, v117
	v_mul_f32_e32 v117, v157, v157
	v_mul_f32_e32 v124, v119, v119
	v_fmac_f32_e32 v117, v156, v156
	v_fmac_f32_e32 v124, v118, v118
	v_add_f32_e32 v117, v117, v124
	v_mul_f32_e32 v124, v155, v155
	v_mul_f32_e32 v125, v159, v159
	v_fmac_f32_e32 v124, v154, v154
	v_fmac_f32_e32 v125, v158, v158
	v_add_f32_e32 v124, v124, v125
	s_waitcnt lgkmcnt(0)
	v_add_f32_e32 v152, v145, v146
	v_add_f32_e32 v145, v163, v164
	v_add_f32_e32 v146, v165, v166
	v_add_f32_e32 v117, v117, v124
	v_add_f32_e32 v145, v145, v146
	v_add_f32_e32 v124, v116, v117
	ds_bpermute_b32 v146, v131, v145
	ds_bpermute_b32 v125, v131, v124
	v_cvt_pk_bf16_f32 v115, v126, v127
	v_cvt_pk_bf16_f32 v116, v120, v121
	v_cvt_pk_bf16_f32 v117, v122, v123
	s_waitcnt lgkmcnt(1)
	v_add_f32_e32 v145, v145, v146
	global_store_dwordx4 v[160:161], v[114:117], off sc1
	ds_bpermute_b32 v153, v134, v152
	ds_bpermute_b32 v150, v134, v149
	s_waitcnt lgkmcnt(2)
	v_add_f32_e32 v114, v124, v125
	ds_bpermute_b32 v148, v134, v147
	ds_bpermute_b32 v146, v134, v145
	ds_bpermute_b32 v144, v134, v143
	ds_bpermute_b32 v142, v134, v137
	ds_bpermute_b32 v136, v134, v135
	ds_bpermute_b32 v115, v134, v114
	s_and_b32 s0, s16, -4
	s_or_b32 s8, s17, s0
	s_mul_hi_u32 s2, s8, 0x21000
	s_mul_i32 s8, s8, 0x21000
	v_cvt_pk_bf16_f32 v116, v156, v157
	v_cvt_pk_bf16_f32 v117, v118, v119
	v_cvt_pk_bf16_f32 v118, v154, v155
	v_cvt_pk_bf16_f32 v119, v158, v159
	global_store_dwordx4 v[160:161], v[116:119], off offset:64 sc1
	s_and_saveexec_b64 s[0:1], vcc
	s_cbranch_execz .LBB0_777
	s_add_u32 s10, s6, s8
	s_addc_u32 s11, s7, s2
	v_lshl_add_u64 v[116:117], v[132:133], 2, s[10:11]
	s_waitcnt lgkmcnt(0)
	v_add_f32_e32 v114, v114, v115
	global_store_dword v[116:117], v114, off
.LBB0_777:
	s_or_b64 exec, exec, s[0:1]
	s_waitcnt lgkmcnt(7)
	v_add_f32_e32 v114, v152, v153
	v_fmac_f32_e32 v151, 0x3a800000, v114
	v_rsq_f32_e32 v114, v151
	v_or_b32_e32 v116, 16, v132
	v_mov_b32_e32 v117, v133
	s_waitcnt lgkmcnt(0)
	v_pk_mul_f32 v[110:111], v[110:111], v[114:115] op_sel_hi:[1,0]
	v_pk_mul_f32 v[108:109], v[108:109], v[114:115] op_sel_hi:[1,0]
	v_pk_mul_f32 v[106:107], v[106:107], v[114:115] op_sel_hi:[1,0]
	v_pk_mul_f32 v[104:105], v[104:105], v[114:115] op_sel_hi:[1,0]
	v_pk_mul_f32 v[102:103], v[102:103], v[114:115] op_sel_hi:[1,0]
	v_pk_mul_f32 v[100:101], v[100:101], v[114:115] op_sel_hi:[1,0]
	v_pk_mul_f32 v[118:119], v[98:99], v[114:115] op_sel_hi:[1,0]
	v_pk_mul_f32 v[114:115], v[96:97], v[114:115] op_sel_hi:[1,0]
	v_lshlrev_b64 v[96:97], 10, v[116:117]
	v_mul_f32_e32 v98, v109, v109
	v_mul_f32_e32 v99, v111, v111
	v_lshl_add_u64 v[96:97], s[4:5], 0, v[96:97]
	v_fmac_f32_e32 v98, v108, v108
	v_fmac_f32_e32 v99, v110, v110
	v_lshl_add_u64 v[116:117], v[96:97], 0, v[112:113]
	v_cvt_pk_bf16_f32 v96, v108, v109
	v_add_f32_e32 v98, v98, v99
	v_mul_f32_e32 v99, v105, v105
	v_mul_f32_e32 v108, v107, v107
	v_fmac_f32_e32 v99, v104, v104
	v_fmac_f32_e32 v108, v106, v106
	v_add_f32_e32 v99, v99, v108
	v_add_f32_e32 v98, v98, v99
	v_mul_f32_e32 v99, v101, v101
	v_mul_f32_e32 v108, v103, v103
	v_fmac_f32_e32 v99, v100, v100
	v_fmac_f32_e32 v108, v102, v102
	v_add_f32_e32 v99, v99, v108
	v_mul_f32_e32 v108, v115, v115
	v_mul_f32_e32 v109, v119, v119
	v_fmac_f32_e32 v108, v114, v114
	v_fmac_f32_e32 v109, v118, v118
	v_add_f32_e32 v108, v108, v109
	v_add_f32_e32 v99, v99, v108
	v_add_f32_e32 v108, v98, v99
	ds_bpermute_b32 v109, v131, v108
	v_cvt_pk_bf16_f32 v97, v110, v111
	v_cvt_pk_bf16_f32 v98, v104, v105
	v_cvt_pk_bf16_f32 v99, v106, v107
	global_store_dwordx4 v[116:117], v[96:99], off sc1
	s_waitcnt lgkmcnt(0)
	s_nop 0
	v_add_f32_e32 v96, v108, v109
	ds_bpermute_b32 v97, v134, v96
	v_cvt_pk_bf16_f32 v98, v100, v101
	v_cvt_pk_bf16_f32 v99, v102, v103
	v_cvt_pk_bf16_f32 v100, v114, v115
	v_cvt_pk_bf16_f32 v101, v118, v119
	global_store_dwordx4 v[116:117], v[98:101], off offset:64 sc1
	s_and_saveexec_b64 s[0:1], vcc
	s_cbranch_execz .LBB0_779
	s_add_u32 s10, s6, s8
	s_addc_u32 s11, s7, s2
	v_lshl_add_u64 v[98:99], v[132:133], 2, s[10:11]
	s_waitcnt lgkmcnt(0)
	v_add_f32_e32 v96, v96, v97
	global_store_dword v[98:99], v96, off offset:64
.LBB0_779:
	s_or_b64 exec, exec, s[0:1]
	s_waitcnt lgkmcnt(0)
	v_add_f32_e32 v97, v149, v150
	v_mov_b32_e32 v96, 0x358637bd
	v_fmamk_f32 v97, v97, 0x3a800000, v96
	v_rsq_f32_e32 v98, v97
	v_mov_b32_e32 v113, 0
	v_or_b32_e32 v100, 32, v132
	v_mov_b32_e32 v101, v113
	v_pk_mul_f32 v[94:95], v[94:95], v[98:99] op_sel_hi:[1,0]
	v_pk_mul_f32 v[92:93], v[92:93], v[98:99] op_sel_hi:[1,0]
	v_pk_mul_f32 v[90:91], v[90:91], v[98:99] op_sel_hi:[1,0]
	v_pk_mul_f32 v[88:89], v[88:89], v[98:99] op_sel_hi:[1,0]
	v_pk_mul_f32 v[86:87], v[86:87], v[98:99] op_sel_hi:[1,0]
	v_pk_mul_f32 v[84:85], v[84:85], v[98:99] op_sel_hi:[1,0]
	v_pk_mul_f32 v[102:103], v[82:83], v[98:99] op_sel_hi:[1,0]
	v_pk_mul_f32 v[98:99], v[80:81], v[98:99] op_sel_hi:[1,0]
	v_lshlrev_b64 v[80:81], 10, v[100:101]
	v_mul_f32_e32 v82, v93, v93
	v_mul_f32_e32 v83, v95, v95
	v_lshl_add_u64 v[80:81], s[4:5], 0, v[80:81]
	v_fmac_f32_e32 v82, v92, v92
	v_fmac_f32_e32 v83, v94, v94
	v_lshl_add_u64 v[100:101], v[80:81], 0, v[112:113]
	v_cvt_pk_bf16_f32 v80, v92, v93
	v_add_f32_e32 v82, v82, v83
	v_mul_f32_e32 v83, v89, v89
	v_mul_f32_e32 v92, v91, v91
	v_fmac_f32_e32 v83, v88, v88
	v_fmac_f32_e32 v92, v90, v90
	v_add_f32_e32 v83, v83, v92
	v_add_f32_e32 v82, v82, v83
	v_mul_f32_e32 v83, v85, v85
	v_mul_f32_e32 v92, v87, v87
	v_fmac_f32_e32 v83, v84, v84
	v_fmac_f32_e32 v92, v86, v86
	v_add_f32_e32 v83, v83, v92
	v_mul_f32_e32 v92, v99, v99
	v_mul_f32_e32 v93, v103, v103
	v_fmac_f32_e32 v92, v98, v98
	v_fmac_f32_e32 v93, v102, v102
	v_add_f32_e32 v92, v92, v93
	v_add_f32_e32 v83, v83, v92
	v_add_f32_e32 v92, v82, v83
	ds_bpermute_b32 v93, v131, v92
	v_cvt_pk_bf16_f32 v81, v94, v95
	v_cvt_pk_bf16_f32 v82, v88, v89
	v_cvt_pk_bf16_f32 v83, v90, v91
	global_store_dwordx4 v[100:101], v[80:83], off sc1
	s_waitcnt lgkmcnt(0)
	s_nop 0
	v_add_f32_e32 v80, v92, v93
	ds_bpermute_b32 v81, v134, v80
	v_cvt_pk_bf16_f32 v82, v84, v85
	v_cvt_pk_bf16_f32 v83, v86, v87
	v_cvt_pk_bf16_f32 v84, v98, v99
	v_cvt_pk_bf16_f32 v85, v102, v103
	global_store_dwordx4 v[100:101], v[82:85], off offset:64 sc1
	s_and_saveexec_b64 s[0:1], vcc
	s_cbranch_execz .LBB0_781
	s_add_u32 s10, s6, s8
	s_addc_u32 s11, s7, s2
	v_lshl_add_u64 v[82:83], v[132:133], 2, s[10:11]
	s_waitcnt lgkmcnt(0)
	v_add_f32_e32 v80, v80, v81
	global_store_dword v[82:83], v80, off offset:128
.LBB0_781:
	s_or_b64 exec, exec, s[0:1]
	v_add_f32_e32 v80, v147, v148
	v_fmac_f32_e32 v96, 0x3a800000, v80
	v_rsq_f32_e32 v80, v96
	v_or_b32_e32 v82, 48, v132
	v_mov_b32_e32 v83, v113
	s_waitcnt lgkmcnt(0)
	v_pk_mul_f32 v[78:79], v[78:79], v[80:81] op_sel_hi:[1,0]
	v_pk_mul_f32 v[76:77], v[76:77], v[80:81] op_sel_hi:[1,0]
	v_pk_mul_f32 v[74:75], v[74:75], v[80:81] op_sel_hi:[1,0]
	v_pk_mul_f32 v[72:73], v[72:73], v[80:81] op_sel_hi:[1,0]
	v_pk_mul_f32 v[70:71], v[70:71], v[80:81] op_sel_hi:[1,0]
	v_pk_mul_f32 v[68:69], v[68:69], v[80:81] op_sel_hi:[1,0]
	v_pk_mul_f32 v[84:85], v[66:67], v[80:81] op_sel_hi:[1,0]
	v_pk_mul_f32 v[80:81], v[64:65], v[80:81] op_sel_hi:[1,0]
	v_lshlrev_b64 v[64:65], 10, v[82:83]
	v_mul_f32_e32 v66, v77, v77
	v_mul_f32_e32 v67, v79, v79
	v_lshl_add_u64 v[64:65], s[4:5], 0, v[64:65]
	v_fmac_f32_e32 v66, v76, v76
	v_fmac_f32_e32 v67, v78, v78
	v_lshl_add_u64 v[82:83], v[64:65], 0, v[112:113]
	v_cvt_pk_bf16_f32 v64, v76, v77
	v_add_f32_e32 v66, v66, v67
	v_mul_f32_e32 v67, v73, v73
	v_mul_f32_e32 v76, v75, v75
	v_fmac_f32_e32 v67, v72, v72
	v_fmac_f32_e32 v76, v74, v74
	v_add_f32_e32 v67, v67, v76
	v_add_f32_e32 v66, v66, v67
	v_mul_f32_e32 v67, v69, v69
	v_mul_f32_e32 v76, v71, v71
	v_fmac_f32_e32 v67, v68, v68
	v_fmac_f32_e32 v76, v70, v70
	v_add_f32_e32 v67, v67, v76
	v_mul_f32_e32 v76, v81, v81
	v_mul_f32_e32 v77, v85, v85
	v_fmac_f32_e32 v76, v80, v80
	v_fmac_f32_e32 v77, v84, v84
	v_add_f32_e32 v76, v76, v77
	v_add_f32_e32 v67, v67, v76
	v_add_f32_e32 v76, v66, v67
	ds_bpermute_b32 v77, v131, v76
	v_cvt_pk_bf16_f32 v65, v78, v79
	v_cvt_pk_bf16_f32 v66, v72, v73
	v_cvt_pk_bf16_f32 v67, v74, v75
	global_store_dwordx4 v[82:83], v[64:67], off sc1
	s_waitcnt lgkmcnt(0)
	s_nop 0
	v_add_f32_e32 v64, v76, v77
	ds_bpermute_b32 v65, v134, v64
	v_cvt_pk_bf16_f32 v66, v68, v69
	v_cvt_pk_bf16_f32 v67, v70, v71
	v_cvt_pk_bf16_f32 v68, v80, v81
	v_cvt_pk_bf16_f32 v69, v84, v85
	global_store_dwordx4 v[82:83], v[66:69], off offset:64 sc1
	s_and_saveexec_b64 s[0:1], vcc
	s_cbranch_execz .LBB0_783
	s_add_u32 s10, s6, s8
	s_addc_u32 s11, s7, s2
	v_lshl_add_u64 v[66:67], v[132:133], 2, s[10:11]
	s_waitcnt lgkmcnt(0)
	v_add_f32_e32 v64, v64, v65
	global_store_dword v[66:67], v64, off offset:192
.LBB0_783:
	s_or_b64 exec, exec, s[0:1]
	s_waitcnt lgkmcnt(0)
	v_add_f32_e32 v65, v145, v146
	v_mov_b32_e32 v64, 0x358637bd
	v_fmamk_f32 v65, v65, 0x3a800000, v64
	v_rsq_f32_e32 v66, v65
	v_mov_b32_e32 v113, 0
	v_add_u32_e32 v68, 0x80, v132
	v_mov_b32_e32 v69, v113
	v_pk_mul_f32 v[62:63], v[62:63], v[66:67] op_sel_hi:[1,0]
	v_pk_mul_f32 v[60:61], v[60:61], v[66:67] op_sel_hi:[1,0]
	v_pk_mul_f32 v[58:59], v[58:59], v[66:67] op_sel_hi:[1,0]
	v_pk_mul_f32 v[56:57], v[56:57], v[66:67] op_sel_hi:[1,0]
	v_pk_mul_f32 v[54:55], v[54:55], v[66:67] op_sel_hi:[1,0]
	v_pk_mul_f32 v[52:53], v[52:53], v[66:67] op_sel_hi:[1,0]
	v_pk_mul_f32 v[70:71], v[50:51], v[66:67] op_sel_hi:[1,0]
	v_pk_mul_f32 v[66:67], v[48:49], v[66:67] op_sel_hi:[1,0]
	v_lshlrev_b64 v[48:49], 10, v[68:69]
	v_mul_f32_e32 v50, v61, v61
	v_mul_f32_e32 v51, v63, v63
	v_lshl_add_u64 v[48:49], s[4:5], 0, v[48:49]
	v_fmac_f32_e32 v50, v60, v60
	v_fmac_f32_e32 v51, v62, v62
	v_lshl_add_u64 v[68:69], v[48:49], 0, v[112:113]
	v_cvt_pk_bf16_f32 v48, v60, v61
	v_add_f32_e32 v50, v50, v51
	v_mul_f32_e32 v51, v57, v57
	v_mul_f32_e32 v60, v59, v59
	v_fmac_f32_e32 v51, v56, v56
	v_fmac_f32_e32 v60, v58, v58
	v_add_f32_e32 v51, v51, v60
	v_add_f32_e32 v50, v50, v51
	v_mul_f32_e32 v51, v53, v53
	v_mul_f32_e32 v60, v55, v55
	v_fmac_f32_e32 v51, v52, v52
	v_fmac_f32_e32 v60, v54, v54
	v_add_f32_e32 v51, v51, v60
	v_mul_f32_e32 v60, v67, v67
	v_mul_f32_e32 v61, v71, v71
	v_fmac_f32_e32 v60, v66, v66
	v_fmac_f32_e32 v61, v70, v70
	v_add_f32_e32 v60, v60, v61
	v_add_f32_e32 v51, v51, v60
	v_add_f32_e32 v60, v50, v51
	ds_bpermute_b32 v61, v131, v60
	v_cvt_pk_bf16_f32 v49, v62, v63
	v_cvt_pk_bf16_f32 v50, v56, v57
	v_cvt_pk_bf16_f32 v51, v58, v59
	global_store_dwordx4 v[68:69], v[48:51], off sc1
	s_waitcnt lgkmcnt(0)
	s_nop 0
	v_add_f32_e32 v48, v60, v61
	ds_bpermute_b32 v49, v134, v48
	v_cvt_pk_bf16_f32 v50, v52, v53
	v_cvt_pk_bf16_f32 v51, v54, v55
	v_cvt_pk_bf16_f32 v52, v66, v67
	v_cvt_pk_bf16_f32 v53, v70, v71
	global_store_dwordx4 v[68:69], v[50:53], off offset:64 sc1
	s_and_saveexec_b64 s[0:1], vcc
	s_cbranch_execz .LBB0_785
	s_add_u32 s10, s6, s8
	s_addc_u32 s11, s7, s2
	v_lshl_add_u64 v[50:51], v[132:133], 2, s[10:11]
	s_waitcnt lgkmcnt(0)
	v_add_f32_e32 v48, v48, v49
	global_store_dword v[50:51], v48, off offset:512
.LBB0_785:
	s_or_b64 exec, exec, s[0:1]
	v_add_f32_e32 v48, v143, v144
	v_fmac_f32_e32 v64, 0x3a800000, v48
	v_rsq_f32_e32 v48, v64
	v_add_u32_e32 v50, 0x90, v132
	v_mov_b32_e32 v51, v113
	s_waitcnt lgkmcnt(0)
	v_pk_mul_f32 v[46:47], v[46:47], v[48:49] op_sel_hi:[1,0]
	v_pk_mul_f32 v[44:45], v[44:45], v[48:49] op_sel_hi:[1,0]
	v_pk_mul_f32 v[42:43], v[42:43], v[48:49] op_sel_hi:[1,0]
	v_pk_mul_f32 v[40:41], v[40:41], v[48:49] op_sel_hi:[1,0]
	v_pk_mul_f32 v[38:39], v[38:39], v[48:49] op_sel_hi:[1,0]
	v_pk_mul_f32 v[36:37], v[36:37], v[48:49] op_sel_hi:[1,0]
	v_pk_mul_f32 v[52:53], v[34:35], v[48:49] op_sel_hi:[1,0]
	v_pk_mul_f32 v[48:49], v[32:33], v[48:49] op_sel_hi:[1,0]
	v_lshlrev_b64 v[32:33], 10, v[50:51]
	v_mul_f32_e32 v34, v45, v45
	v_mul_f32_e32 v35, v47, v47
	v_lshl_add_u64 v[32:33], s[4:5], 0, v[32:33]
	v_fmac_f32_e32 v34, v44, v44
	v_fmac_f32_e32 v35, v46, v46
	v_lshl_add_u64 v[50:51], v[32:33], 0, v[112:113]
	v_cvt_pk_bf16_f32 v32, v44, v45
	v_add_f32_e32 v34, v34, v35
	v_mul_f32_e32 v35, v41, v41
	v_mul_f32_e32 v44, v43, v43
	v_fmac_f32_e32 v35, v40, v40
	v_fmac_f32_e32 v44, v42, v42
	v_add_f32_e32 v35, v35, v44
	v_add_f32_e32 v34, v34, v35
	v_mul_f32_e32 v35, v37, v37
	v_mul_f32_e32 v44, v39, v39
	v_fmac_f32_e32 v35, v36, v36
	v_fmac_f32_e32 v44, v38, v38
	v_add_f32_e32 v35, v35, v44
	v_mul_f32_e32 v44, v49, v49
	v_mul_f32_e32 v45, v53, v53
	v_fmac_f32_e32 v44, v48, v48
	v_fmac_f32_e32 v45, v52, v52
	v_add_f32_e32 v44, v44, v45
	v_add_f32_e32 v35, v35, v44
	v_add_f32_e32 v44, v34, v35
	ds_bpermute_b32 v45, v131, v44
	v_cvt_pk_bf16_f32 v33, v46, v47
	v_cvt_pk_bf16_f32 v34, v40, v41
	v_cvt_pk_bf16_f32 v35, v42, v43
	global_store_dwordx4 v[50:51], v[32:35], off sc1
	s_waitcnt lgkmcnt(0)
	s_nop 0
	v_add_f32_e32 v32, v44, v45
	ds_bpermute_b32 v33, v134, v32
	v_cvt_pk_bf16_f32 v34, v36, v37
	v_cvt_pk_bf16_f32 v35, v38, v39
	v_cvt_pk_bf16_f32 v36, v48, v49
	v_cvt_pk_bf16_f32 v37, v52, v53
	global_store_dwordx4 v[50:51], v[34:37], off offset:64 sc1
	s_and_saveexec_b64 s[0:1], vcc
	s_cbranch_execz .LBB0_787
	s_add_u32 s10, s6, s8
	s_addc_u32 s11, s7, s2
	v_lshl_add_u64 v[34:35], v[132:133], 2, s[10:11]
	s_waitcnt lgkmcnt(0)
	v_add_f32_e32 v32, v32, v33
	global_store_dword v[34:35], v32, off offset:576
.LBB0_787:
	s_or_b64 exec, exec, s[0:1]
	s_waitcnt lgkmcnt(0)
	v_add_f32_e32 v33, v137, v142
	v_mov_b32_e32 v32, 0x358637bd
	v_fmamk_f32 v33, v33, 0x3a800000, v32
	v_rsq_f32_e32 v34, v33
	v_mov_b32_e32 v113, 0
	v_add_u32_e32 v36, 0xa0, v132
	v_mov_b32_e32 v37, v113
	v_pk_mul_f32 v[30:31], v[30:31], v[34:35] op_sel_hi:[1,0]
	v_pk_mul_f32 v[28:29], v[28:29], v[34:35] op_sel_hi:[1,0]
	v_pk_mul_f32 v[26:27], v[26:27], v[34:35] op_sel_hi:[1,0]
	v_pk_mul_f32 v[24:25], v[24:25], v[34:35] op_sel_hi:[1,0]
	v_pk_mul_f32 v[22:23], v[22:23], v[34:35] op_sel_hi:[1,0]
	v_pk_mul_f32 v[20:21], v[20:21], v[34:35] op_sel_hi:[1,0]
	v_pk_mul_f32 v[38:39], v[18:19], v[34:35] op_sel_hi:[1,0]
	v_pk_mul_f32 v[34:35], v[16:17], v[34:35] op_sel_hi:[1,0]
	v_lshlrev_b64 v[16:17], 10, v[36:37]
	v_mul_f32_e32 v18, v29, v29
	v_mul_f32_e32 v19, v31, v31
	v_lshl_add_u64 v[16:17], s[4:5], 0, v[16:17]
	v_fmac_f32_e32 v18, v28, v28
	v_fmac_f32_e32 v19, v30, v30
	v_lshl_add_u64 v[36:37], v[16:17], 0, v[112:113]
	v_cvt_pk_bf16_f32 v16, v28, v29
	v_add_f32_e32 v18, v18, v19
	v_mul_f32_e32 v19, v25, v25
	v_mul_f32_e32 v28, v27, v27
	v_fmac_f32_e32 v19, v24, v24
	v_fmac_f32_e32 v28, v26, v26
	v_add_f32_e32 v19, v19, v28
	v_add_f32_e32 v18, v18, v19
	v_mul_f32_e32 v19, v21, v21
	v_mul_f32_e32 v28, v23, v23
	v_fmac_f32_e32 v19, v20, v20
	v_fmac_f32_e32 v28, v22, v22
	v_add_f32_e32 v19, v19, v28
	v_mul_f32_e32 v28, v35, v35
	v_mul_f32_e32 v29, v39, v39
	v_fmac_f32_e32 v28, v34, v34
	v_fmac_f32_e32 v29, v38, v38
	v_add_f32_e32 v28, v28, v29
	v_add_f32_e32 v19, v19, v28
	v_add_f32_e32 v28, v18, v19
	ds_bpermute_b32 v29, v131, v28
	v_cvt_pk_bf16_f32 v17, v30, v31
	v_cvt_pk_bf16_f32 v18, v24, v25
	v_cvt_pk_bf16_f32 v19, v26, v27
	global_store_dwordx4 v[36:37], v[16:19], off sc1
	s_waitcnt lgkmcnt(0)
	s_nop 0
	v_add_f32_e32 v16, v28, v29
	ds_bpermute_b32 v17, v134, v16
	v_cvt_pk_bf16_f32 v18, v20, v21
	v_cvt_pk_bf16_f32 v19, v22, v23
	v_cvt_pk_bf16_f32 v20, v34, v35
	v_cvt_pk_bf16_f32 v21, v38, v39
	global_store_dwordx4 v[36:37], v[18:21], off offset:64 sc1
	s_and_saveexec_b64 s[0:1], vcc
	s_cbranch_execz .LBB0_789
	s_add_u32 s10, s6, s8
	s_addc_u32 s11, s7, s2
	v_lshl_add_u64 v[18:19], v[132:133], 2, s[10:11]
	s_waitcnt lgkmcnt(0)
	v_add_f32_e32 v16, v16, v17
	global_store_dword v[18:19], v16, off offset:640
.LBB0_789:
	s_or_b64 exec, exec, s[0:1]
	v_add_f32_e32 v16, v135, v136
	v_fmac_f32_e32 v32, 0x3a800000, v16
	v_rsq_f32_e32 v16, v32
	v_add_u32_e32 v18, 0xb0, v132
	v_mov_b32_e32 v19, v113
	s_waitcnt lgkmcnt(0)
	v_pk_mul_f32 v[14:15], v[14:15], v[16:17] op_sel_hi:[1,0]
	v_pk_mul_f32 v[12:13], v[12:13], v[16:17] op_sel_hi:[1,0]
	v_pk_mul_f32 v[10:11], v[10:11], v[16:17] op_sel_hi:[1,0]
	v_pk_mul_f32 v[8:9], v[8:9], v[16:17] op_sel_hi:[1,0]
	v_pk_mul_f32 v[6:7], v[6:7], v[16:17] op_sel_hi:[1,0]
	v_pk_mul_f32 v[4:5], v[4:5], v[16:17] op_sel_hi:[1,0]
	v_pk_mul_f32 v[20:21], v[2:3], v[16:17] op_sel_hi:[1,0]
	v_pk_mul_f32 v[16:17], v[0:1], v[16:17] op_sel_hi:[1,0]
	v_lshlrev_b64 v[0:1], 10, v[18:19]
	v_mul_f32_e32 v2, v13, v13
	v_mul_f32_e32 v3, v15, v15
	v_lshl_add_u64 v[0:1], s[4:5], 0, v[0:1]
	v_fmac_f32_e32 v2, v12, v12
	v_fmac_f32_e32 v3, v14, v14
	v_lshl_add_u64 v[18:19], v[0:1], 0, v[112:113]
	v_cvt_pk_bf16_f32 v0, v12, v13
	v_add_f32_e32 v2, v2, v3
	v_mul_f32_e32 v3, v9, v9
	v_mul_f32_e32 v12, v11, v11
	v_fmac_f32_e32 v3, v8, v8
	v_fmac_f32_e32 v12, v10, v10
	v_add_f32_e32 v3, v3, v12
	v_add_f32_e32 v2, v2, v3
	v_mul_f32_e32 v3, v5, v5
	v_mul_f32_e32 v12, v7, v7
	v_fmac_f32_e32 v3, v4, v4
	v_fmac_f32_e32 v12, v6, v6
	v_add_f32_e32 v3, v3, v12
	v_mul_f32_e32 v12, v17, v17
	v_mul_f32_e32 v13, v21, v21
	v_fmac_f32_e32 v12, v16, v16
	v_fmac_f32_e32 v13, v20, v20
	v_add_f32_e32 v12, v12, v13
	v_add_f32_e32 v3, v3, v12
	v_add_f32_e32 v12, v2, v3
	ds_bpermute_b32 v13, v131, v12
	v_cvt_pk_bf16_f32 v1, v14, v15
	v_cvt_pk_bf16_f32 v2, v8, v9
	v_cvt_pk_bf16_f32 v3, v10, v11
	global_store_dwordx4 v[18:19], v[0:3], off sc1
	s_waitcnt lgkmcnt(0)
	s_nop 0
	v_add_f32_e32 v0, v12, v13
	ds_bpermute_b32 v1, v134, v0
	v_cvt_pk_bf16_f32 v2, v4, v5
	v_cvt_pk_bf16_f32 v3, v6, v7
	v_cvt_pk_bf16_f32 v4, v16, v17
	v_cvt_pk_bf16_f32 v5, v20, v21
	global_store_dwordx4 v[18:19], v[2:5], off offset:64 sc1
	s_and_saveexec_b64 s[0:1], vcc
	s_cbranch_execz .LBB0_791
	s_add_u32 s4, s6, s8
	s_addc_u32 s5, s7, s2
	v_lshl_add_u64 v[2:3], v[132:133], 2, s[4:5]
	s_waitcnt lgkmcnt(0)
	v_add_f32_e32 v0, v0, v1
	global_store_dword v[2:3], v0, off offset:704

.LBB0_883:
	ds_read_b128 v[128:131], v186
	ds_read_b128 v[132:135], v186 offset:1024
	ds_read_b128 v[136:139], v186 offset:2048
	ds_read_b128 v[140:143], v186 offset:3072
	s_add_u32 s28, s26, 0xfffc0080
	s_addc_u32 s29, s27, -1
	s_cmp_eq_u32 s40, 12
	s_cselect_b32 s31, s25, s29
	s_cselect_b32 s30, s34, s28
	s_cselect_b32 s29, s36, s39
	s_cselect_b32 s28, s37, s38
	v_lshl_add_u64 v[182:183], s[26:27], 0, v[164:165]
	s_add_i32 m0, s45, 0xc000
	ds_read_b128 v[144:147], v187
	ds_read_b128 v[148:151], v187 offset:1024
	ds_read_b128 v[152:155], v187 offset:2048
	ds_read_b128 v[156:159], v187 offset:3072
	ds_read_b128 v[170:173], v187 offset:4096
	ds_read_b128 v[174:177], v187 offset:5120
	ds_read_b128 v[178:181], v187 offset:6144
	ds_read_b128 v[192:195], v187 offset:7168
	global_load_lds_dwordx4 v[182:183], off
	v_lshl_add_u64 v[182:183], s[26:27], 0, v[166:167]
	s_add_i32 m0, s45, 0xe000
	s_nop 0
	global_load_lds_dwordx4 v[182:183], off
	ds_read_b128 v[196:199], v188
	ds_read_b128 v[204:207], v188 offset:1024
	ds_read_b128 v[208:211], v188 offset:2048
	ds_read_b128 v[212:215], v188 offset:3072
	s_waitcnt lgkmcnt(0)
	s_waitcnt vmcnt(8)
	s_barrier
	s_setprio 1
	v_mfma_f32_16x16x32_bf16 v[124:127], v[128:131], v[144:147], v[124:127]
	v_mfma_f32_16x16x32_bf16 v[120:123], v[136:139], v[144:147], v[120:123]
	v_mfma_f32_16x16x32_bf16 v[108:111], v[128:131], v[152:155], v[108:111]
	v_mfma_f32_16x16x32_bf16 v[104:107], v[136:139], v[152:155], v[104:107]
	v_mfma_f32_16x16x32_bf16 v[92:95], v[128:131], v[170:173], v[92:95]
	v_mfma_f32_16x16x32_bf16 v[88:91], v[136:139], v[170:173], v[88:91]
	v_mfma_f32_16x16x32_bf16 v[76:79], v[128:131], v[178:181], v[76:79]
	v_mfma_f32_16x16x32_bf16 v[72:75], v[136:139], v[178:181], v[72:75]
	v_mfma_f32_16x16x32_bf16 v[124:127], v[132:135], v[148:151], v[124:127]
	v_mfma_f32_16x16x32_bf16 v[120:123], v[140:143], v[148:151], v[120:123]
	v_mfma_f32_16x16x32_bf16 v[108:111], v[132:135], v[156:159], v[108:111]
	v_mfma_f32_16x16x32_bf16 v[104:107], v[140:143], v[156:159], v[104:107]
	v_mfma_f32_16x16x32_bf16 v[92:95], v[132:135], v[174:177], v[92:95]
	v_mfma_f32_16x16x32_bf16 v[88:91], v[140:143], v[174:177], v[88:91]
	v_mfma_f32_16x16x32_bf16 v[76:79], v[132:135], v[192:195], v[76:79]
	v_mfma_f32_16x16x32_bf16 v[72:75], v[140:143], v[192:195], v[72:75]
	v_mfma_f32_16x16x32_bf16 v[116:119], v[196:199], v[144:147], v[116:119]
	v_mfma_f32_16x16x32_bf16 v[112:115], v[208:211], v[144:147], v[112:115]
	v_mfma_f32_16x16x32_bf16 v[100:103], v[196:199], v[152:155], v[100:103]
	v_mfma_f32_16x16x32_bf16 v[96:99], v[208:211], v[152:155], v[96:99]
	v_mfma_f32_16x16x32_bf16 v[84:87], v[196:199], v[170:173], v[84:87]
	v_mfma_f32_16x16x32_bf16 v[80:83], v[208:211], v[170:173], v[80:83]
	v_mfma_f32_16x16x32_bf16 v[68:71], v[196:199], v[178:181], v[68:71]
	v_mfma_f32_16x16x32_bf16 v[64:67], v[208:211], v[178:181], v[64:67]
	v_mfma_f32_16x16x32_bf16 v[116:119], v[204:207], v[148:151], v[116:119]
	v_mfma_f32_16x16x32_bf16 v[112:115], v[212:215], v[148:151], v[112:115]
	v_mfma_f32_16x16x32_bf16 v[100:103], v[204:207], v[156:159], v[100:103]
	v_mfma_f32_16x16x32_bf16 v[96:99], v[212:215], v[156:159], v[96:99]
	v_mfma_f32_16x16x32_bf16 v[84:87], v[204:207], v[174:177], v[84:87]
	v_mfma_f32_16x16x32_bf16 v[80:83], v[212:215], v[174:177], v[80:83]
	v_mfma_f32_16x16x32_bf16 v[68:71], v[204:207], v[192:195], v[68:71]
	v_mfma_f32_16x16x32_bf16 v[64:67], v[212:215], v[192:195], v[64:67]
	s_setprio 0
	s_barrier
	ds_read_b128 v[144:147], v187 offset:16384
	ds_read_b128 v[148:151], v187 offset:17408
	ds_read_b128 v[152:155], v187 offset:18432
	ds_read_b128 v[156:159], v187 offset:19456
	ds_read_b128 v[170:173], v187 offset:20480
	ds_read_b128 v[174:177], v187 offset:21504
	ds_read_b128 v[178:181], v187 offset:22528
	ds_read_b128 v[192:195], v187 offset:23552
	s_mov_b32 m0, s43
	v_lshl_add_u64 v[182:183], s[28:29], 0, v[160:161]
	global_load_lds_dwordx4 v[182:183], off
	v_lshl_add_u64 v[200:201], s[28:29], 0, v[162:163]
	s_mov_b32 m0, s44
	s_nop 0
	global_load_lds_dwordx4 v[200:201], off
	s_mov_b32 m0, s45
	v_lshl_add_u64 v[216:217], s[30:31], 0, v[160:161]
	global_load_lds_dwordx4 v[216:217], off
	v_lshl_add_u64 v[218:219], s[30:31], 0, v[162:163]
	s_mov_b32 m0, s46
	s_nop 0
	global_load_lds_dwordx4 v[218:219], off
	s_add_u32 s66, s28, 0x40000
	s_addc_u32 s67, s29, 0
	s_mov_b32 m0, s47
	v_lshl_add_u64 v[248:249], s[66:67], 0, v[160:161]
	global_load_lds_dwordx4 v[248:249], off
	v_lshl_add_u64 v[248:249], s[66:67], 0, v[162:163]
	s_mov_b32 m0, s48
	s_nop 0
	global_load_lds_dwordx4 v[248:249], off
	s_waitcnt lgkmcnt(0)
	s_waitcnt vmcnt(8)
	s_barrier
	s_setprio 1
	v_mfma_f32_16x16x32_bf16 v[60:63], v[128:131], v[144:147], v[60:63]
	v_mfma_f32_16x16x32_bf16 v[56:59], v[136:139], v[144:147], v[56:59]
	v_mfma_f32_16x16x32_bf16 v[44:47], v[128:131], v[152:155], v[44:47]
	v_mfma_f32_16x16x32_bf16 v[40:43], v[136:139], v[152:155], v[40:43]
	v_mfma_f32_16x16x32_bf16 v[28:31], v[128:131], v[170:173], v[28:31]
	v_mfma_f32_16x16x32_bf16 v[24:27], v[136:139], v[170:173], v[24:27]
	v_mfma_f32_16x16x32_bf16 v[12:15], v[128:131], v[178:181], v[12:15]
	v_mfma_f32_16x16x32_bf16 v[8:11], v[136:139], v[178:181], v[8:11]
	v_mfma_f32_16x16x32_bf16 v[60:63], v[132:135], v[148:151], v[60:63]
	v_mfma_f32_16x16x32_bf16 v[56:59], v[140:143], v[148:151], v[56:59]
	v_mfma_f32_16x16x32_bf16 v[44:47], v[132:135], v[156:159], v[44:47]
	v_mfma_f32_16x16x32_bf16 v[40:43], v[140:143], v[156:159], v[40:43]
	v_mfma_f32_16x16x32_bf16 v[28:31], v[132:135], v[174:177], v[28:31]
	v_mfma_f32_16x16x32_bf16 v[24:27], v[140:143], v[174:177], v[24:27]
	v_mfma_f32_16x16x32_bf16 v[12:15], v[132:135], v[192:195], v[12:15]
	v_mfma_f32_16x16x32_bf16 v[8:11], v[140:143], v[192:195], v[8:11]
	v_mfma_f32_16x16x32_bf16 v[52:55], v[196:199], v[144:147], v[52:55]
	v_mfma_f32_16x16x32_bf16 v[48:51], v[208:211], v[144:147], v[48:51]
	v_mfma_f32_16x16x32_bf16 v[36:39], v[196:199], v[152:155], v[36:39]
	v_mfma_f32_16x16x32_bf16 v[32:35], v[208:211], v[152:155], v[32:35]
	v_mfma_f32_16x16x32_bf16 v[20:23], v[196:199], v[170:173], v[20:23]
	v_mfma_f32_16x16x32_bf16 v[16:19], v[208:211], v[170:173], v[16:19]
	v_mfma_f32_16x16x32_bf16 v[4:7], v[196:199], v[178:181], v[4:7]
	v_mfma_f32_16x16x32_bf16 v[0:3], v[208:211], v[178:181], v[0:3]
	v_mfma_f32_16x16x32_bf16 v[52:55], v[204:207], v[148:151], v[52:55]
	v_mfma_f32_16x16x32_bf16 v[48:51], v[212:215], v[148:151], v[48:51]
	v_mfma_f32_16x16x32_bf16 v[36:39], v[204:207], v[156:159], v[36:39]
	v_mfma_f32_16x16x32_bf16 v[32:35], v[212:215], v[156:159], v[32:35]
	v_mfma_f32_16x16x32_bf16 v[20:23], v[204:207], v[174:177], v[20:23]
	v_mfma_f32_16x16x32_bf16 v[16:19], v[212:215], v[174:177], v[16:19]
	v_mfma_f32_16x16x32_bf16 v[4:7], v[204:207], v[192:195], v[4:7]
	v_mfma_f32_16x16x32_bf16 v[0:3], v[212:215], v[192:195], v[0:3]
	s_setprio 0
	s_barrier
	ds_read_b128 v[128:131], v189
	ds_read_b128 v[132:135], v189 offset:1024
	ds_read_b128 v[136:139], v189 offset:2048
	ds_read_b128 v[140:143], v189 offset:3072
	s_add_u32 s30, s30, 0x40000
	s_addc_u32 s31, s31, 0
	s_mov_b32 m0, s49
	v_lshl_add_u64 v[196:197], s[30:31], 0, v[160:161]
	ds_read_b128 v[144:147], v187 offset:32768
	ds_read_b128 v[148:151], v187 offset:33792
	ds_read_b128 v[152:155], v187 offset:34816
	ds_read_b128 v[156:159], v187 offset:35840
	ds_read_b128 v[170:173], v187 offset:36864
	ds_read_b128 v[174:177], v187 offset:37888
	ds_read_b128 v[178:181], v187 offset:38912
	ds_read_b128 v[192:195], v187 offset:39936
	global_load_lds_dwordx4 v[196:197], off
	v_lshl_add_u64 v[196:197], s[30:31], 0, v[162:163]
	s_mov_b32 m0, s50
	s_nop 0
	global_load_lds_dwordx4 v[196:197], off
	ds_read_b128 v[196:199], v190
	ds_read_b128 v[204:207], v190 offset:1024
	ds_read_b128 v[208:211], v190 offset:2048
	ds_read_b128 v[212:215], v190 offset:3072
	s_waitcnt lgkmcnt(0)
	s_waitcnt vmcnt(8)
	s_barrier
	s_setprio 1
	v_mfma_f32_16x16x32_bf16 v[124:127], v[128:131], v[144:147], v[124:127]
	v_mfma_f32_16x16x32_bf16 v[120:123], v[136:139], v[144:147], v[120:123]
	v_mfma_f32_16x16x32_bf16 v[108:111], v[128:131], v[152:155], v[108:111]
	v_mfma_f32_16x16x32_bf16 v[104:107], v[136:139], v[152:155], v[104:107]
	v_mfma_f32_16x16x32_bf16 v[92:95], v[128:131], v[170:173], v[92:95]
	v_mfma_f32_16x16x32_bf16 v[88:91], v[136:139], v[170:173], v[88:91]
	v_mfma_f32_16x16x32_bf16 v[76:79], v[128:131], v[178:181], v[76:79]
	v_mfma_f32_16x16x32_bf16 v[72:75], v[136:139], v[178:181], v[72:75]
	v_mfma_f32_16x16x32_bf16 v[124:127], v[132:135], v[148:151], v[124:127]
	v_mfma_f32_16x16x32_bf16 v[120:123], v[140:143], v[148:151], v[120:123]
	v_mfma_f32_16x16x32_bf16 v[108:111], v[132:135], v[156:159], v[108:111]
	v_mfma_f32_16x16x32_bf16 v[104:107], v[140:143], v[156:159], v[104:107]
	v_mfma_f32_16x16x32_bf16 v[92:95], v[132:135], v[174:177], v[92:95]
	v_mfma_f32_16x16x32_bf16 v[88:91], v[140:143], v[174:177], v[88:91]
	v_mfma_f32_16x16x32_bf16 v[76:79], v[132:135], v[192:195], v[76:79]
	v_mfma_f32_16x16x32_bf16 v[72:75], v[140:143], v[192:195], v[72:75]
	v_mfma_f32_16x16x32_bf16 v[116:119], v[196:199], v[144:147], v[116:119]
	v_mfma_f32_16x16x32_bf16 v[112:115], v[208:211], v[144:147], v[112:115]
	v_mfma_f32_16x16x32_bf16 v[100:103], v[196:199], v[152:155], v[100:103]
	v_mfma_f32_16x16x32_bf16 v[96:99], v[208:211], v[152:155], v[96:99]
	v_mfma_f32_16x16x32_bf16 v[84:87], v[196:199], v[170:173], v[84:87]
	v_mfma_f32_16x16x32_bf16 v[80:83], v[208:211], v[170:173], v[80:83]
	v_mfma_f32_16x16x32_bf16 v[68:71], v[196:199], v[178:181], v[68:71]
	v_mfma_f32_16x16x32_bf16 v[64:67], v[208:211], v[178:181], v[64:67]
	v_mfma_f32_16x16x32_bf16 v[116:119], v[204:207], v[148:151], v[116:119]
	v_mfma_f32_16x16x32_bf16 v[112:115], v[212:215], v[148:151], v[112:115]
	v_mfma_f32_16x16x32_bf16 v[100:103], v[204:207], v[156:159], v[100:103]
	v_mfma_f32_16x16x32_bf16 v[96:99], v[212:215], v[156:159], v[96:99]
	v_mfma_f32_16x16x32_bf16 v[84:87], v[204:207], v[174:177], v[84:87]
	v_mfma_f32_16x16x32_bf16 v[80:83], v[212:215], v[174:177], v[80:83]
	v_mfma_f32_16x16x32_bf16 v[68:71], v[204:207], v[192:195], v[68:71]
	v_mfma_f32_16x16x32_bf16 v[64:67], v[212:215], v[192:195], v[64:67]
	s_setprio 0
	s_barrier
	ds_read_b128 v[144:147], v187 offset:49152
	ds_read_b128 v[148:151], v187 offset:50176
	ds_read_b128 v[152:155], v187 offset:51200
	ds_read_b128 v[156:159], v187 offset:52224
	ds_read_b128 v[170:173], v187 offset:53248
	ds_read_b128 v[174:177], v187 offset:54272
	ds_read_b128 v[178:181], v187 offset:55296
	ds_read_b128 v[192:195], v187 offset:56320
	s_mov_b32 m0, s54
	v_lshl_add_u64 v[182:183], v[182:183], 0, s[12:13]
	global_load_lds_dwordx4 v[182:183], off
	v_lshl_add_u64 v[182:183], v[200:201], 0, s[12:13]
	s_mov_b32 m0, s55
	s_nop 0
	global_load_lds_dwordx4 v[182:183], off
	s_mov_b32 m0, s56
	v_lshl_add_u64 v[182:183], v[216:217], 0, s[12:13]
	global_load_lds_dwordx4 v[182:183], off
	v_lshl_add_u64 v[182:183], v[218:219], 0, s[12:13]
	s_mov_b32 m0, s57
	s_nop 0
	global_load_lds_dwordx4 v[182:183], off
	s_add_u32 s28, s28, 0x40080
	s_addc_u32 s29, s29, 0
	s_mov_b32 m0, s58
	v_lshl_add_u64 v[248:249], s[28:29], 0, v[160:161]
	global_load_lds_dwordx4 v[248:249], off
	v_lshl_add_u64 v[248:249], s[28:29], 0, v[162:163]
	s_mov_b32 m0, s59
	s_nop 0
	global_load_lds_dwordx4 v[248:249], off
	s_waitcnt lgkmcnt(0)
	s_waitcnt vmcnt(8)
	s_barrier
	s_setprio 1
	v_mfma_f32_16x16x32_bf16 v[60:63], v[128:131], v[144:147], v[60:63]
	v_mfma_f32_16x16x32_bf16 v[56:59], v[136:139], v[144:147], v[56:59]
	v_mfma_f32_16x16x32_bf16 v[44:47], v[128:131], v[152:155], v[44:47]
	v_mfma_f32_16x16x32_bf16 v[40:43], v[136:139], v[152:155], v[40:43]
	v_mfma_f32_16x16x32_bf16 v[28:31], v[128:131], v[170:173], v[28:31]
	v_mfma_f32_16x16x32_bf16 v[24:27], v[136:139], v[170:173], v[24:27]
	v_mfma_f32_16x16x32_bf16 v[12:15], v[128:131], v[178:181], v[12:15]
	v_mfma_f32_16x16x32_bf16 v[8:11], v[136:139], v[178:181], v[8:11]
	v_mfma_f32_16x16x32_bf16 v[60:63], v[132:135], v[148:151], v[60:63]
	v_mfma_f32_16x16x32_bf16 v[56:59], v[140:143], v[148:151], v[56:59]
	v_mfma_f32_16x16x32_bf16 v[44:47], v[132:135], v[156:159], v[44:47]
	v_mfma_f32_16x16x32_bf16 v[40:43], v[140:143], v[156:159], v[40:43]
	v_mfma_f32_16x16x32_bf16 v[28:31], v[132:135], v[174:177], v[28:31]
	v_mfma_f32_16x16x32_bf16 v[24:27], v[140:143], v[174:177], v[24:27]
	v_mfma_f32_16x16x32_bf16 v[12:15], v[132:135], v[192:195], v[12:15]
	v_mfma_f32_16x16x32_bf16 v[8:11], v[140:143], v[192:195], v[8:11]
	v_mfma_f32_16x16x32_bf16 v[52:55], v[196:199], v[144:147], v[52:55]
	v_mfma_f32_16x16x32_bf16 v[48:51], v[208:211], v[144:147], v[48:51]
	v_mfma_f32_16x16x32_bf16 v[36:39], v[196:199], v[152:155], v[36:39]
	v_mfma_f32_16x16x32_bf16 v[32:35], v[208:211], v[152:155], v[32:35]
	v_mfma_f32_16x16x32_bf16 v[20:23], v[196:199], v[170:173], v[20:23]
	v_mfma_f32_16x16x32_bf16 v[16:19], v[208:211], v[170:173], v[16:19]
	v_mfma_f32_16x16x32_bf16 v[4:7], v[196:199], v[178:181], v[4:7]
	v_mfma_f32_16x16x32_bf16 v[0:3], v[208:211], v[178:181], v[0:3]
	v_mfma_f32_16x16x32_bf16 v[52:55], v[204:207], v[148:151], v[52:55]
	v_mfma_f32_16x16x32_bf16 v[48:51], v[212:215], v[148:151], v[48:51]
	v_mfma_f32_16x16x32_bf16 v[36:39], v[204:207], v[156:159], v[36:39]
	v_mfma_f32_16x16x32_bf16 v[32:35], v[212:215], v[156:159], v[32:35]
	v_mfma_f32_16x16x32_bf16 v[20:23], v[204:207], v[174:177], v[20:23]
	v_mfma_f32_16x16x32_bf16 v[16:19], v[212:215], v[174:177], v[16:19]
	v_mfma_f32_16x16x32_bf16 v[4:7], v[204:207], v[192:195], v[4:7]
	v_mfma_f32_16x16x32_bf16 v[0:3], v[212:215], v[192:195], v[0:3]
	s_setprio 0
	s_add_i32 s40, s40, 2
	s_add_u32 s26, s26, 0x100
	s_addc_u32 s27, s27, 0
	s_add_u32 s38, s38, 0x100
	s_addc_u32 s39, s39, 0
	s_cmp_gt_u32 s40, 13
	s_barrier
	s_cbranch_scc0 .LBB0_883
	v_lshl_or_b32 v128, s65, 8, v185
	v_lshl_add_u32 v170, s24, 8, v184
	v_ashrrev_i32_e32 v129, 31, v128
	v_lshlrev_b64 v[174:175], 1, v[128:129]
	v_ashrrev_i32_e32 v171, 31, v170
	v_lshl_add_u64 v[128:129], s[10:11], 0, v[174:175]
	v_lshlrev_b64 v[204:205], 11, v[170:171]
	v_lshl_add_u64 v[130:131], v[128:129], 0, v[204:205]
	global_load_dwordx4 v[194:197], v[130:131], off
	global_load_dwordx4 v[198:201], v[130:131], off offset:64
	v_or_b32_e32 v130, 16, v170
	v_or_b32_e32 v132, 32, v170
	v_or_b32_e32 v134, 48, v170
	v_ashrrev_i32_e32 v131, 31, v130
	v_ashrrev_i32_e32 v133, 31, v132
	v_ashrrev_i32_e32 v135, 31, v134
	v_lshlrev_b64 v[182:183], 11, v[130:131]
	v_add_u32_e32 v178, 0x80, v170
	v_lshlrev_b64 v[180:181], 11, v[132:133]
	v_lshlrev_b64 v[176:177], 11, v[134:135]
	v_lshl_add_u64 v[132:133], v[128:129], 0, v[182:183]
	v_ashrrev_i32_e32 v179, 31, v178
	v_lshl_add_u64 v[134:135], v[128:129], 0, v[180:181]
	v_lshl_add_u64 v[128:129], v[128:129], 0, v[176:177]
	global_load_dwordx4 v[156:159], v[132:133], off
	global_load_dwordx4 v[152:155], v[132:133], off offset:64
	global_load_dwordx4 v[148:151], v[134:135], off
	global_load_dwordx4 v[144:147], v[134:135], off offset:64
	global_load_dwordx4 v[140:143], v[128:129], off
	global_load_dwordx4 v[136:139], v[128:129], off offset:64
	v_lshlrev_b64 v[130:131], 11, v[178:179]
	v_lshl_add_u64 v[130:131], s[10:11], 0, v[130:131]
	v_lshl_add_u64 v[172:173], v[130:131], 0, v[174:175]
	global_load_dwordx4 v[132:135], v[172:173], off
	global_load_dwordx4 v[128:131], v[172:173], off offset:64
	v_and_b32_e32 v192, 64, v191
	v_xor_b32_e32 v179, 16, v191
	v_add_u32_e32 v192, 64, v192
	v_xor_b32_e32 v193, 32, v191
	v_cmp_lt_i32_e32 vcc, v179, v192
	v_lshl_add_u64 v[204:205], s[10:11], 0, v[204:205]
	v_lshl_add_u64 v[204:205], v[204:205], 0, v[174:175]
	v_cndmask_b32_e32 v179, v191, v179, vcc
	v_cmp_lt_i32_e32 vcc, v193, v192
	v_lshlrev_b32_e32 v192, 2, v179
	s_lshl_b32 s24, s65, 2
	v_cndmask_b32_e32 v193, v191, v193, vcc
	v_lshlrev_b32_e32 v179, 2, v193
	s_or_b32 s27, s24, s53
	s_mul_hi_i32 s26, s27, 0x21000
	s_mul_i32 s27, s27, 0x21000
	s_waitcnt vmcnt(0)
	v_lshlrev_b32_e32 v206, 16, v194
	v_and_b32_e32 v207, 0xffff0000, v194
	v_lshlrev_b32_e32 v194, 16, v195
	v_and_b32_e32 v195, 0xffff0000, v195
	v_lshlrev_b32_e32 v208, 16, v196
	v_and_b32_e32 v209, 0xffff0000, v196
	v_lshlrev_b32_e32 v196, 16, v197
	v_and_b32_e32 v197, 0xffff0000, v197
	v_lshlrev_b32_e32 v212, 16, v200
	v_and_b32_e32 v213, 0xffff0000, v200
	v_lshlrev_b32_e32 v200, 16, v201
	v_and_b32_e32 v201, 0xffff0000, v201
	v_pk_add_f32 v[126:127], v[126:127], v[194:195]
	v_pk_add_f32 v[124:125], v[124:125], v[206:207]
	v_pk_add_f32 v[122:123], v[122:123], v[196:197]
	v_pk_add_f32 v[120:121], v[120:121], v[208:209]
	v_lshlrev_b32_e32 v210, 16, v198
	v_and_b32_e32 v211, 0xffff0000, v198
	v_lshlrev_b32_e32 v198, 16, v199
	v_and_b32_e32 v199, 0xffff0000, v199
	v_pk_add_f32 v[194:195], v[114:115], v[200:201]
	v_pk_add_f32 v[196:197], v[112:113], v[212:213]
	v_cvt_pk_bf16_f32 v112, v124, v125
	v_cvt_pk_bf16_f32 v113, v126, v127
	v_mul_f32_e32 v114, v125, v125
	v_mul_f32_e32 v115, v127, v127
	v_mul_f32_e32 v125, v121, v121
	v_mul_f32_e32 v127, v123, v123
	v_pk_add_f32 v[118:119], v[118:119], v[198:199]
	v_pk_add_f32 v[116:117], v[116:117], v[210:211]
	v_fmac_f32_e32 v114, v124, v124
	v_fmac_f32_e32 v115, v126, v126
	v_fmac_f32_e32 v125, v120, v120
	v_fmac_f32_e32 v127, v122, v122
	v_mul_f32_e32 v193, v117, v117
	v_mul_f32_e32 v198, v119, v119
	v_add_f32_e32 v114, v114, v115
	v_add_f32_e32 v115, v125, v127
	v_mul_f32_e32 v124, v197, v197
	v_mul_f32_e32 v125, v195, v195
	v_fmac_f32_e32 v193, v116, v116
	v_fmac_f32_e32 v198, v118, v118
	v_fmac_f32_e32 v124, v196, v196
	v_fmac_f32_e32 v125, v194, v194
	v_add_f32_e32 v114, v114, v115
	v_add_f32_e32 v115, v193, v198
	v_add_f32_e32 v124, v124, v125
	v_add_f32_e32 v115, v115, v124
	v_add_f32_e32 v124, v114, v115
	ds_bpermute_b32 v125, v192, v124
	v_cvt_pk_bf16_f32 v114, v120, v121
	v_cvt_pk_bf16_f32 v115, v122, v123
	global_store_dwordx4 v[204:205], v[112:115], off sc1
	s_waitcnt lgkmcnt(0)
	s_nop 0
	v_add_f32_e32 v112, v124, v125
	ds_bpermute_b32 v113, v179, v112
	v_cvt_pk_bf16_f32 v114, v116, v117
	v_cvt_pk_bf16_f32 v115, v118, v119
	v_cvt_pk_bf16_f32 v116, v196, v197
	v_cvt_pk_bf16_f32 v117, v194, v195
	global_store_dwordx4 v[204:205], v[114:117], off offset:64 sc1
	s_and_saveexec_b64 s[24:25], s[4:5]
	s_cbranch_execz .LBB0_886
	s_add_u32 s28, s51, s27
	s_addc_u32 s29, s52, s26
	s_waitcnt lgkmcnt(0)
	v_add_f32_e32 v114, v112, v113
	v_lshl_add_u64 v[112:113], v[170:171], 2, s[28:29]
	global_store_dword v[112:113], v114, off
.LBB0_886:
	s_or_b64 exec, exec, s[24:25]
	v_or_b32_e32 v112, 16, v178
	s_waitcnt lgkmcnt(0)
	v_ashrrev_i32_e32 v113, 31, v112
	v_lshlrev_b64 v[112:113], 11, v[112:113]
	v_lshl_add_u64 v[112:113], s[10:11], 0, v[112:113]
	v_lshl_add_u64 v[120:121], v[112:113], 0, v[174:175]
	global_load_dwordx4 v[116:119], v[120:121], off
	global_load_dwordx4 v[112:115], v[120:121], off offset:64
	v_lshlrev_b32_e32 v124, 16, v157
	v_and_b32_e32 v125, 0xffff0000, v157
	v_lshlrev_b32_e32 v122, 16, v156
	v_and_b32_e32 v123, 0xffff0000, v156
	v_pk_add_f32 v[110:111], v[110:111], v[124:125]
	v_lshlrev_b32_e32 v124, 16, v159
	v_and_b32_e32 v125, 0xffff0000, v159
	v_pk_add_f32 v[108:109], v[108:109], v[122:123]
	v_lshlrev_b32_e32 v122, 16, v158
	v_and_b32_e32 v123, 0xffff0000, v158
	v_pk_add_f32 v[106:107], v[106:107], v[124:125]
	v_lshlrev_b32_e32 v124, 16, v153
	v_and_b32_e32 v125, 0xffff0000, v153
	v_pk_add_f32 v[104:105], v[104:105], v[122:123]
	v_lshlrev_b32_e32 v122, 16, v152
	v_and_b32_e32 v123, 0xffff0000, v152
	v_pk_add_f32 v[102:103], v[102:103], v[124:125]
	v_lshlrev_b32_e32 v124, 16, v155
	v_and_b32_e32 v125, 0xffff0000, v155
	v_pk_add_f32 v[100:101], v[100:101], v[122:123]
	v_lshlrev_b32_e32 v122, 16, v154
	v_and_b32_e32 v123, 0xffff0000, v154
	v_pk_add_f32 v[124:125], v[98:99], v[124:125]
	v_mul_f32_e32 v98, v109, v109
	v_mul_f32_e32 v99, v111, v111
	v_pk_add_f32 v[122:123], v[96:97], v[122:123]
	v_lshl_add_u64 v[96:97], s[10:11], 0, v[182:183]
	v_fmac_f32_e32 v98, v108, v108
	v_fmac_f32_e32 v99, v110, v110
	v_lshl_add_u64 v[126:127], v[96:97], 0, v[174:175]
	v_cvt_pk_bf16_f32 v96, v108, v109
	v_add_f32_e32 v98, v98, v99
	v_mul_f32_e32 v99, v105, v105
	v_mul_f32_e32 v108, v107, v107
	v_fmac_f32_e32 v99, v104, v104
	v_fmac_f32_e32 v108, v106, v106
	v_add_f32_e32 v99, v99, v108
	v_add_f32_e32 v98, v98, v99
	v_mul_f32_e32 v99, v101, v101
	v_mul_f32_e32 v108, v103, v103
	v_fmac_f32_e32 v99, v100, v100
	v_fmac_f32_e32 v108, v102, v102
	v_add_f32_e32 v99, v99, v108
	v_mul_f32_e32 v108, v123, v123
	v_mul_f32_e32 v109, v125, v125
	v_fmac_f32_e32 v108, v122, v122
	v_fmac_f32_e32 v109, v124, v124
	v_add_f32_e32 v108, v108, v109
	v_add_f32_e32 v99, v99, v108
	v_add_f32_e32 v108, v98, v99
	ds_bpermute_b32 v109, v192, v108
	v_cvt_pk_bf16_f32 v97, v110, v111
	v_cvt_pk_bf16_f32 v98, v104, v105
	v_cvt_pk_bf16_f32 v99, v106, v107
	global_store_dwordx4 v[126:127], v[96:99], off sc1
	s_waitcnt lgkmcnt(0)
	s_nop 0
	v_add_f32_e32 v96, v108, v109
	ds_bpermute_b32 v97, v179, v96
	v_cvt_pk_bf16_f32 v98, v100, v101
	v_cvt_pk_bf16_f32 v99, v102, v103
	v_cvt_pk_bf16_f32 v100, v122, v123
	v_cvt_pk_bf16_f32 v101, v124, v125
	global_store_dwordx4 v[126:127], v[98:101], off offset:64 sc1
	s_and_saveexec_b64 s[24:25], s[4:5]
	s_mov_b32 s30, s72
	s_cbranch_execz .LBB0_888
	s_add_u32 s28, s51, s27
	s_addc_u32 s29, s52, s26
	s_waitcnt lgkmcnt(0)
	v_add_f32_e32 v98, v96, v97
	v_lshl_add_u64 v[96:97], v[170:171], 2, s[28:29]
	global_store_dword v[96:97], v98, off offset:64
.LBB0_888:
	s_or_b64 exec, exec, s[24:25]
	v_or_b32_e32 v96, 32, v178
	s_waitcnt lgkmcnt(0)
	v_ashrrev_i32_e32 v97, 31, v96
	v_lshlrev_b64 v[96:97], 11, v[96:97]
	v_lshl_add_u64 v[96:97], s[10:11], 0, v[96:97]
	v_lshl_add_u64 v[104:105], v[96:97], 0, v[174:175]
	global_load_dwordx4 v[100:103], v[104:105], off
	global_load_dwordx4 v[96:99], v[104:105], off offset:64
	v_lshlrev_b32_e32 v108, 16, v149
	v_and_b32_e32 v109, 0xffff0000, v149
	v_lshlrev_b32_e32 v106, 16, v148
	v_and_b32_e32 v107, 0xffff0000, v148
	v_pk_add_f32 v[94:95], v[94:95], v[108:109]
	v_lshlrev_b32_e32 v108, 16, v151
	v_and_b32_e32 v109, 0xffff0000, v151
	v_pk_add_f32 v[92:93], v[92:93], v[106:107]
	v_lshlrev_b32_e32 v106, 16, v150
	v_and_b32_e32 v107, 0xffff0000, v150
	v_pk_add_f32 v[90:91], v[90:91], v[108:109]
	v_lshlrev_b32_e32 v108, 16, v145
	v_and_b32_e32 v109, 0xffff0000, v145
	v_pk_add_f32 v[88:89], v[88:89], v[106:107]
	v_lshlrev_b32_e32 v106, 16, v144
	v_and_b32_e32 v107, 0xffff0000, v144
	v_pk_add_f32 v[86:87], v[86:87], v[108:109]
	v_lshlrev_b32_e32 v108, 16, v147
	v_and_b32_e32 v109, 0xffff0000, v147
	v_pk_add_f32 v[84:85], v[84:85], v[106:107]
	v_lshlrev_b32_e32 v106, 16, v146
	v_and_b32_e32 v107, 0xffff0000, v146
	v_pk_add_f32 v[108:109], v[82:83], v[108:109]
	v_mul_f32_e32 v82, v93, v93
	v_mul_f32_e32 v83, v95, v95
	v_pk_add_f32 v[106:107], v[80:81], v[106:107]
	v_lshl_add_u64 v[80:81], s[10:11], 0, v[180:181]
	v_fmac_f32_e32 v82, v92, v92
	v_fmac_f32_e32 v83, v94, v94
	v_lshl_add_u64 v[110:111], v[80:81], 0, v[174:175]
	v_cvt_pk_bf16_f32 v80, v92, v93
	v_add_f32_e32 v82, v82, v83
	v_mul_f32_e32 v83, v89, v89
	v_mul_f32_e32 v92, v91, v91
	v_fmac_f32_e32 v83, v88, v88
	v_fmac_f32_e32 v92, v90, v90
	v_add_f32_e32 v83, v83, v92
	v_add_f32_e32 v82, v82, v83
	v_mul_f32_e32 v83, v85, v85
	v_mul_f32_e32 v92, v87, v87
	v_fmac_f32_e32 v83, v84, v84
	v_fmac_f32_e32 v92, v86, v86
	v_add_f32_e32 v83, v83, v92
	v_mul_f32_e32 v92, v107, v107
	v_mul_f32_e32 v93, v109, v109
	v_fmac_f32_e32 v92, v106, v106
	v_fmac_f32_e32 v93, v108, v108
	v_add_f32_e32 v92, v92, v93
	v_add_f32_e32 v83, v83, v92
	v_add_f32_e32 v92, v82, v83
	ds_bpermute_b32 v93, v192, v92
	v_cvt_pk_bf16_f32 v81, v94, v95
	v_cvt_pk_bf16_f32 v82, v88, v89
	v_cvt_pk_bf16_f32 v83, v90, v91
	global_store_dwordx4 v[110:111], v[80:83], off sc1
	s_waitcnt lgkmcnt(0)
	s_nop 0
	v_add_f32_e32 v80, v92, v93
	ds_bpermute_b32 v81, v179, v80
	v_cvt_pk_bf16_f32 v82, v84, v85
	v_cvt_pk_bf16_f32 v83, v86, v87
	v_cvt_pk_bf16_f32 v84, v106, v107
	v_cvt_pk_bf16_f32 v85, v108, v109
	global_store_dwordx4 v[110:111], v[82:85], off offset:64 sc1
	s_and_saveexec_b64 s[24:25], s[4:5]
	s_cbranch_execz .LBB0_890
	s_add_u32 s28, s51, s27
	s_addc_u32 s29, s52, s26
	s_waitcnt lgkmcnt(0)
	v_add_f32_e32 v82, v80, v81
	v_lshl_add_u64 v[80:81], v[170:171], 2, s[28:29]
	global_store_dword v[80:81], v82, off offset:128
.LBB0_890:
	s_or_b64 exec, exec, s[24:25]
	v_or_b32_e32 v80, 48, v178
	s_waitcnt lgkmcnt(0)
	v_ashrrev_i32_e32 v81, 31, v80
	v_lshlrev_b64 v[80:81], 11, v[80:81]
	v_lshl_add_u64 v[80:81], s[10:11], 0, v[80:81]
	v_lshl_add_u64 v[88:89], v[80:81], 0, v[174:175]
	global_load_dwordx4 v[84:87], v[88:89], off
	global_load_dwordx4 v[80:83], v[88:89], off offset:64
	v_lshlrev_b32_e32 v92, 16, v141
	v_and_b32_e32 v93, 0xffff0000, v141
	v_lshlrev_b32_e32 v90, 16, v140
	v_and_b32_e32 v91, 0xffff0000, v140
	v_pk_add_f32 v[78:79], v[78:79], v[92:93]
	v_lshlrev_b32_e32 v92, 16, v143
	v_and_b32_e32 v93, 0xffff0000, v143
	v_pk_add_f32 v[76:77], v[76:77], v[90:91]
	v_lshlrev_b32_e32 v90, 16, v142
	v_and_b32_e32 v91, 0xffff0000, v142
	v_pk_add_f32 v[74:75], v[74:75], v[92:93]
	v_lshlrev_b32_e32 v92, 16, v137
	v_and_b32_e32 v93, 0xffff0000, v137
	v_pk_add_f32 v[72:73], v[72:73], v[90:91]
	v_lshlrev_b32_e32 v90, 16, v136
	v_and_b32_e32 v91, 0xffff0000, v136
	v_pk_add_f32 v[70:71], v[70:71], v[92:93]
	v_lshlrev_b32_e32 v92, 16, v139
	v_and_b32_e32 v93, 0xffff0000, v139
	v_pk_add_f32 v[68:69], v[68:69], v[90:91]
	v_lshlrev_b32_e32 v90, 16, v138
	v_and_b32_e32 v91, 0xffff0000, v138
	v_pk_add_f32 v[92:93], v[66:67], v[92:93]
	v_mul_f32_e32 v66, v77, v77
	v_mul_f32_e32 v67, v79, v79
	v_pk_add_f32 v[90:91], v[64:65], v[90:91]
	v_lshl_add_u64 v[64:65], s[10:11], 0, v[176:177]
	v_fmac_f32_e32 v66, v76, v76
	v_fmac_f32_e32 v67, v78, v78
	v_lshl_add_u64 v[94:95], v[64:65], 0, v[174:175]
	v_cvt_pk_bf16_f32 v64, v76, v77
	v_add_f32_e32 v66, v66, v67
	v_mul_f32_e32 v67, v73, v73
	v_mul_f32_e32 v76, v75, v75
	v_fmac_f32_e32 v67, v72, v72
	v_fmac_f32_e32 v76, v74, v74
	v_add_f32_e32 v67, v67, v76
	v_add_f32_e32 v66, v66, v67
	v_mul_f32_e32 v67, v69, v69
	v_mul_f32_e32 v76, v71, v71
	v_fmac_f32_e32 v67, v68, v68
	v_fmac_f32_e32 v76, v70, v70
	v_add_f32_e32 v67, v67, v76
	v_mul_f32_e32 v76, v91, v91
	v_mul_f32_e32 v77, v93, v93
	v_fmac_f32_e32 v76, v90, v90
	v_fmac_f32_e32 v77, v92, v92
	v_add_f32_e32 v76, v76, v77
	v_add_f32_e32 v67, v67, v76
	v_add_f32_e32 v76, v66, v67
	ds_bpermute_b32 v77, v192, v76
	v_cvt_pk_bf16_f32 v65, v78, v79
	v_cvt_pk_bf16_f32 v66, v72, v73
	v_cvt_pk_bf16_f32 v67, v74, v75
	global_store_dwordx4 v[94:95], v[64:67], off sc1
	s_waitcnt lgkmcnt(0)
	s_nop 0
	v_add_f32_e32 v64, v76, v77
	ds_bpermute_b32 v65, v179, v64
	v_cvt_pk_bf16_f32 v66, v68, v69
	v_cvt_pk_bf16_f32 v67, v70, v71
	v_cvt_pk_bf16_f32 v68, v90, v91
	v_cvt_pk_bf16_f32 v69, v92, v93
	global_store_dwordx4 v[94:95], v[66:69], off offset:64 sc1
	s_and_saveexec_b64 s[24:25], s[4:5]
	s_cbranch_execz .LBB0_892
	s_add_u32 s28, s51, s27
	s_addc_u32 s29, s52, s26
	s_waitcnt lgkmcnt(0)
	v_add_f32_e32 v66, v64, v65
	v_lshl_add_u64 v[64:65], v[170:171], 2, s[28:29]
	global_store_dword v[64:65], v66, off offset:192
.LBB0_892:
	s_or_b64 exec, exec, s[24:25]
	v_lshlrev_b32_e32 v66, 16, v133
	v_and_b32_e32 v67, 0xffff0000, v133
	v_pk_add_f32 v[62:63], v[62:63], v[66:67]
	v_lshlrev_b32_e32 v66, 16, v135
	v_and_b32_e32 v67, 0xffff0000, v135
	v_lshlrev_b32_e32 v64, 16, v132
	s_waitcnt lgkmcnt(0)
	v_and_b32_e32 v65, 0xffff0000, v132
	v_pk_add_f32 v[58:59], v[58:59], v[66:67]
	v_lshlrev_b32_e32 v66, 16, v129
	v_and_b32_e32 v67, 0xffff0000, v129
	v_pk_add_f32 v[60:61], v[60:61], v[64:65]
	v_lshlrev_b32_e32 v64, 16, v134
	v_and_b32_e32 v65, 0xffff0000, v134
	v_pk_add_f32 v[54:55], v[54:55], v[66:67]
	v_lshlrev_b32_e32 v66, 16, v131
	v_and_b32_e32 v67, 0xffff0000, v131
	v_pk_add_f32 v[56:57], v[56:57], v[64:65]
	v_lshlrev_b32_e32 v64, 16, v128
	v_and_b32_e32 v65, 0xffff0000, v128
	v_pk_add_f32 v[66:67], v[50:51], v[66:67]
	v_mul_f32_e32 v50, v61, v61
	v_mul_f32_e32 v51, v63, v63
	v_pk_add_f32 v[52:53], v[52:53], v[64:65]
	v_lshlrev_b32_e32 v64, 16, v130
	v_and_b32_e32 v65, 0xffff0000, v130
	v_fmac_f32_e32 v50, v60, v60
	v_fmac_f32_e32 v51, v62, v62
	v_pk_add_f32 v[64:65], v[48:49], v[64:65]
	v_cvt_pk_bf16_f32 v48, v60, v61
	v_add_f32_e32 v50, v50, v51
	v_mul_f32_e32 v51, v57, v57
	v_mul_f32_e32 v60, v59, v59
	v_fmac_f32_e32 v51, v56, v56
	v_fmac_f32_e32 v60, v58, v58
	v_add_f32_e32 v51, v51, v60
	v_add_f32_e32 v50, v50, v51
	v_mul_f32_e32 v51, v53, v53
	v_mul_f32_e32 v60, v55, v55
	v_fmac_f32_e32 v51, v52, v52
	v_fmac_f32_e32 v60, v54, v54
	v_add_f32_e32 v51, v51, v60
	v_mul_f32_e32 v60, v65, v65
	v_mul_f32_e32 v61, v67, v67
	v_fmac_f32_e32 v60, v64, v64
	v_fmac_f32_e32 v61, v66, v66
	v_add_f32_e32 v60, v60, v61
	v_add_f32_e32 v51, v51, v60
	v_add_f32_e32 v60, v50, v51
	ds_bpermute_b32 v61, v192, v60
	v_cvt_pk_bf16_f32 v49, v62, v63
	v_cvt_pk_bf16_f32 v50, v56, v57
	v_cvt_pk_bf16_f32 v51, v58, v59
	global_store_dwordx4 v[172:173], v[48:51], off sc1
	s_waitcnt lgkmcnt(0)
	s_nop 0
	v_add_f32_e32 v48, v60, v61
	ds_bpermute_b32 v49, v179, v48
	v_cvt_pk_bf16_f32 v50, v52, v53
	v_cvt_pk_bf16_f32 v51, v54, v55
	v_cvt_pk_bf16_f32 v52, v64, v65
	v_cvt_pk_bf16_f32 v53, v66, v67
	global_store_dwordx4 v[172:173], v[50:53], off offset:64 sc1
	s_and_saveexec_b64 s[24:25], s[4:5]
	s_cbranch_execz .LBB0_894
	s_add_u32 s28, s51, s27
	s_addc_u32 s29, s52, s26
	s_waitcnt lgkmcnt(0)
	v_add_f32_e32 v50, v48, v49
	v_lshl_add_u64 v[48:49], v[170:171], 2, s[28:29]
	global_store_dword v[48:49], v50, off offset:512
.LBB0_894:
	s_or_b64 exec, exec, s[24:25]
	s_waitcnt vmcnt(13)
	v_lshlrev_b32_e32 v50, 16, v117
	v_and_b32_e32 v51, 0xffff0000, v117
	v_pk_add_f32 v[46:47], v[46:47], v[50:51]
	v_lshlrev_b32_e32 v50, 16, v119
	v_and_b32_e32 v51, 0xffff0000, v119
	v_lshlrev_b32_e32 v48, 16, v116
	s_waitcnt lgkmcnt(0)
	v_and_b32_e32 v49, 0xffff0000, v116
	v_pk_add_f32 v[42:43], v[42:43], v[50:51]
	s_waitcnt vmcnt(12)
	v_lshlrev_b32_e32 v50, 16, v113
	v_and_b32_e32 v51, 0xffff0000, v113
	v_pk_add_f32 v[44:45], v[44:45], v[48:49]
	v_lshlrev_b32_e32 v48, 16, v118
	v_and_b32_e32 v49, 0xffff0000, v118
	v_pk_add_f32 v[38:39], v[38:39], v[50:51]
	v_lshlrev_b32_e32 v50, 16, v115
	v_and_b32_e32 v51, 0xffff0000, v115
	v_pk_add_f32 v[40:41], v[40:41], v[48:49]
	v_lshlrev_b32_e32 v48, 16, v112
	v_and_b32_e32 v49, 0xffff0000, v112
	v_pk_add_f32 v[50:51], v[34:35], v[50:51]
	v_mul_f32_e32 v34, v45, v45
	v_mul_f32_e32 v35, v47, v47
	v_pk_add_f32 v[36:37], v[36:37], v[48:49]
	v_lshlrev_b32_e32 v48, 16, v114
	v_and_b32_e32 v49, 0xffff0000, v114
	v_fmac_f32_e32 v34, v44, v44
	v_fmac_f32_e32 v35, v46, v46
	v_pk_add_f32 v[48:49], v[32:33], v[48:49]
	v_cvt_pk_bf16_f32 v32, v44, v45
	v_add_f32_e32 v34, v34, v35
	v_mul_f32_e32 v35, v41, v41
	v_mul_f32_e32 v44, v43, v43
	v_fmac_f32_e32 v35, v40, v40
	v_fmac_f32_e32 v44, v42, v42
	v_add_f32_e32 v35, v35, v44
	v_add_f32_e32 v34, v34, v35
	v_mul_f32_e32 v35, v37, v37
	v_mul_f32_e32 v44, v39, v39
	v_fmac_f32_e32 v35, v36, v36
	v_fmac_f32_e32 v44, v38, v38
	v_add_f32_e32 v35, v35, v44
	v_mul_f32_e32 v44, v49, v49
	v_mul_f32_e32 v45, v51, v51
	v_fmac_f32_e32 v44, v48, v48
	v_fmac_f32_e32 v45, v50, v50
	v_add_f32_e32 v44, v44, v45
	v_add_f32_e32 v35, v35, v44
	v_add_f32_e32 v44, v34, v35
	ds_bpermute_b32 v45, v192, v44
	v_cvt_pk_bf16_f32 v33, v46, v47
	v_cvt_pk_bf16_f32 v34, v40, v41
	v_cvt_pk_bf16_f32 v35, v42, v43
	global_store_dwordx4 v[120:121], v[32:35], off sc1
	s_waitcnt lgkmcnt(0)
	s_nop 0
	v_add_f32_e32 v32, v44, v45
	ds_bpermute_b32 v33, v179, v32
	v_cvt_pk_bf16_f32 v34, v36, v37
	v_cvt_pk_bf16_f32 v35, v38, v39
	v_cvt_pk_bf16_f32 v36, v48, v49
	v_cvt_pk_bf16_f32 v37, v50, v51
	global_store_dwordx4 v[120:121], v[34:37], off offset:64 sc1
	s_and_saveexec_b64 s[24:25], s[4:5]
	s_cbranch_execz .LBB0_896
	s_add_u32 s28, s51, s27
	s_addc_u32 s29, s52, s26
	s_waitcnt lgkmcnt(0)
	v_add_f32_e32 v34, v32, v33
	v_lshl_add_u64 v[32:33], v[170:171], 2, s[28:29]
	global_store_dword v[32:33], v34, off offset:576
.LBB0_896:
	s_or_b64 exec, exec, s[24:25]
	s_waitcnt vmcnt(11)
	v_lshlrev_b32_e32 v34, 16, v101
	v_and_b32_e32 v35, 0xffff0000, v101
	v_pk_add_f32 v[30:31], v[30:31], v[34:35]
	v_lshlrev_b32_e32 v34, 16, v103
	v_and_b32_e32 v35, 0xffff0000, v103
	v_lshlrev_b32_e32 v32, 16, v100
	s_waitcnt lgkmcnt(0)
	v_and_b32_e32 v33, 0xffff0000, v100
	v_pk_add_f32 v[26:27], v[26:27], v[34:35]
	s_waitcnt vmcnt(10)
	v_lshlrev_b32_e32 v34, 16, v97
	v_and_b32_e32 v35, 0xffff0000, v97
	v_pk_add_f32 v[28:29], v[28:29], v[32:33]
	v_lshlrev_b32_e32 v32, 16, v102
	v_and_b32_e32 v33, 0xffff0000, v102
	v_pk_add_f32 v[22:23], v[22:23], v[34:35]
	v_lshlrev_b32_e32 v34, 16, v99
	v_and_b32_e32 v35, 0xffff0000, v99
	v_pk_add_f32 v[24:25], v[24:25], v[32:33]
	v_lshlrev_b32_e32 v32, 16, v96
	v_and_b32_e32 v33, 0xffff0000, v96
	v_pk_add_f32 v[34:35], v[18:19], v[34:35]
	v_mul_f32_e32 v18, v29, v29
	v_mul_f32_e32 v19, v31, v31
	v_pk_add_f32 v[20:21], v[20:21], v[32:33]
	v_lshlrev_b32_e32 v32, 16, v98
	v_and_b32_e32 v33, 0xffff0000, v98
	v_fmac_f32_e32 v18, v28, v28
	v_fmac_f32_e32 v19, v30, v30
	v_pk_add_f32 v[32:33], v[16:17], v[32:33]
	v_cvt_pk_bf16_f32 v16, v28, v29
	v_add_f32_e32 v18, v18, v19
	v_mul_f32_e32 v19, v25, v25
	v_mul_f32_e32 v28, v27, v27
	v_fmac_f32_e32 v19, v24, v24
	v_fmac_f32_e32 v28, v26, v26
	v_add_f32_e32 v19, v19, v28
	v_add_f32_e32 v18, v18, v19
	v_mul_f32_e32 v19, v21, v21
	v_mul_f32_e32 v28, v23, v23
	v_fmac_f32_e32 v19, v20, v20
	v_fmac_f32_e32 v28, v22, v22
	v_add_f32_e32 v19, v19, v28
	v_mul_f32_e32 v28, v33, v33
	v_mul_f32_e32 v29, v35, v35
	v_fmac_f32_e32 v28, v32, v32
	v_fmac_f32_e32 v29, v34, v34
	v_add_f32_e32 v28, v28, v29
	v_add_f32_e32 v19, v19, v28
	v_add_f32_e32 v28, v18, v19
	ds_bpermute_b32 v29, v192, v28
	v_cvt_pk_bf16_f32 v17, v30, v31
	v_cvt_pk_bf16_f32 v18, v24, v25
	v_cvt_pk_bf16_f32 v19, v26, v27
	global_store_dwordx4 v[104:105], v[16:19], off sc1
	s_waitcnt lgkmcnt(0)
	s_nop 0
	v_add_f32_e32 v16, v28, v29
	ds_bpermute_b32 v17, v179, v16
	v_cvt_pk_bf16_f32 v18, v20, v21
	v_cvt_pk_bf16_f32 v19, v22, v23
	v_cvt_pk_bf16_f32 v20, v32, v33
	v_cvt_pk_bf16_f32 v21, v34, v35
	global_store_dwordx4 v[104:105], v[18:21], off offset:64 sc1
	s_and_saveexec_b64 s[24:25], s[4:5]
	s_cbranch_execz .LBB0_898
	s_add_u32 s28, s51, s27
	s_addc_u32 s29, s52, s26
	s_waitcnt lgkmcnt(0)
	v_add_f32_e32 v18, v16, v17
	v_lshl_add_u64 v[16:17], v[170:171], 2, s[28:29]
	global_store_dword v[16:17], v18, off offset:640
.LBB0_898:
	s_or_b64 exec, exec, s[24:25]
	s_waitcnt vmcnt(9)
	v_lshlrev_b32_e32 v18, 16, v85
	v_and_b32_e32 v19, 0xffff0000, v85
	v_pk_add_f32 v[14:15], v[14:15], v[18:19]
	v_lshlrev_b32_e32 v18, 16, v87
	v_and_b32_e32 v19, 0xffff0000, v87
	v_lshlrev_b32_e32 v16, 16, v84
	s_waitcnt lgkmcnt(0)
	v_and_b32_e32 v17, 0xffff0000, v84
	v_pk_add_f32 v[10:11], v[10:11], v[18:19]
	s_waitcnt vmcnt(8)
	v_lshlrev_b32_e32 v18, 16, v81
	v_and_b32_e32 v19, 0xffff0000, v81
	v_pk_add_f32 v[12:13], v[12:13], v[16:17]
	v_lshlrev_b32_e32 v16, 16, v86
	v_and_b32_e32 v17, 0xffff0000, v86
	v_pk_add_f32 v[6:7], v[6:7], v[18:19]
	v_lshlrev_b32_e32 v18, 16, v83
	v_and_b32_e32 v19, 0xffff0000, v83
	v_pk_add_f32 v[8:9], v[8:9], v[16:17]
	v_lshlrev_b32_e32 v16, 16, v80
	v_and_b32_e32 v17, 0xffff0000, v80
	v_pk_add_f32 v[18:19], v[2:3], v[18:19]
	v_mul_f32_e32 v2, v13, v13
	v_mul_f32_e32 v3, v15, v15
	v_pk_add_f32 v[4:5], v[4:5], v[16:17]
	v_lshlrev_b32_e32 v16, 16, v82
	v_and_b32_e32 v17, 0xffff0000, v82
	v_fmac_f32_e32 v2, v12, v12
	v_fmac_f32_e32 v3, v14, v14
	v_pk_add_f32 v[16:17], v[0:1], v[16:17]
	v_cvt_pk_bf16_f32 v0, v12, v13
	v_add_f32_e32 v2, v2, v3
	v_mul_f32_e32 v3, v9, v9
	v_mul_f32_e32 v12, v11, v11
	v_fmac_f32_e32 v3, v8, v8
	v_fmac_f32_e32 v12, v10, v10
	v_add_f32_e32 v3, v3, v12
	v_add_f32_e32 v2, v2, v3
	v_mul_f32_e32 v3, v5, v5
	v_mul_f32_e32 v12, v7, v7
	v_fmac_f32_e32 v3, v4, v4
	v_fmac_f32_e32 v12, v6, v6
	v_add_f32_e32 v3, v3, v12
	v_mul_f32_e32 v12, v17, v17
	v_mul_f32_e32 v13, v19, v19
	v_fmac_f32_e32 v12, v16, v16
	v_fmac_f32_e32 v13, v18, v18
	v_add_f32_e32 v12, v12, v13
	v_add_f32_e32 v3, v3, v12
	v_add_f32_e32 v12, v2, v3
	ds_bpermute_b32 v13, v192, v12
	v_cvt_pk_bf16_f32 v1, v14, v15
	v_cvt_pk_bf16_f32 v2, v8, v9
	v_cvt_pk_bf16_f32 v3, v10, v11
	global_store_dwordx4 v[88:89], v[0:3], off sc1
	s_waitcnt lgkmcnt(0)
	s_nop 0
	v_add_f32_e32 v0, v12, v13
	ds_bpermute_b32 v1, v179, v0
	v_cvt_pk_bf16_f32 v2, v4, v5
	v_cvt_pk_bf16_f32 v3, v6, v7
	v_cvt_pk_bf16_f32 v4, v16, v17
	v_cvt_pk_bf16_f32 v5, v18, v19
	global_store_dwordx4 v[88:89], v[2:5], off offset:64 sc1
	s_and_saveexec_b64 s[24:25], s[4:5]
	s_cbranch_execz .LBB0_877
	s_add_u32 s28, s51, s27
	s_addc_u32 s29, s52, s26
	s_waitcnt lgkmcnt(0)
	v_add_f32_e32 v2, v0, v1
	v_lshl_add_u64 v[0:1], v[170:171], 2, s[28:29]
	global_store_dword v[0:1], v2, off offset:704
	s_branch .LBB0_877

.LBB0_972:
	ds_read_b128 v[140:143], v146
	ds_read_b128 v[154:157], v146 offset:1024
	ds_read_b128 v[158:161], v146 offset:2048
	ds_read_b128 v[162:165], v146 offset:3072
	s_add_u32 s28, s26, 0xfffc0080
	s_addc_u32 s29, s27, -1
	s_cmp_eq_u32 s40, 12
	s_cselect_b32 s31, s25, s29
	s_cselect_b32 s30, s34, s28
	s_cselect_b32 s29, s36, s39
	s_cselect_b32 s28, s37, s38
	v_lshl_add_u64 v[198:199], s[26:27], 0, v[134:135]
	s_add_i32 m0, s45, 0xc000
	ds_read_b128 v[166:169], v147
	ds_read_b128 v[170:173], v147 offset:1024
	ds_read_b128 v[174:177], v147 offset:2048
	ds_read_b128 v[178:181], v147 offset:3072
	ds_read_b128 v[182:185], v147 offset:4096
	ds_read_b128 v[186:189], v147 offset:5120
	ds_read_b128 v[190:193], v147 offset:6144
	ds_read_b128 v[194:197], v147 offset:7168
	global_load_lds_dwordx4 v[198:199], off
	v_lshl_add_u64 v[198:199], s[26:27], 0, v[136:137]
	s_add_i32 m0, s45, 0xe000
	s_nop 0
	global_load_lds_dwordx4 v[198:199], off
	ds_read_b128 v[198:201], v148
	ds_read_b128 v[204:207], v148 offset:1024
	ds_read_b128 v[208:211], v148 offset:2048
	ds_read_b128 v[212:215], v148 offset:3072
	s_waitcnt lgkmcnt(0)
	s_waitcnt vmcnt(8)
	s_barrier
	s_setprio 1
	v_mfma_f32_16x16x32_bf16 v[124:127], v[140:143], v[166:169], v[124:127]
	v_mfma_f32_16x16x32_bf16 v[120:123], v[158:161], v[166:169], v[120:123]
	v_mfma_f32_16x16x32_bf16 v[108:111], v[140:143], v[174:177], v[108:111]
	v_mfma_f32_16x16x32_bf16 v[104:107], v[158:161], v[174:177], v[104:107]
	v_mfma_f32_16x16x32_bf16 v[92:95], v[140:143], v[182:185], v[92:95]
	v_mfma_f32_16x16x32_bf16 v[88:91], v[158:161], v[182:185], v[88:91]
	v_mfma_f32_16x16x32_bf16 v[76:79], v[140:143], v[190:193], v[76:79]
	v_mfma_f32_16x16x32_bf16 v[72:75], v[158:161], v[190:193], v[72:75]
	v_mfma_f32_16x16x32_bf16 v[124:127], v[154:157], v[170:173], v[124:127]
	v_mfma_f32_16x16x32_bf16 v[120:123], v[162:165], v[170:173], v[120:123]
	v_mfma_f32_16x16x32_bf16 v[108:111], v[154:157], v[178:181], v[108:111]
	v_mfma_f32_16x16x32_bf16 v[104:107], v[162:165], v[178:181], v[104:107]
	v_mfma_f32_16x16x32_bf16 v[92:95], v[154:157], v[186:189], v[92:95]
	v_mfma_f32_16x16x32_bf16 v[88:91], v[162:165], v[186:189], v[88:91]
	v_mfma_f32_16x16x32_bf16 v[76:79], v[154:157], v[194:197], v[76:79]
	v_mfma_f32_16x16x32_bf16 v[72:75], v[162:165], v[194:197], v[72:75]
	v_mfma_f32_16x16x32_bf16 v[116:119], v[198:201], v[166:169], v[116:119]
	v_mfma_f32_16x16x32_bf16 v[112:115], v[208:211], v[166:169], v[112:115]
	v_mfma_f32_16x16x32_bf16 v[100:103], v[198:201], v[174:177], v[100:103]
	v_mfma_f32_16x16x32_bf16 v[96:99], v[208:211], v[174:177], v[96:99]
	v_mfma_f32_16x16x32_bf16 v[84:87], v[198:201], v[182:185], v[84:87]
	v_mfma_f32_16x16x32_bf16 v[80:83], v[208:211], v[182:185], v[80:83]
	v_mfma_f32_16x16x32_bf16 v[68:71], v[198:201], v[190:193], v[68:71]
	v_mfma_f32_16x16x32_bf16 v[64:67], v[208:211], v[190:193], v[64:67]
	v_mfma_f32_16x16x32_bf16 v[116:119], v[204:207], v[170:173], v[116:119]
	v_mfma_f32_16x16x32_bf16 v[112:115], v[212:215], v[170:173], v[112:115]
	v_mfma_f32_16x16x32_bf16 v[100:103], v[204:207], v[178:181], v[100:103]
	v_mfma_f32_16x16x32_bf16 v[96:99], v[212:215], v[178:181], v[96:99]
	v_mfma_f32_16x16x32_bf16 v[84:87], v[204:207], v[186:189], v[84:87]
	v_mfma_f32_16x16x32_bf16 v[80:83], v[212:215], v[186:189], v[80:83]
	v_mfma_f32_16x16x32_bf16 v[68:71], v[204:207], v[194:197], v[68:71]
	v_mfma_f32_16x16x32_bf16 v[64:67], v[212:215], v[194:197], v[64:67]
	s_setprio 0
	s_barrier
	ds_read_b128 v[166:169], v147 offset:16384
	ds_read_b128 v[170:173], v147 offset:17408
	ds_read_b128 v[174:177], v147 offset:18432
	ds_read_b128 v[178:181], v147 offset:19456
	ds_read_b128 v[182:185], v147 offset:20480
	ds_read_b128 v[186:189], v147 offset:21504
	ds_read_b128 v[190:193], v147 offset:22528
	ds_read_b128 v[194:197], v147 offset:23552
	s_mov_b32 m0, s43
	v_lshl_add_u64 v[216:217], s[28:29], 0, v[128:129]
	global_load_lds_dwordx4 v[216:217], off
	v_lshl_add_u64 v[218:219], s[28:29], 0, v[130:131]
	s_mov_b32 m0, s44
	s_nop 0
	global_load_lds_dwordx4 v[218:219], off
	s_mov_b32 m0, s45
	v_lshl_add_u64 v[220:221], s[30:31], 0, v[128:129]
	global_load_lds_dwordx4 v[220:221], off
	v_lshl_add_u64 v[222:223], s[30:31], 0, v[130:131]
	s_mov_b32 m0, s46
	s_nop 0
	global_load_lds_dwordx4 v[222:223], off
	s_add_u32 s70, s28, 0x40000
	s_addc_u32 s71, s29, 0
	s_mov_b32 m0, s47
	v_lshl_add_u64 v[248:249], s[70:71], 0, v[128:129]
	global_load_lds_dwordx4 v[248:249], off
	v_lshl_add_u64 v[248:249], s[70:71], 0, v[130:131]
	s_mov_b32 m0, s48
	s_nop 0
	global_load_lds_dwordx4 v[248:249], off
	s_waitcnt lgkmcnt(0)
	s_waitcnt vmcnt(8)
	s_barrier
	s_setprio 1
	v_mfma_f32_16x16x32_bf16 v[60:63], v[140:143], v[166:169], v[60:63]
	v_mfma_f32_16x16x32_bf16 v[56:59], v[158:161], v[166:169], v[56:59]
	v_mfma_f32_16x16x32_bf16 v[44:47], v[140:143], v[174:177], v[44:47]
	v_mfma_f32_16x16x32_bf16 v[40:43], v[158:161], v[174:177], v[40:43]
	v_mfma_f32_16x16x32_bf16 v[28:31], v[140:143], v[182:185], v[28:31]
	v_mfma_f32_16x16x32_bf16 v[24:27], v[158:161], v[182:185], v[24:27]
	v_mfma_f32_16x16x32_bf16 v[12:15], v[140:143], v[190:193], v[12:15]
	v_mfma_f32_16x16x32_bf16 v[8:11], v[158:161], v[190:193], v[8:11]
	v_mfma_f32_16x16x32_bf16 v[60:63], v[154:157], v[170:173], v[60:63]
	v_mfma_f32_16x16x32_bf16 v[56:59], v[162:165], v[170:173], v[56:59]
	v_mfma_f32_16x16x32_bf16 v[44:47], v[154:157], v[178:181], v[44:47]
	v_mfma_f32_16x16x32_bf16 v[40:43], v[162:165], v[178:181], v[40:43]
	v_mfma_f32_16x16x32_bf16 v[28:31], v[154:157], v[186:189], v[28:31]
	v_mfma_f32_16x16x32_bf16 v[24:27], v[162:165], v[186:189], v[24:27]
	v_mfma_f32_16x16x32_bf16 v[12:15], v[154:157], v[194:197], v[12:15]
	v_mfma_f32_16x16x32_bf16 v[8:11], v[162:165], v[194:197], v[8:11]
	v_mfma_f32_16x16x32_bf16 v[52:55], v[198:201], v[166:169], v[52:55]
	v_mfma_f32_16x16x32_bf16 v[48:51], v[208:211], v[166:169], v[48:51]
	v_mfma_f32_16x16x32_bf16 v[36:39], v[198:201], v[174:177], v[36:39]
	v_mfma_f32_16x16x32_bf16 v[32:35], v[208:211], v[174:177], v[32:35]
	v_mfma_f32_16x16x32_bf16 v[20:23], v[198:201], v[182:185], v[20:23]
	v_mfma_f32_16x16x32_bf16 v[16:19], v[208:211], v[182:185], v[16:19]
	v_mfma_f32_16x16x32_bf16 v[4:7], v[198:201], v[190:193], v[4:7]
	v_mfma_f32_16x16x32_bf16 v[0:3], v[208:211], v[190:193], v[0:3]
	v_mfma_f32_16x16x32_bf16 v[52:55], v[204:207], v[170:173], v[52:55]
	v_mfma_f32_16x16x32_bf16 v[48:51], v[212:215], v[170:173], v[48:51]
	v_mfma_f32_16x16x32_bf16 v[36:39], v[204:207], v[178:181], v[36:39]
	v_mfma_f32_16x16x32_bf16 v[32:35], v[212:215], v[178:181], v[32:35]
	v_mfma_f32_16x16x32_bf16 v[20:23], v[204:207], v[186:189], v[20:23]
	v_mfma_f32_16x16x32_bf16 v[16:19], v[212:215], v[186:189], v[16:19]
	v_mfma_f32_16x16x32_bf16 v[4:7], v[204:207], v[194:197], v[4:7]
	v_mfma_f32_16x16x32_bf16 v[0:3], v[212:215], v[194:197], v[0:3]
	s_setprio 0
	s_barrier
	ds_read_b128 v[140:143], v149
	ds_read_b128 v[154:157], v149 offset:1024
	ds_read_b128 v[158:161], v149 offset:2048
	ds_read_b128 v[162:165], v149 offset:3072
	s_add_u32 s30, s30, 0x40000
	s_addc_u32 s31, s31, 0
	s_mov_b32 m0, s49
	v_lshl_add_u64 v[198:199], s[30:31], 0, v[128:129]
	ds_read_b128 v[166:169], v147 offset:32768
	ds_read_b128 v[170:173], v147 offset:33792
	ds_read_b128 v[174:177], v147 offset:34816
	ds_read_b128 v[178:181], v147 offset:35840
	ds_read_b128 v[182:185], v147 offset:36864
	ds_read_b128 v[186:189], v147 offset:37888
	ds_read_b128 v[190:193], v147 offset:38912
	ds_read_b128 v[194:197], v147 offset:39936
	global_load_lds_dwordx4 v[198:199], off
	v_lshl_add_u64 v[198:199], s[30:31], 0, v[130:131]
	s_mov_b32 m0, s50
	s_nop 0
	global_load_lds_dwordx4 v[198:199], off
	ds_read_b128 v[198:201], v150
	ds_read_b128 v[204:207], v150 offset:1024
	ds_read_b128 v[208:211], v150 offset:2048
	ds_read_b128 v[212:215], v150 offset:3072
	s_waitcnt lgkmcnt(0)
	s_waitcnt vmcnt(8)
	s_barrier
	s_setprio 1
	v_mfma_f32_16x16x32_bf16 v[124:127], v[140:143], v[166:169], v[124:127]
	v_mfma_f32_16x16x32_bf16 v[120:123], v[158:161], v[166:169], v[120:123]
	v_mfma_f32_16x16x32_bf16 v[108:111], v[140:143], v[174:177], v[108:111]
	v_mfma_f32_16x16x32_bf16 v[104:107], v[158:161], v[174:177], v[104:107]
	v_mfma_f32_16x16x32_bf16 v[92:95], v[140:143], v[182:185], v[92:95]
	v_mfma_f32_16x16x32_bf16 v[88:91], v[158:161], v[182:185], v[88:91]
	v_mfma_f32_16x16x32_bf16 v[76:79], v[140:143], v[190:193], v[76:79]
	v_mfma_f32_16x16x32_bf16 v[72:75], v[158:161], v[190:193], v[72:75]
	v_mfma_f32_16x16x32_bf16 v[124:127], v[154:157], v[170:173], v[124:127]
	v_mfma_f32_16x16x32_bf16 v[120:123], v[162:165], v[170:173], v[120:123]
	v_mfma_f32_16x16x32_bf16 v[108:111], v[154:157], v[178:181], v[108:111]
	v_mfma_f32_16x16x32_bf16 v[104:107], v[162:165], v[178:181], v[104:107]
	v_mfma_f32_16x16x32_bf16 v[92:95], v[154:157], v[186:189], v[92:95]
	v_mfma_f32_16x16x32_bf16 v[88:91], v[162:165], v[186:189], v[88:91]
	v_mfma_f32_16x16x32_bf16 v[76:79], v[154:157], v[194:197], v[76:79]
	v_mfma_f32_16x16x32_bf16 v[72:75], v[162:165], v[194:197], v[72:75]
	v_mfma_f32_16x16x32_bf16 v[116:119], v[198:201], v[166:169], v[116:119]
	v_mfma_f32_16x16x32_bf16 v[112:115], v[208:211], v[166:169], v[112:115]
	v_mfma_f32_16x16x32_bf16 v[100:103], v[198:201], v[174:177], v[100:103]
	v_mfma_f32_16x16x32_bf16 v[96:99], v[208:211], v[174:177], v[96:99]
	v_mfma_f32_16x16x32_bf16 v[84:87], v[198:201], v[182:185], v[84:87]
	v_mfma_f32_16x16x32_bf16 v[80:83], v[208:211], v[182:185], v[80:83]
	v_mfma_f32_16x16x32_bf16 v[68:71], v[198:201], v[190:193], v[68:71]
	v_mfma_f32_16x16x32_bf16 v[64:67], v[208:211], v[190:193], v[64:67]
	v_mfma_f32_16x16x32_bf16 v[116:119], v[204:207], v[170:173], v[116:119]
	v_mfma_f32_16x16x32_bf16 v[112:115], v[212:215], v[170:173], v[112:115]
	v_mfma_f32_16x16x32_bf16 v[100:103], v[204:207], v[178:181], v[100:103]
	v_mfma_f32_16x16x32_bf16 v[96:99], v[212:215], v[178:181], v[96:99]
	v_mfma_f32_16x16x32_bf16 v[84:87], v[204:207], v[186:189], v[84:87]
	v_mfma_f32_16x16x32_bf16 v[80:83], v[212:215], v[186:189], v[80:83]
	v_mfma_f32_16x16x32_bf16 v[68:71], v[204:207], v[194:197], v[68:71]
	v_mfma_f32_16x16x32_bf16 v[64:67], v[212:215], v[194:197], v[64:67]
	s_setprio 0
	s_barrier
	ds_read_b128 v[166:169], v147 offset:49152
	ds_read_b128 v[170:173], v147 offset:50176
	ds_read_b128 v[174:177], v147 offset:51200
	ds_read_b128 v[178:181], v147 offset:52224
	ds_read_b128 v[182:185], v147 offset:53248
	ds_read_b128 v[186:189], v147 offset:54272
	ds_read_b128 v[190:193], v147 offset:55296
	ds_read_b128 v[194:197], v147 offset:56320
	s_mov_b32 m0, s54
	v_lshl_add_u64 v[216:217], v[216:217], 0, s[12:13]
	global_load_lds_dwordx4 v[216:217], off
	v_lshl_add_u64 v[216:217], v[218:219], 0, s[12:13]
	s_mov_b32 m0, s55
	s_nop 0
	global_load_lds_dwordx4 v[216:217], off
	s_mov_b32 m0, s56
	v_lshl_add_u64 v[216:217], v[220:221], 0, s[12:13]
	global_load_lds_dwordx4 v[216:217], off
	v_lshl_add_u64 v[216:217], v[222:223], 0, s[12:13]
	s_mov_b32 m0, s57
	s_nop 0
	global_load_lds_dwordx4 v[216:217], off
	s_add_u32 s28, s28, 0x40080
	s_addc_u32 s29, s29, 0
	s_mov_b32 m0, s58
	v_lshl_add_u64 v[248:249], s[28:29], 0, v[128:129]
	global_load_lds_dwordx4 v[248:249], off
	v_lshl_add_u64 v[248:249], s[28:29], 0, v[130:131]
	s_mov_b32 m0, s59
	s_nop 0
	global_load_lds_dwordx4 v[248:249], off
	s_waitcnt lgkmcnt(0)
	s_waitcnt vmcnt(8)
	s_barrier
	s_setprio 1
	v_mfma_f32_16x16x32_bf16 v[60:63], v[140:143], v[166:169], v[60:63]
	v_mfma_f32_16x16x32_bf16 v[56:59], v[158:161], v[166:169], v[56:59]
	v_mfma_f32_16x16x32_bf16 v[44:47], v[140:143], v[174:177], v[44:47]
	v_mfma_f32_16x16x32_bf16 v[40:43], v[158:161], v[174:177], v[40:43]
	v_mfma_f32_16x16x32_bf16 v[28:31], v[140:143], v[182:185], v[28:31]
	v_mfma_f32_16x16x32_bf16 v[24:27], v[158:161], v[182:185], v[24:27]
	v_mfma_f32_16x16x32_bf16 v[12:15], v[140:143], v[190:193], v[12:15]
	v_mfma_f32_16x16x32_bf16 v[8:11], v[158:161], v[190:193], v[8:11]
	v_mfma_f32_16x16x32_bf16 v[60:63], v[154:157], v[170:173], v[60:63]
	v_mfma_f32_16x16x32_bf16 v[56:59], v[162:165], v[170:173], v[56:59]
	v_mfma_f32_16x16x32_bf16 v[44:47], v[154:157], v[178:181], v[44:47]
	v_mfma_f32_16x16x32_bf16 v[40:43], v[162:165], v[178:181], v[40:43]
	v_mfma_f32_16x16x32_bf16 v[28:31], v[154:157], v[186:189], v[28:31]
	v_mfma_f32_16x16x32_bf16 v[24:27], v[162:165], v[186:189], v[24:27]
	v_mfma_f32_16x16x32_bf16 v[12:15], v[154:157], v[194:197], v[12:15]
	v_mfma_f32_16x16x32_bf16 v[8:11], v[162:165], v[194:197], v[8:11]
	v_mfma_f32_16x16x32_bf16 v[52:55], v[198:201], v[166:169], v[52:55]
	v_mfma_f32_16x16x32_bf16 v[48:51], v[208:211], v[166:169], v[48:51]
	v_mfma_f32_16x16x32_bf16 v[36:39], v[198:201], v[174:177], v[36:39]
	v_mfma_f32_16x16x32_bf16 v[32:35], v[208:211], v[174:177], v[32:35]
	v_mfma_f32_16x16x32_bf16 v[20:23], v[198:201], v[182:185], v[20:23]
	v_mfma_f32_16x16x32_bf16 v[16:19], v[208:211], v[182:185], v[16:19]
	v_mfma_f32_16x16x32_bf16 v[4:7], v[198:201], v[190:193], v[4:7]
	v_mfma_f32_16x16x32_bf16 v[0:3], v[208:211], v[190:193], v[0:3]
	v_mfma_f32_16x16x32_bf16 v[52:55], v[204:207], v[170:173], v[52:55]
	v_mfma_f32_16x16x32_bf16 v[48:51], v[212:215], v[170:173], v[48:51]
	v_mfma_f32_16x16x32_bf16 v[36:39], v[204:207], v[178:181], v[36:39]
	v_mfma_f32_16x16x32_bf16 v[32:35], v[212:215], v[178:181], v[32:35]
	v_mfma_f32_16x16x32_bf16 v[20:23], v[204:207], v[186:189], v[20:23]
	v_mfma_f32_16x16x32_bf16 v[16:19], v[212:215], v[186:189], v[16:19]
	v_mfma_f32_16x16x32_bf16 v[4:7], v[204:207], v[194:197], v[4:7]
	v_mfma_f32_16x16x32_bf16 v[0:3], v[212:215], v[194:197], v[0:3]
	s_setprio 0
	s_add_i32 s40, s40, 2
	s_add_u32 s26, s26, 0x100
	s_addc_u32 s27, s27, 0
	s_add_u32 s38, s38, 0x100
	s_addc_u32 s39, s39, 0
	s_cmp_gt_u32 s40, 13
	s_barrier
	s_cbranch_scc0 .LBB0_972
	v_lshl_add_u32 v140, s24, 8, v144
	v_ashrrev_i32_e32 v141, 31, v140
	v_lshl_add_u64 v[142:143], v[140:141], 2, v[132:133]
	v_add_co_u32_e32 v154, vcc, s60, v142
	v_xor_b32_e32 v153, 16, v151
	s_nop 0
	v_addc_co_u32_e32 v155, vcc, 0, v143, vcc
	v_add_co_u32_e32 v156, vcc, s65, v142
	s_lshl_b32 s24, s68, 2
	s_nop 0
	v_addc_co_u32_e32 v157, vcc, 0, v143, vcc
	v_add_co_u32_e32 v158, vcc, s66, v142
	s_or_b32 s27, s24, s53
	s_nop 0
	v_addc_co_u32_e32 v159, vcc, 0, v143, vcc
	global_load_dword v160, v[142:143], off
	global_load_dword v162, v[142:143], off offset:64
	global_load_dword v163, v[142:143], off offset:128
	global_load_dword v164, v[142:143], off offset:192
	global_load_dword v165, v[142:143], off offset:512
	global_load_dword v166, v[142:143], off offset:576
	global_load_dword v167, v[142:143], off offset:640
	global_load_dword v168, v[142:143], off offset:704
	s_nop 0
	global_load_dword v142, v[154:155], off
	global_load_dword v169, v[154:155], off offset:64
	global_load_dword v170, v[154:155], off offset:128
	global_load_dword v171, v[154:155], off offset:192
	global_load_dword v172, v[154:155], off offset:512
	global_load_dword v173, v[154:155], off offset:576
	global_load_dword v174, v[154:155], off offset:640
	s_nop 0
	global_load_dword v155, v[154:155], off offset:704
	s_nop 0
	global_load_dword v161, v[156:157], off
	global_load_dword v175, v[156:157], off offset:64
	global_load_dword v176, v[156:157], off offset:128
	global_load_dword v177, v[156:157], off offset:192
	global_load_dword v178, v[156:157], off offset:512
	global_load_dword v179, v[156:157], off offset:576
	global_load_dword v180, v[156:157], off offset:640
	s_nop 0
	global_load_dword v156, v[156:157], off offset:704
	s_nop 0
	global_load_dword v143, v[158:159], off
	global_load_dword v157, v[158:159], off offset:64
	global_load_dword v181, v[158:159], off offset:128
	global_load_dword v182, v[158:159], off offset:192
	global_load_dword v183, v[158:159], off offset:512
	global_load_dword v184, v[158:159], off offset:576
	global_load_dword v185, v[158:159], off offset:640
	s_nop 0
	global_load_dword v158, v[158:159], off offset:704
	v_and_b32_e32 v154, 64, v151
	v_add_u32_e32 v154, 64, v154
	v_xor_b32_e32 v159, 32, v151
	v_cmp_lt_i32_e32 vcc, v153, v154
	s_mul_hi_i32 s26, s27, 0x21000
	s_mul_i32 s27, s27, 0x21000
	v_cndmask_b32_e32 v153, v151, v153, vcc
	v_cmp_lt_i32_e32 vcc, v159, v154
	v_lshlrev_b32_e32 v154, 2, v153
	s_waitcnt vmcnt(0)
	v_add_f32_e32 v155, v168, v155
	v_cndmask_b32_e32 v159, v151, v159, vcc
	v_lshlrev_b32_e32 v153, 2, v159
	v_add_f32_e32 v159, v162, v169
	v_add_f32_e32 v162, v163, v170
	v_add_f32_e32 v163, v164, v171
	v_add_f32_e32 v164, v165, v172
	v_add_f32_e32 v165, v166, v173
	v_add_f32_e32 v166, v167, v174
	v_pk_add_f32 v[142:143], v[160:161], v[142:143]
	v_add_f32_e32 v157, v175, v157
	v_add_f32_e32 v142, v142, v143
	v_add_f32_e32 v161, v177, v182
	v_add_f32_e32 v143, v159, v157
	v_add_f32_e32 v167, v178, v183
	v_add_f32_e32 v159, v164, v167
	v_add_f32_e32 v156, v156, v158
	v_add_f32_e32 v155, v155, v156
	ds_bpermute_b32 v156, v154, v142
	v_add_f32_e32 v158, v163, v161
	ds_bpermute_b32 v161, v154, v143
	v_add_f32_e32 v160, v176, v181
	v_add_f32_e32 v168, v179, v184
	s_waitcnt lgkmcnt(0)
	v_add_f32_e32 v142, v142, v156
	v_add_f32_e32 v169, v180, v185
	v_add_f32_e32 v167, v143, v161
	ds_bpermute_b32 v143, v153, v142
	v_add_f32_e32 v157, v162, v160
	v_add_f32_e32 v160, v165, v168
	v_add_f32_e32 v169, v166, v169
	ds_bpermute_b32 v171, v154, v160
	s_waitcnt lgkmcnt(1)
	v_add_f32_e32 v142, v142, v143
	v_fmamk_f32 v142, v142, 0x3a800000, v152
	ds_bpermute_b32 v162, v154, v157
	ds_bpermute_b32 v164, v154, v159
	ds_bpermute_b32 v172, v154, v169
	v_rsq_f32_e32 v170, v142
	ds_bpermute_b32 v142, v154, v155
	s_waitcnt lgkmcnt(3)
	v_add_f32_e32 v165, v157, v162
	s_waitcnt lgkmcnt(2)
	v_add_f32_e32 v161, v159, v164
	v_pk_mul_f32 v[126:127], v[126:127], v[170:171] op_sel_hi:[1,0]
	v_pk_mul_f32 v[124:125], v[124:125], v[170:171] op_sel_hi:[1,0]
	v_add_f32_e32 v159, v160, v171
	s_waitcnt lgkmcnt(1)
	v_add_f32_e32 v157, v169, v172
	s_waitcnt lgkmcnt(0)
	v_add_f32_e32 v155, v155, v142
	v_lshl_or_b32 v142, s68, 8, v145
	v_pk_mul_f32 v[122:123], v[122:123], v[170:171] op_sel_hi:[1,0]
	v_pk_mul_f32 v[120:121], v[120:121], v[170:171] op_sel_hi:[1,0]
	v_pk_mul_f32 v[118:119], v[118:119], v[170:171] op_sel_hi:[1,0]
	v_pk_mul_f32 v[116:117], v[116:117], v[170:171] op_sel_hi:[1,0]
	v_pk_mul_f32 v[172:173], v[114:115], v[170:171] op_sel_hi:[1,0]
	v_pk_mul_f32 v[170:171], v[112:113], v[170:171] op_sel_hi:[1,0]
	v_lshlrev_b64 v[112:113], 10, v[140:141]
	v_mul_f32_e32 v114, v125, v125
	v_mul_f32_e32 v115, v127, v127
	v_ashrrev_i32_e32 v143, 31, v142
	v_lshl_add_u64 v[112:113], s[10:11], 0, v[112:113]
	v_fmac_f32_e32 v114, v124, v124
	v_fmac_f32_e32 v115, v126, v126
	v_lshl_add_u64 v[174:175], v[142:143], 1, v[112:113]
	v_cvt_pk_bf16_f32 v112, v124, v125
	v_add_f32_e32 v114, v114, v115
	v_mul_f32_e32 v115, v121, v121
	v_mul_f32_e32 v124, v123, v123
	v_fmac_f32_e32 v115, v120, v120
	v_fmac_f32_e32 v124, v122, v122
	v_add_f32_e32 v115, v115, v124
	v_add_f32_e32 v114, v114, v115
	v_mul_f32_e32 v115, v117, v117
	v_mul_f32_e32 v124, v119, v119
	v_fmac_f32_e32 v115, v116, v116
	v_fmac_f32_e32 v124, v118, v118
	v_add_f32_e32 v115, v115, v124
	v_mul_f32_e32 v124, v171, v171
	v_mul_f32_e32 v125, v173, v173
	v_fmac_f32_e32 v124, v170, v170
	v_fmac_f32_e32 v125, v172, v172
	v_add_f32_e32 v124, v124, v125
	v_add_f32_e32 v115, v115, v124
	v_add_f32_e32 v124, v114, v115
	ds_bpermute_b32 v163, v154, v158
	ds_bpermute_b32 v125, v154, v124
	v_cvt_pk_bf16_f32 v113, v126, v127
	v_cvt_pk_bf16_f32 v114, v120, v121
	v_cvt_pk_bf16_f32 v115, v122, v123
	s_waitcnt lgkmcnt(1)
	v_add_f32_e32 v163, v158, v163
	global_store_dwordx4 v[174:175], v[112:115], off sc1
	ds_bpermute_b32 v168, v153, v167
	ds_bpermute_b32 v166, v153, v165
	s_waitcnt lgkmcnt(2)
	v_add_f32_e32 v112, v124, v125
	ds_bpermute_b32 v164, v153, v163
	ds_bpermute_b32 v162, v153, v161
	ds_bpermute_b32 v160, v153, v159
	ds_bpermute_b32 v158, v153, v157
	ds_bpermute_b32 v156, v153, v155
	ds_bpermute_b32 v113, v153, v112
	v_cvt_pk_bf16_f32 v114, v116, v117
	v_cvt_pk_bf16_f32 v115, v118, v119
	v_cvt_pk_bf16_f32 v116, v170, v171
	v_cvt_pk_bf16_f32 v117, v172, v173
	global_store_dwordx4 v[174:175], v[114:117], off offset:64 sc1
	s_and_saveexec_b64 s[24:25], s[4:5]
	s_cbranch_execz .LBB0_975
	s_add_u32 s28, s51, s27
	s_addc_u32 s29, s52, s26
	v_lshl_add_u64 v[114:115], v[140:141], 2, s[28:29]
	s_waitcnt lgkmcnt(0)
	v_add_f32_e32 v112, v112, v113
	global_store_dword v[114:115], v112, off
.LBB0_975:
	s_or_b64 exec, exec, s[24:25]
	s_waitcnt lgkmcnt(7)
	v_add_f32_e32 v112, v167, v168
	v_fmamk_f32 v112, v112, 0x3a800000, v152
	v_rsq_f32_e32 v112, v112
	v_or_b32_e32 v114, 16, v140
	v_ashrrev_i32_e32 v115, 31, v114
	s_waitcnt lgkmcnt(0)
	v_pk_mul_f32 v[110:111], v[110:111], v[112:113] op_sel_hi:[1,0]
	v_pk_mul_f32 v[108:109], v[108:109], v[112:113] op_sel_hi:[1,0]
	v_pk_mul_f32 v[106:107], v[106:107], v[112:113] op_sel_hi:[1,0]
	v_pk_mul_f32 v[104:105], v[104:105], v[112:113] op_sel_hi:[1,0]
	v_pk_mul_f32 v[102:103], v[102:103], v[112:113] op_sel_hi:[1,0]
	v_pk_mul_f32 v[100:101], v[100:101], v[112:113] op_sel_hi:[1,0]
	v_pk_mul_f32 v[116:117], v[98:99], v[112:113] op_sel_hi:[1,0]
	v_pk_mul_f32 v[112:113], v[96:97], v[112:113] op_sel_hi:[1,0]
	v_lshlrev_b64 v[96:97], 10, v[114:115]
	v_mul_f32_e32 v98, v109, v109
	v_mul_f32_e32 v99, v111, v111
	v_lshl_add_u64 v[96:97], s[10:11], 0, v[96:97]
	v_fmac_f32_e32 v98, v108, v108
	v_fmac_f32_e32 v99, v110, v110
	v_lshl_add_u64 v[114:115], v[142:143], 1, v[96:97]
	v_cvt_pk_bf16_f32 v96, v108, v109
	v_add_f32_e32 v98, v98, v99
	v_mul_f32_e32 v99, v105, v105
	v_mul_f32_e32 v108, v107, v107
	v_fmac_f32_e32 v99, v104, v104
	v_fmac_f32_e32 v108, v106, v106
	v_add_f32_e32 v99, v99, v108
	v_add_f32_e32 v98, v98, v99
	v_mul_f32_e32 v99, v101, v101
	v_mul_f32_e32 v108, v103, v103
	v_fmac_f32_e32 v99, v100, v100
	v_fmac_f32_e32 v108, v102, v102
	v_add_f32_e32 v99, v99, v108
	v_mul_f32_e32 v108, v113, v113
	v_mul_f32_e32 v109, v117, v117
	v_fmac_f32_e32 v108, v112, v112
	v_fmac_f32_e32 v109, v116, v116
	v_add_f32_e32 v108, v108, v109
	v_add_f32_e32 v99, v99, v108
	v_add_f32_e32 v108, v98, v99
	ds_bpermute_b32 v109, v154, v108
	v_cvt_pk_bf16_f32 v97, v110, v111
	v_cvt_pk_bf16_f32 v98, v104, v105
	v_cvt_pk_bf16_f32 v99, v106, v107
	global_store_dwordx4 v[114:115], v[96:99], off sc1
	s_waitcnt lgkmcnt(0)
	s_nop 0
	v_add_f32_e32 v96, v108, v109
	ds_bpermute_b32 v97, v153, v96
	v_cvt_pk_bf16_f32 v98, v100, v101
	v_cvt_pk_bf16_f32 v99, v102, v103
	v_cvt_pk_bf16_f32 v100, v112, v113
	v_cvt_pk_bf16_f32 v101, v116, v117
	global_store_dwordx4 v[114:115], v[98:101], off offset:64 sc1
	s_and_saveexec_b64 s[24:25], s[4:5]
	s_mov_b32 s30, s72
	s_cbranch_execz .LBB0_977
	s_add_u32 s28, s51, s27
	s_addc_u32 s29, s52, s26
	v_lshl_add_u64 v[98:99], v[140:141], 2, s[28:29]
	s_waitcnt lgkmcnt(0)
	v_add_f32_e32 v96, v96, v97
	global_store_dword v[98:99], v96, off offset:64
.LBB0_977:
	s_or_b64 exec, exec, s[24:25]
	v_add_f32_e32 v96, v165, v166
	v_fmamk_f32 v96, v96, 0x3a800000, v152
	v_rsq_f32_e32 v96, v96
	v_or_b32_e32 v98, 32, v140
	v_ashrrev_i32_e32 v99, 31, v98
	s_waitcnt lgkmcnt(0)
	v_pk_mul_f32 v[94:95], v[94:95], v[96:97] op_sel_hi:[1,0]
	v_pk_mul_f32 v[92:93], v[92:93], v[96:97] op_sel_hi:[1,0]
	v_pk_mul_f32 v[90:91], v[90:91], v[96:97] op_sel_hi:[1,0]
	v_pk_mul_f32 v[88:89], v[88:89], v[96:97] op_sel_hi:[1,0]
	v_pk_mul_f32 v[86:87], v[86:87], v[96:97] op_sel_hi:[1,0]
	v_pk_mul_f32 v[84:85], v[84:85], v[96:97] op_sel_hi:[1,0]
	v_pk_mul_f32 v[100:101], v[82:83], v[96:97] op_sel_hi:[1,0]
	v_pk_mul_f32 v[96:97], v[80:81], v[96:97] op_sel_hi:[1,0]
	v_lshlrev_b64 v[80:81], 10, v[98:99]
	v_mul_f32_e32 v82, v93, v93
	v_mul_f32_e32 v83, v95, v95
	v_lshl_add_u64 v[80:81], s[10:11], 0, v[80:81]
	v_fmac_f32_e32 v82, v92, v92
	v_fmac_f32_e32 v83, v94, v94
	v_lshl_add_u64 v[98:99], v[142:143], 1, v[80:81]
	v_cvt_pk_bf16_f32 v80, v92, v93
	v_add_f32_e32 v82, v82, v83
	v_mul_f32_e32 v83, v89, v89
	v_mul_f32_e32 v92, v91, v91
	v_fmac_f32_e32 v83, v88, v88
	v_fmac_f32_e32 v92, v90, v90
	v_add_f32_e32 v83, v83, v92
	v_add_f32_e32 v82, v82, v83
	v_mul_f32_e32 v83, v85, v85
	v_mul_f32_e32 v92, v87, v87
	v_fmac_f32_e32 v83, v84, v84
	v_fmac_f32_e32 v92, v86, v86
	v_add_f32_e32 v83, v83, v92
	v_mul_f32_e32 v92, v97, v97
	v_mul_f32_e32 v93, v101, v101
	v_fmac_f32_e32 v92, v96, v96
	v_fmac_f32_e32 v93, v100, v100
	v_add_f32_e32 v92, v92, v93
	v_add_f32_e32 v83, v83, v92
	v_add_f32_e32 v92, v82, v83
	ds_bpermute_b32 v93, v154, v92
	v_cvt_pk_bf16_f32 v81, v94, v95
	v_cvt_pk_bf16_f32 v82, v88, v89
	v_cvt_pk_bf16_f32 v83, v90, v91
	global_store_dwordx4 v[98:99], v[80:83], off sc1
	s_waitcnt lgkmcnt(0)
	s_nop 0
	v_add_f32_e32 v80, v92, v93
	ds_bpermute_b32 v81, v153, v80
	v_cvt_pk_bf16_f32 v82, v84, v85
	v_cvt_pk_bf16_f32 v83, v86, v87
	v_cvt_pk_bf16_f32 v84, v96, v97
	v_cvt_pk_bf16_f32 v85, v100, v101
	global_store_dwordx4 v[98:99], v[82:85], off offset:64 sc1
	s_and_saveexec_b64 s[24:25], s[4:5]
	s_cbranch_execz .LBB0_979
	s_add_u32 s28, s51, s27
	s_addc_u32 s29, s52, s26
	v_lshl_add_u64 v[82:83], v[140:141], 2, s[28:29]
	s_waitcnt lgkmcnt(0)
	v_add_f32_e32 v80, v80, v81
	global_store_dword v[82:83], v80, off offset:128
.LBB0_979:
	s_or_b64 exec, exec, s[24:25]
	v_add_f32_e32 v80, v163, v164
	v_fmamk_f32 v80, v80, 0x3a800000, v152
	v_rsq_f32_e32 v80, v80
	v_or_b32_e32 v82, 48, v140
	v_ashrrev_i32_e32 v83, 31, v82
	s_waitcnt lgkmcnt(0)
	v_pk_mul_f32 v[78:79], v[78:79], v[80:81] op_sel_hi:[1,0]
	v_pk_mul_f32 v[76:77], v[76:77], v[80:81] op_sel_hi:[1,0]
	v_pk_mul_f32 v[74:75], v[74:75], v[80:81] op_sel_hi:[1,0]
	v_pk_mul_f32 v[72:73], v[72:73], v[80:81] op_sel_hi:[1,0]
	v_pk_mul_f32 v[70:71], v[70:71], v[80:81] op_sel_hi:[1,0]
	v_pk_mul_f32 v[68:69], v[68:69], v[80:81] op_sel_hi:[1,0]
	v_pk_mul_f32 v[84:85], v[66:67], v[80:81] op_sel_hi:[1,0]
	v_pk_mul_f32 v[80:81], v[64:65], v[80:81] op_sel_hi:[1,0]
	v_lshlrev_b64 v[64:65], 10, v[82:83]
	v_mul_f32_e32 v66, v77, v77
	v_mul_f32_e32 v67, v79, v79
	v_lshl_add_u64 v[64:65], s[10:11], 0, v[64:65]
	v_fmac_f32_e32 v66, v76, v76
	v_fmac_f32_e32 v67, v78, v78
	v_lshl_add_u64 v[82:83], v[142:143], 1, v[64:65]
	v_cvt_pk_bf16_f32 v64, v76, v77
	v_add_f32_e32 v66, v66, v67
	v_mul_f32_e32 v67, v73, v73
	v_mul_f32_e32 v76, v75, v75
	v_fmac_f32_e32 v67, v72, v72
	v_fmac_f32_e32 v76, v74, v74
	v_add_f32_e32 v67, v67, v76
	v_add_f32_e32 v66, v66, v67
	v_mul_f32_e32 v67, v69, v69
	v_mul_f32_e32 v76, v71, v71
	v_fmac_f32_e32 v67, v68, v68
	v_fmac_f32_e32 v76, v70, v70
	v_add_f32_e32 v67, v67, v76
	v_mul_f32_e32 v76, v81, v81
	v_mul_f32_e32 v77, v85, v85
	v_fmac_f32_e32 v76, v80, v80
	v_fmac_f32_e32 v77, v84, v84
	v_add_f32_e32 v76, v76, v77
	v_add_f32_e32 v67, v67, v76
	v_add_f32_e32 v76, v66, v67
	ds_bpermute_b32 v77, v154, v76
	v_cvt_pk_bf16_f32 v65, v78, v79
	v_cvt_pk_bf16_f32 v66, v72, v73
	v_cvt_pk_bf16_f32 v67, v74, v75
	global_store_dwordx4 v[82:83], v[64:67], off sc1
	s_waitcnt lgkmcnt(0)
	s_nop 0
	v_add_f32_e32 v64, v76, v77
	ds_bpermute_b32 v65, v153, v64
	v_cvt_pk_bf16_f32 v66, v68, v69
	v_cvt_pk_bf16_f32 v67, v70, v71
	v_cvt_pk_bf16_f32 v68, v80, v81
	v_cvt_pk_bf16_f32 v69, v84, v85
	global_store_dwordx4 v[82:83], v[66:69], off offset:64 sc1
	s_and_saveexec_b64 s[24:25], s[4:5]
	s_cbranch_execz .LBB0_981
	s_add_u32 s28, s51, s27
	s_addc_u32 s29, s52, s26
	v_lshl_add_u64 v[66:67], v[140:141], 2, s[28:29]
	s_waitcnt lgkmcnt(0)
	v_add_f32_e32 v64, v64, v65
	global_store_dword v[66:67], v64, off offset:192
.LBB0_981:
	s_or_b64 exec, exec, s[24:25]
	v_add_f32_e32 v64, v161, v162
	v_fmamk_f32 v64, v64, 0x3a800000, v152
	v_rsq_f32_e32 v66, v64
	v_add_u32_e32 v64, 0x80, v140
	s_waitcnt lgkmcnt(0)
	v_ashrrev_i32_e32 v65, 31, v64
	v_pk_mul_f32 v[62:63], v[62:63], v[66:67] op_sel_hi:[1,0]
	v_pk_mul_f32 v[60:61], v[60:61], v[66:67] op_sel_hi:[1,0]
	v_pk_mul_f32 v[58:59], v[58:59], v[66:67] op_sel_hi:[1,0]
	v_pk_mul_f32 v[56:57], v[56:57], v[66:67] op_sel_hi:[1,0]
	v_pk_mul_f32 v[54:55], v[54:55], v[66:67] op_sel_hi:[1,0]
	v_pk_mul_f32 v[52:53], v[52:53], v[66:67] op_sel_hi:[1,0]
	v_pk_mul_f32 v[68:69], v[50:51], v[66:67] op_sel_hi:[1,0]
	v_pk_mul_f32 v[66:67], v[48:49], v[66:67] op_sel_hi:[1,0]
	v_lshlrev_b64 v[48:49], 10, v[64:65]
	v_mul_f32_e32 v50, v61, v61
	v_mul_f32_e32 v51, v63, v63
	v_lshl_add_u64 v[48:49], s[10:11], 0, v[48:49]
	v_fmac_f32_e32 v50, v60, v60
	v_fmac_f32_e32 v51, v62, v62
	v_lshl_add_u64 v[70:71], v[142:143], 1, v[48:49]
	v_cvt_pk_bf16_f32 v48, v60, v61
	v_add_f32_e32 v50, v50, v51
	v_mul_f32_e32 v51, v57, v57
	v_mul_f32_e32 v60, v59, v59
	v_fmac_f32_e32 v51, v56, v56
	v_fmac_f32_e32 v60, v58, v58
	v_add_f32_e32 v51, v51, v60
	v_add_f32_e32 v50, v50, v51
	v_mul_f32_e32 v51, v53, v53
	v_mul_f32_e32 v60, v55, v55
	v_fmac_f32_e32 v51, v52, v52
	v_fmac_f32_e32 v60, v54, v54
	v_add_f32_e32 v51, v51, v60
	v_mul_f32_e32 v60, v67, v67
	v_mul_f32_e32 v61, v69, v69
	v_fmac_f32_e32 v60, v66, v66
	v_fmac_f32_e32 v61, v68, v68
	v_add_f32_e32 v60, v60, v61
	v_add_f32_e32 v51, v51, v60
	v_add_f32_e32 v60, v50, v51
	ds_bpermute_b32 v61, v154, v60
	v_cvt_pk_bf16_f32 v49, v62, v63
	v_cvt_pk_bf16_f32 v50, v56, v57
	v_cvt_pk_bf16_f32 v51, v58, v59
	global_store_dwordx4 v[70:71], v[48:51], off sc1
	s_waitcnt lgkmcnt(0)
	s_nop 0
	v_add_f32_e32 v48, v60, v61
	ds_bpermute_b32 v49, v153, v48
	v_cvt_pk_bf16_f32 v50, v52, v53
	v_cvt_pk_bf16_f32 v51, v54, v55
	v_cvt_pk_bf16_f32 v52, v66, v67
	v_cvt_pk_bf16_f32 v53, v68, v69
	global_store_dwordx4 v[70:71], v[50:53], off offset:64 sc1
	s_and_saveexec_b64 s[24:25], s[4:5]
	s_cbranch_execz .LBB0_983
	s_add_u32 s28, s51, s27
	s_addc_u32 s29, s52, s26
	v_lshl_add_u64 v[50:51], v[64:65], 2, s[28:29]
	s_waitcnt lgkmcnt(0)
	v_add_f32_e32 v48, v48, v49
	global_store_dword v[50:51], v48, off
.LBB0_983:
	s_or_b64 exec, exec, s[24:25]
	v_add_f32_e32 v48, v159, v160
	v_fmamk_f32 v48, v48, 0x3a800000, v152
	v_rsq_f32_e32 v50, v48
	v_add_u32_e32 v48, 0x90, v140
	s_waitcnt lgkmcnt(0)
	v_ashrrev_i32_e32 v49, 31, v48
	v_pk_mul_f32 v[46:47], v[46:47], v[50:51] op_sel_hi:[1,0]
	v_pk_mul_f32 v[44:45], v[44:45], v[50:51] op_sel_hi:[1,0]
	v_pk_mul_f32 v[42:43], v[42:43], v[50:51] op_sel_hi:[1,0]
	v_pk_mul_f32 v[40:41], v[40:41], v[50:51] op_sel_hi:[1,0]
	v_pk_mul_f32 v[38:39], v[38:39], v[50:51] op_sel_hi:[1,0]
	v_pk_mul_f32 v[36:37], v[36:37], v[50:51] op_sel_hi:[1,0]
	v_pk_mul_f32 v[52:53], v[34:35], v[50:51] op_sel_hi:[1,0]
	v_pk_mul_f32 v[50:51], v[32:33], v[50:51] op_sel_hi:[1,0]
	v_lshlrev_b64 v[32:33], 10, v[48:49]
	v_mul_f32_e32 v34, v45, v45
	v_mul_f32_e32 v35, v47, v47
	v_lshl_add_u64 v[32:33], s[10:11], 0, v[32:33]
	v_fmac_f32_e32 v34, v44, v44
	v_fmac_f32_e32 v35, v46, v46
	v_lshl_add_u64 v[54:55], v[142:143], 1, v[32:33]
	v_cvt_pk_bf16_f32 v32, v44, v45
	v_add_f32_e32 v34, v34, v35
	v_mul_f32_e32 v35, v41, v41
	v_mul_f32_e32 v44, v43, v43
	v_fmac_f32_e32 v35, v40, v40
	v_fmac_f32_e32 v44, v42, v42
	v_add_f32_e32 v35, v35, v44
	v_add_f32_e32 v34, v34, v35
	v_mul_f32_e32 v35, v37, v37
	v_mul_f32_e32 v44, v39, v39
	v_fmac_f32_e32 v35, v36, v36
	v_fmac_f32_e32 v44, v38, v38
	v_add_f32_e32 v35, v35, v44
	v_mul_f32_e32 v44, v51, v51
	v_mul_f32_e32 v45, v53, v53
	v_fmac_f32_e32 v44, v50, v50
	v_fmac_f32_e32 v45, v52, v52
	v_add_f32_e32 v44, v44, v45
	v_add_f32_e32 v35, v35, v44
	v_add_f32_e32 v44, v34, v35
	ds_bpermute_b32 v45, v154, v44
	v_cvt_pk_bf16_f32 v33, v46, v47
	v_cvt_pk_bf16_f32 v34, v40, v41
	v_cvt_pk_bf16_f32 v35, v42, v43
	global_store_dwordx4 v[54:55], v[32:35], off sc1
	s_waitcnt lgkmcnt(0)
	s_nop 0
	v_add_f32_e32 v32, v44, v45
	ds_bpermute_b32 v33, v153, v32
	v_cvt_pk_bf16_f32 v34, v36, v37
	v_cvt_pk_bf16_f32 v35, v38, v39
	v_cvt_pk_bf16_f32 v36, v50, v51
	v_cvt_pk_bf16_f32 v37, v52, v53
	global_store_dwordx4 v[54:55], v[34:37], off offset:64 sc1
	s_and_saveexec_b64 s[24:25], s[4:5]
	s_cbranch_execz .LBB0_985
	s_add_u32 s28, s51, s27
	s_addc_u32 s29, s52, s26
	v_lshl_add_u64 v[34:35], v[48:49], 2, s[28:29]
	s_waitcnt lgkmcnt(0)
	v_add_f32_e32 v32, v32, v33
	global_store_dword v[34:35], v32, off
.LBB0_985:
	s_or_b64 exec, exec, s[24:25]
	v_add_f32_e32 v32, v157, v158
	v_fmamk_f32 v32, v32, 0x3a800000, v152
	v_rsq_f32_e32 v34, v32
	v_add_u32_e32 v32, 0xa0, v140
	s_waitcnt lgkmcnt(0)
	v_ashrrev_i32_e32 v33, 31, v32
	v_pk_mul_f32 v[30:31], v[30:31], v[34:35] op_sel_hi:[1,0]
	v_pk_mul_f32 v[28:29], v[28:29], v[34:35] op_sel_hi:[1,0]
	v_pk_mul_f32 v[26:27], v[26:27], v[34:35] op_sel_hi:[1,0]
	v_pk_mul_f32 v[24:25], v[24:25], v[34:35] op_sel_hi:[1,0]
	v_pk_mul_f32 v[22:23], v[22:23], v[34:35] op_sel_hi:[1,0]
	v_pk_mul_f32 v[20:21], v[20:21], v[34:35] op_sel_hi:[1,0]
	v_pk_mul_f32 v[36:37], v[18:19], v[34:35] op_sel_hi:[1,0]
	v_pk_mul_f32 v[34:35], v[16:17], v[34:35] op_sel_hi:[1,0]
	v_lshlrev_b64 v[16:17], 10, v[32:33]
	v_mul_f32_e32 v18, v29, v29
	v_mul_f32_e32 v19, v31, v31
	v_lshl_add_u64 v[16:17], s[10:11], 0, v[16:17]
	v_fmac_f32_e32 v18, v28, v28
	v_fmac_f32_e32 v19, v30, v30
	v_lshl_add_u64 v[38:39], v[142:143], 1, v[16:17]
	v_cvt_pk_bf16_f32 v16, v28, v29
	v_add_f32_e32 v18, v18, v19
	v_mul_f32_e32 v19, v25, v25
	v_mul_f32_e32 v28, v27, v27
	v_fmac_f32_e32 v19, v24, v24
	v_fmac_f32_e32 v28, v26, v26
	v_add_f32_e32 v19, v19, v28
	v_add_f32_e32 v18, v18, v19
	v_mul_f32_e32 v19, v21, v21
	v_mul_f32_e32 v28, v23, v23
	v_fmac_f32_e32 v19, v20, v20
	v_fmac_f32_e32 v28, v22, v22
	v_add_f32_e32 v19, v19, v28
	v_mul_f32_e32 v28, v35, v35
	v_mul_f32_e32 v29, v37, v37
	v_fmac_f32_e32 v28, v34, v34
	v_fmac_f32_e32 v29, v36, v36
	v_add_f32_e32 v28, v28, v29
	v_add_f32_e32 v19, v19, v28
	v_add_f32_e32 v28, v18, v19
	ds_bpermute_b32 v29, v154, v28
	v_cvt_pk_bf16_f32 v17, v30, v31
	v_cvt_pk_bf16_f32 v18, v24, v25
	v_cvt_pk_bf16_f32 v19, v26, v27
	global_store_dwordx4 v[38:39], v[16:19], off sc1
	s_waitcnt lgkmcnt(0)
	s_nop 0
	v_add_f32_e32 v16, v28, v29
	ds_bpermute_b32 v17, v153, v16
	v_cvt_pk_bf16_f32 v18, v20, v21
	v_cvt_pk_bf16_f32 v19, v22, v23
	v_cvt_pk_bf16_f32 v20, v34, v35
	v_cvt_pk_bf16_f32 v21, v36, v37
	global_store_dwordx4 v[38:39], v[18:21], off offset:64 sc1
	s_and_saveexec_b64 s[24:25], s[4:5]
	s_cbranch_execz .LBB0_987
	s_add_u32 s28, s51, s27
	s_addc_u32 s29, s52, s26
	v_lshl_add_u64 v[18:19], v[32:33], 2, s[28:29]
	s_waitcnt lgkmcnt(0)
	v_add_f32_e32 v16, v16, v17
	global_store_dword v[18:19], v16, off
.LBB0_987:
	s_or_b64 exec, exec, s[24:25]
	v_add_f32_e32 v16, v155, v156
	v_fmamk_f32 v16, v16, 0x3a800000, v152
	v_rsq_f32_e32 v18, v16
	v_add_u32_e32 v16, 0xb0, v140
	s_waitcnt lgkmcnt(0)
	v_ashrrev_i32_e32 v17, 31, v16
	v_pk_mul_f32 v[14:15], v[14:15], v[18:19] op_sel_hi:[1,0]
	v_pk_mul_f32 v[12:13], v[12:13], v[18:19] op_sel_hi:[1,0]
	v_pk_mul_f32 v[10:11], v[10:11], v[18:19] op_sel_hi:[1,0]
	v_pk_mul_f32 v[8:9], v[8:9], v[18:19] op_sel_hi:[1,0]
	v_pk_mul_f32 v[6:7], v[6:7], v[18:19] op_sel_hi:[1,0]
	v_pk_mul_f32 v[4:5], v[4:5], v[18:19] op_sel_hi:[1,0]
	v_pk_mul_f32 v[20:21], v[2:3], v[18:19] op_sel_hi:[1,0]
	v_pk_mul_f32 v[18:19], v[0:1], v[18:19] op_sel_hi:[1,0]
	v_lshlrev_b64 v[0:1], 10, v[16:17]
	v_mul_f32_e32 v2, v13, v13
	v_mul_f32_e32 v3, v15, v15
	v_lshl_add_u64 v[0:1], s[10:11], 0, v[0:1]
	v_fmac_f32_e32 v2, v12, v12
	v_fmac_f32_e32 v3, v14, v14
	v_lshl_add_u64 v[22:23], v[142:143], 1, v[0:1]
	v_cvt_pk_bf16_f32 v0, v12, v13
	v_add_f32_e32 v2, v2, v3
	v_mul_f32_e32 v3, v9, v9
	v_mul_f32_e32 v12, v11, v11
	v_fmac_f32_e32 v3, v8, v8
	v_fmac_f32_e32 v12, v10, v10
	v_add_f32_e32 v3, v3, v12
	v_add_f32_e32 v2, v2, v3
	v_mul_f32_e32 v3, v5, v5
	v_mul_f32_e32 v12, v7, v7
	v_fmac_f32_e32 v3, v4, v4
	v_fmac_f32_e32 v12, v6, v6
	v_add_f32_e32 v3, v3, v12
	v_mul_f32_e32 v12, v19, v19
	v_mul_f32_e32 v13, v21, v21
	v_fmac_f32_e32 v12, v18, v18
	v_fmac_f32_e32 v13, v20, v20
	v_add_f32_e32 v12, v12, v13
	v_add_f32_e32 v3, v3, v12
	v_add_f32_e32 v12, v2, v3
	ds_bpermute_b32 v13, v154, v12
	v_cvt_pk_bf16_f32 v1, v14, v15
	v_cvt_pk_bf16_f32 v2, v8, v9
	v_cvt_pk_bf16_f32 v3, v10, v11
	global_store_dwordx4 v[22:23], v[0:3], off sc1
	s_waitcnt lgkmcnt(0)
	s_nop 0
	v_add_f32_e32 v0, v12, v13
	ds_bpermute_b32 v1, v153, v0
	v_cvt_pk_bf16_f32 v2, v4, v5
	v_cvt_pk_bf16_f32 v3, v6, v7
	v_cvt_pk_bf16_f32 v4, v18, v19
	v_cvt_pk_bf16_f32 v5, v20, v21
	global_store_dwordx4 v[22:23], v[2:5], off offset:64 sc1
	s_and_saveexec_b64 s[24:25], s[4:5]
	s_cbranch_execz .LBB0_966
	s_add_u32 s28, s51, s27
	s_addc_u32 s29, s52, s26
	v_lshl_add_u64 v[2:3], v[16:17], 2, s[28:29]
	s_waitcnt lgkmcnt(0)
	v_add_f32_e32 v0, v0, v1
	global_store_dword v[2:3], v0, off
	s_branch .LBB0_966

.LBB0_1128:
	ds_read_b128 v[128:131], v186
	ds_read_b128 v[132:135], v186 offset:1024
	ds_read_b128 v[136:139], v186 offset:2048
	ds_read_b128 v[140:143], v186 offset:3072
	s_add_u32 s26, s24, 0xfffe0080
	s_addc_u32 s27, s25, -1
	s_cmp_eq_u32 s38, 4
	s_cselect_b32 s29, s19, s27
	s_cselect_b32 s28, s30, s26
	s_cselect_b32 s27, s34, s37
	s_cselect_b32 s26, s35, s36
	v_lshl_add_u64 v[182:183], s[24:25], 0, v[164:165]
	s_add_i32 m0, s42, 0xc000
	ds_read_b128 v[144:147], v187
	ds_read_b128 v[148:151], v187 offset:1024
	ds_read_b128 v[152:155], v187 offset:2048
	ds_read_b128 v[156:159], v187 offset:3072
	ds_read_b128 v[170:173], v187 offset:4096
	ds_read_b128 v[174:177], v187 offset:5120
	ds_read_b128 v[178:181], v187 offset:6144
	ds_read_b128 v[192:195], v187 offset:7168
	global_load_lds_dwordx4 v[182:183], off
	v_lshl_add_u64 v[182:183], s[24:25], 0, v[166:167]
	s_add_i32 m0, s42, 0xe000
	s_nop 0
	global_load_lds_dwordx4 v[182:183], off
	ds_read_b128 v[196:199], v188
	ds_read_b128 v[204:207], v188 offset:1024
	ds_read_b128 v[208:211], v188 offset:2048
	ds_read_b128 v[212:215], v188 offset:3072
	s_waitcnt lgkmcnt(0)
	s_waitcnt vmcnt(8)
	s_barrier
	s_setprio 1
	v_mfma_f32_16x16x32_bf16 v[124:127], v[128:131], v[144:147], v[124:127]
	v_mfma_f32_16x16x32_bf16 v[120:123], v[136:139], v[144:147], v[120:123]
	v_mfma_f32_16x16x32_bf16 v[108:111], v[128:131], v[152:155], v[108:111]
	v_mfma_f32_16x16x32_bf16 v[104:107], v[136:139], v[152:155], v[104:107]
	v_mfma_f32_16x16x32_bf16 v[92:95], v[128:131], v[170:173], v[92:95]
	v_mfma_f32_16x16x32_bf16 v[88:91], v[136:139], v[170:173], v[88:91]
	v_mfma_f32_16x16x32_bf16 v[76:79], v[128:131], v[178:181], v[76:79]
	v_mfma_f32_16x16x32_bf16 v[72:75], v[136:139], v[178:181], v[72:75]
	v_mfma_f32_16x16x32_bf16 v[124:127], v[132:135], v[148:151], v[124:127]
	v_mfma_f32_16x16x32_bf16 v[120:123], v[140:143], v[148:151], v[120:123]
	v_mfma_f32_16x16x32_bf16 v[108:111], v[132:135], v[156:159], v[108:111]
	v_mfma_f32_16x16x32_bf16 v[104:107], v[140:143], v[156:159], v[104:107]
	v_mfma_f32_16x16x32_bf16 v[92:95], v[132:135], v[174:177], v[92:95]
	v_mfma_f32_16x16x32_bf16 v[88:91], v[140:143], v[174:177], v[88:91]
	v_mfma_f32_16x16x32_bf16 v[76:79], v[132:135], v[192:195], v[76:79]
	v_mfma_f32_16x16x32_bf16 v[72:75], v[140:143], v[192:195], v[72:75]
	v_mfma_f32_16x16x32_bf16 v[116:119], v[196:199], v[144:147], v[116:119]
	v_mfma_f32_16x16x32_bf16 v[112:115], v[208:211], v[144:147], v[112:115]
	v_mfma_f32_16x16x32_bf16 v[100:103], v[196:199], v[152:155], v[100:103]
	v_mfma_f32_16x16x32_bf16 v[96:99], v[208:211], v[152:155], v[96:99]
	v_mfma_f32_16x16x32_bf16 v[84:87], v[196:199], v[170:173], v[84:87]
	v_mfma_f32_16x16x32_bf16 v[80:83], v[208:211], v[170:173], v[80:83]
	v_mfma_f32_16x16x32_bf16 v[68:71], v[196:199], v[178:181], v[68:71]
	v_mfma_f32_16x16x32_bf16 v[64:67], v[208:211], v[178:181], v[64:67]
	v_mfma_f32_16x16x32_bf16 v[116:119], v[204:207], v[148:151], v[116:119]
	v_mfma_f32_16x16x32_bf16 v[112:115], v[212:215], v[148:151], v[112:115]
	v_mfma_f32_16x16x32_bf16 v[100:103], v[204:207], v[156:159], v[100:103]
	v_mfma_f32_16x16x32_bf16 v[96:99], v[212:215], v[156:159], v[96:99]
	v_mfma_f32_16x16x32_bf16 v[84:87], v[204:207], v[174:177], v[84:87]
	v_mfma_f32_16x16x32_bf16 v[80:83], v[212:215], v[174:177], v[80:83]
	v_mfma_f32_16x16x32_bf16 v[68:71], v[204:207], v[192:195], v[68:71]
	v_mfma_f32_16x16x32_bf16 v[64:67], v[212:215], v[192:195], v[64:67]
	s_setprio 0
	s_barrier
	ds_read_b128 v[144:147], v187 offset:16384
	ds_read_b128 v[148:151], v187 offset:17408
	ds_read_b128 v[152:155], v187 offset:18432
	ds_read_b128 v[156:159], v187 offset:19456
	ds_read_b128 v[170:173], v187 offset:20480
	ds_read_b128 v[174:177], v187 offset:21504
	ds_read_b128 v[178:181], v187 offset:22528
	ds_read_b128 v[192:195], v187 offset:23552
	s_mov_b32 m0, s40
	v_lshl_add_u64 v[182:183], s[26:27], 0, v[160:161]
	global_load_lds_dwordx4 v[182:183], off
	v_lshl_add_u64 v[200:201], s[26:27], 0, v[162:163]
	s_mov_b32 m0, s41
	s_nop 0
	global_load_lds_dwordx4 v[200:201], off
	s_mov_b32 m0, s42
	v_lshl_add_u64 v[216:217], s[28:29], 0, v[160:161]
	global_load_lds_dwordx4 v[216:217], off
	v_lshl_add_u64 v[218:219], s[28:29], 0, v[162:163]
	s_mov_b32 m0, s43
	s_nop 0
	global_load_lds_dwordx4 v[218:219], off
	s_add_u32 s64, s26, 0x20000
	s_addc_u32 s65, s27, 0
	s_mov_b32 m0, s44
	v_lshl_add_u64 v[248:249], s[64:65], 0, v[160:161]
	global_load_lds_dwordx4 v[248:249], off
	v_lshl_add_u64 v[248:249], s[64:65], 0, v[162:163]
	s_mov_b32 m0, s45
	s_nop 0
	global_load_lds_dwordx4 v[248:249], off
	s_waitcnt lgkmcnt(0)
	s_waitcnt vmcnt(8)
	s_barrier
	s_setprio 1
	v_mfma_f32_16x16x32_bf16 v[60:63], v[128:131], v[144:147], v[60:63]
	v_mfma_f32_16x16x32_bf16 v[56:59], v[136:139], v[144:147], v[56:59]
	v_mfma_f32_16x16x32_bf16 v[44:47], v[128:131], v[152:155], v[44:47]
	v_mfma_f32_16x16x32_bf16 v[40:43], v[136:139], v[152:155], v[40:43]
	v_mfma_f32_16x16x32_bf16 v[28:31], v[128:131], v[170:173], v[28:31]
	v_mfma_f32_16x16x32_bf16 v[24:27], v[136:139], v[170:173], v[24:27]
	v_mfma_f32_16x16x32_bf16 v[12:15], v[128:131], v[178:181], v[12:15]
	v_mfma_f32_16x16x32_bf16 v[8:11], v[136:139], v[178:181], v[8:11]
	v_mfma_f32_16x16x32_bf16 v[60:63], v[132:135], v[148:151], v[60:63]
	v_mfma_f32_16x16x32_bf16 v[56:59], v[140:143], v[148:151], v[56:59]
	v_mfma_f32_16x16x32_bf16 v[44:47], v[132:135], v[156:159], v[44:47]
	v_mfma_f32_16x16x32_bf16 v[40:43], v[140:143], v[156:159], v[40:43]
	v_mfma_f32_16x16x32_bf16 v[28:31], v[132:135], v[174:177], v[28:31]
	v_mfma_f32_16x16x32_bf16 v[24:27], v[140:143], v[174:177], v[24:27]
	v_mfma_f32_16x16x32_bf16 v[12:15], v[132:135], v[192:195], v[12:15]
	v_mfma_f32_16x16x32_bf16 v[8:11], v[140:143], v[192:195], v[8:11]
	v_mfma_f32_16x16x32_bf16 v[52:55], v[196:199], v[144:147], v[52:55]
	v_mfma_f32_16x16x32_bf16 v[48:51], v[208:211], v[144:147], v[48:51]
	v_mfma_f32_16x16x32_bf16 v[36:39], v[196:199], v[152:155], v[36:39]
	v_mfma_f32_16x16x32_bf16 v[32:35], v[208:211], v[152:155], v[32:35]
	v_mfma_f32_16x16x32_bf16 v[20:23], v[196:199], v[170:173], v[20:23]
	v_mfma_f32_16x16x32_bf16 v[16:19], v[208:211], v[170:173], v[16:19]
	v_mfma_f32_16x16x32_bf16 v[4:7], v[196:199], v[178:181], v[4:7]
	v_mfma_f32_16x16x32_bf16 v[0:3], v[208:211], v[178:181], v[0:3]
	v_mfma_f32_16x16x32_bf16 v[52:55], v[204:207], v[148:151], v[52:55]
	v_mfma_f32_16x16x32_bf16 v[48:51], v[212:215], v[148:151], v[48:51]
	v_mfma_f32_16x16x32_bf16 v[36:39], v[204:207], v[156:159], v[36:39]
	v_mfma_f32_16x16x32_bf16 v[32:35], v[212:215], v[156:159], v[32:35]
	v_mfma_f32_16x16x32_bf16 v[20:23], v[204:207], v[174:177], v[20:23]
	v_mfma_f32_16x16x32_bf16 v[16:19], v[212:215], v[174:177], v[16:19]
	v_mfma_f32_16x16x32_bf16 v[4:7], v[204:207], v[192:195], v[4:7]
	v_mfma_f32_16x16x32_bf16 v[0:3], v[212:215], v[192:195], v[0:3]
	s_setprio 0
	s_barrier
	ds_read_b128 v[128:131], v189
	ds_read_b128 v[132:135], v189 offset:1024
	ds_read_b128 v[136:139], v189 offset:2048
	ds_read_b128 v[140:143], v189 offset:3072
	s_add_u32 s28, s28, 0x20000
	s_addc_u32 s29, s29, 0
	s_mov_b32 m0, s46
	v_lshl_add_u64 v[196:197], s[28:29], 0, v[160:161]
	ds_read_b128 v[144:147], v187 offset:32768
	ds_read_b128 v[148:151], v187 offset:33792
	ds_read_b128 v[152:155], v187 offset:34816
	ds_read_b128 v[156:159], v187 offset:35840
	ds_read_b128 v[170:173], v187 offset:36864
	ds_read_b128 v[174:177], v187 offset:37888
	ds_read_b128 v[178:181], v187 offset:38912
	ds_read_b128 v[192:195], v187 offset:39936
	global_load_lds_dwordx4 v[196:197], off
	v_lshl_add_u64 v[196:197], s[28:29], 0, v[162:163]
	s_mov_b32 m0, s47
	s_nop 0
	global_load_lds_dwordx4 v[196:197], off
	ds_read_b128 v[196:199], v190
	ds_read_b128 v[204:207], v190 offset:1024
	ds_read_b128 v[208:211], v190 offset:2048
	ds_read_b128 v[212:215], v190 offset:3072
	s_waitcnt lgkmcnt(0)
	s_waitcnt vmcnt(8)
	s_barrier
	s_setprio 1
	v_mfma_f32_16x16x32_bf16 v[124:127], v[128:131], v[144:147], v[124:127]
	v_mfma_f32_16x16x32_bf16 v[120:123], v[136:139], v[144:147], v[120:123]
	v_mfma_f32_16x16x32_bf16 v[108:111], v[128:131], v[152:155], v[108:111]
	v_mfma_f32_16x16x32_bf16 v[104:107], v[136:139], v[152:155], v[104:107]
	v_mfma_f32_16x16x32_bf16 v[92:95], v[128:131], v[170:173], v[92:95]
	v_mfma_f32_16x16x32_bf16 v[88:91], v[136:139], v[170:173], v[88:91]
	v_mfma_f32_16x16x32_bf16 v[76:79], v[128:131], v[178:181], v[76:79]
	v_mfma_f32_16x16x32_bf16 v[72:75], v[136:139], v[178:181], v[72:75]
	v_mfma_f32_16x16x32_bf16 v[124:127], v[132:135], v[148:151], v[124:127]
	v_mfma_f32_16x16x32_bf16 v[120:123], v[140:143], v[148:151], v[120:123]
	v_mfma_f32_16x16x32_bf16 v[108:111], v[132:135], v[156:159], v[108:111]
	v_mfma_f32_16x16x32_bf16 v[104:107], v[140:143], v[156:159], v[104:107]
	v_mfma_f32_16x16x32_bf16 v[92:95], v[132:135], v[174:177], v[92:95]
	v_mfma_f32_16x16x32_bf16 v[88:91], v[140:143], v[174:177], v[88:91]
	v_mfma_f32_16x16x32_bf16 v[76:79], v[132:135], v[192:195], v[76:79]
	v_mfma_f32_16x16x32_bf16 v[72:75], v[140:143], v[192:195], v[72:75]
	v_mfma_f32_16x16x32_bf16 v[116:119], v[196:199], v[144:147], v[116:119]
	v_mfma_f32_16x16x32_bf16 v[112:115], v[208:211], v[144:147], v[112:115]
	v_mfma_f32_16x16x32_bf16 v[100:103], v[196:199], v[152:155], v[100:103]
	v_mfma_f32_16x16x32_bf16 v[96:99], v[208:211], v[152:155], v[96:99]
	v_mfma_f32_16x16x32_bf16 v[84:87], v[196:199], v[170:173], v[84:87]
	v_mfma_f32_16x16x32_bf16 v[80:83], v[208:211], v[170:173], v[80:83]
	v_mfma_f32_16x16x32_bf16 v[68:71], v[196:199], v[178:181], v[68:71]
	v_mfma_f32_16x16x32_bf16 v[64:67], v[208:211], v[178:181], v[64:67]
	v_mfma_f32_16x16x32_bf16 v[116:119], v[204:207], v[148:151], v[116:119]
	v_mfma_f32_16x16x32_bf16 v[112:115], v[212:215], v[148:151], v[112:115]
	v_mfma_f32_16x16x32_bf16 v[100:103], v[204:207], v[156:159], v[100:103]
	v_mfma_f32_16x16x32_bf16 v[96:99], v[212:215], v[156:159], v[96:99]
	v_mfma_f32_16x16x32_bf16 v[84:87], v[204:207], v[174:177], v[84:87]
	v_mfma_f32_16x16x32_bf16 v[80:83], v[212:215], v[174:177], v[80:83]
	v_mfma_f32_16x16x32_bf16 v[68:71], v[204:207], v[192:195], v[68:71]
	v_mfma_f32_16x16x32_bf16 v[64:67], v[212:215], v[192:195], v[64:67]
	s_setprio 0
	s_barrier
	ds_read_b128 v[144:147], v187 offset:49152
	ds_read_b128 v[148:151], v187 offset:50176
	ds_read_b128 v[152:155], v187 offset:51200
	ds_read_b128 v[156:159], v187 offset:52224
	ds_read_b128 v[170:173], v187 offset:53248
	ds_read_b128 v[174:177], v187 offset:54272
	ds_read_b128 v[178:181], v187 offset:55296
	ds_read_b128 v[192:195], v187 offset:56320
	s_mov_b32 m0, s51
	v_lshl_add_u64 v[182:183], v[182:183], 0, s[10:11]
	global_load_lds_dwordx4 v[182:183], off
	v_lshl_add_u64 v[182:183], v[200:201], 0, s[10:11]
	s_mov_b32 m0, s52
	s_nop 0
	global_load_lds_dwordx4 v[182:183], off
	s_mov_b32 m0, s53
	v_lshl_add_u64 v[182:183], v[216:217], 0, s[10:11]
	global_load_lds_dwordx4 v[182:183], off
	v_lshl_add_u64 v[182:183], v[218:219], 0, s[10:11]
	s_mov_b32 m0, s54
	s_nop 0
	global_load_lds_dwordx4 v[182:183], off
	s_add_u32 s26, s26, 0x20080
	s_addc_u32 s27, s27, 0
	s_mov_b32 m0, s55
	v_lshl_add_u64 v[248:249], s[26:27], 0, v[160:161]
	global_load_lds_dwordx4 v[248:249], off
	v_lshl_add_u64 v[248:249], s[26:27], 0, v[162:163]
	s_mov_b32 m0, s56
	s_nop 0
	global_load_lds_dwordx4 v[248:249], off
	s_waitcnt lgkmcnt(0)
	s_waitcnt vmcnt(8)
	s_barrier
	s_setprio 1
	v_mfma_f32_16x16x32_bf16 v[60:63], v[128:131], v[144:147], v[60:63]
	v_mfma_f32_16x16x32_bf16 v[56:59], v[136:139], v[144:147], v[56:59]
	v_mfma_f32_16x16x32_bf16 v[44:47], v[128:131], v[152:155], v[44:47]
	v_mfma_f32_16x16x32_bf16 v[40:43], v[136:139], v[152:155], v[40:43]
	v_mfma_f32_16x16x32_bf16 v[28:31], v[128:131], v[170:173], v[28:31]
	v_mfma_f32_16x16x32_bf16 v[24:27], v[136:139], v[170:173], v[24:27]
	v_mfma_f32_16x16x32_bf16 v[12:15], v[128:131], v[178:181], v[12:15]
	v_mfma_f32_16x16x32_bf16 v[8:11], v[136:139], v[178:181], v[8:11]
	v_mfma_f32_16x16x32_bf16 v[60:63], v[132:135], v[148:151], v[60:63]
	v_mfma_f32_16x16x32_bf16 v[56:59], v[140:143], v[148:151], v[56:59]
	v_mfma_f32_16x16x32_bf16 v[44:47], v[132:135], v[156:159], v[44:47]
	v_mfma_f32_16x16x32_bf16 v[40:43], v[140:143], v[156:159], v[40:43]
	v_mfma_f32_16x16x32_bf16 v[28:31], v[132:135], v[174:177], v[28:31]
	v_mfma_f32_16x16x32_bf16 v[24:27], v[140:143], v[174:177], v[24:27]
	v_mfma_f32_16x16x32_bf16 v[12:15], v[132:135], v[192:195], v[12:15]
	v_mfma_f32_16x16x32_bf16 v[8:11], v[140:143], v[192:195], v[8:11]
	v_mfma_f32_16x16x32_bf16 v[52:55], v[196:199], v[144:147], v[52:55]
	v_mfma_f32_16x16x32_bf16 v[48:51], v[208:211], v[144:147], v[48:51]
	v_mfma_f32_16x16x32_bf16 v[36:39], v[196:199], v[152:155], v[36:39]
	v_mfma_f32_16x16x32_bf16 v[32:35], v[208:211], v[152:155], v[32:35]
	v_mfma_f32_16x16x32_bf16 v[20:23], v[196:199], v[170:173], v[20:23]
	v_mfma_f32_16x16x32_bf16 v[16:19], v[208:211], v[170:173], v[16:19]
	v_mfma_f32_16x16x32_bf16 v[4:7], v[196:199], v[178:181], v[4:7]
	v_mfma_f32_16x16x32_bf16 v[0:3], v[208:211], v[178:181], v[0:3]
	v_mfma_f32_16x16x32_bf16 v[52:55], v[204:207], v[148:151], v[52:55]
	v_mfma_f32_16x16x32_bf16 v[48:51], v[212:215], v[148:151], v[48:51]
	v_mfma_f32_16x16x32_bf16 v[36:39], v[204:207], v[156:159], v[36:39]
	v_mfma_f32_16x16x32_bf16 v[32:35], v[212:215], v[156:159], v[32:35]
	v_mfma_f32_16x16x32_bf16 v[20:23], v[204:207], v[174:177], v[20:23]
	v_mfma_f32_16x16x32_bf16 v[16:19], v[212:215], v[174:177], v[16:19]
	v_mfma_f32_16x16x32_bf16 v[4:7], v[204:207], v[192:195], v[4:7]
	v_mfma_f32_16x16x32_bf16 v[0:3], v[212:215], v[192:195], v[0:3]
	s_setprio 0
	s_add_i32 s38, s38, 2
	s_add_u32 s24, s24, 0x100
	s_addc_u32 s25, s25, 0
	s_add_u32 s36, s36, 0x100
	s_addc_u32 s37, s37, 0
	s_cmp_gt_u32 s38, 5
	s_barrier
	s_cbranch_scc0 .LBB0_1128
	v_lshl_or_b32 v128, s63, 8, v185
	v_lshl_add_u32 v170, s18, 8, v184
	v_ashrrev_i32_e32 v129, 31, v128
	v_lshlrev_b64 v[174:175], 1, v[128:129]
	v_ashrrev_i32_e32 v171, 31, v170
	v_lshl_add_u64 v[128:129], s[8:9], 0, v[174:175]
	v_lshlrev_b64 v[204:205], 11, v[170:171]
	v_lshl_add_u64 v[130:131], v[128:129], 0, v[204:205]
	global_load_dwordx4 v[194:197], v[130:131], off
	global_load_dwordx4 v[198:201], v[130:131], off offset:64
	v_or_b32_e32 v130, 16, v170
	v_or_b32_e32 v132, 32, v170
	v_or_b32_e32 v134, 48, v170
	v_ashrrev_i32_e32 v131, 31, v130
	v_ashrrev_i32_e32 v133, 31, v132
	v_ashrrev_i32_e32 v135, 31, v134
	v_lshlrev_b64 v[182:183], 11, v[130:131]
	v_add_u32_e32 v178, 0x80, v170
	v_lshlrev_b64 v[180:181], 11, v[132:133]
	v_lshlrev_b64 v[176:177], 11, v[134:135]
	v_lshl_add_u64 v[132:133], v[128:129], 0, v[182:183]
	v_ashrrev_i32_e32 v179, 31, v178
	v_lshl_add_u64 v[134:135], v[128:129], 0, v[180:181]
	v_lshl_add_u64 v[128:129], v[128:129], 0, v[176:177]
	global_load_dwordx4 v[156:159], v[132:133], off
	global_load_dwordx4 v[152:155], v[132:133], off offset:64
	global_load_dwordx4 v[148:151], v[134:135], off
	global_load_dwordx4 v[144:147], v[134:135], off offset:64
	global_load_dwordx4 v[140:143], v[128:129], off
	global_load_dwordx4 v[136:139], v[128:129], off offset:64
	v_lshlrev_b64 v[130:131], 11, v[178:179]
	v_lshl_add_u64 v[130:131], s[8:9], 0, v[130:131]
	v_lshl_add_u64 v[172:173], v[130:131], 0, v[174:175]
	global_load_dwordx4 v[132:135], v[172:173], off
	global_load_dwordx4 v[128:131], v[172:173], off offset:64
	v_and_b32_e32 v192, 64, v191
	v_xor_b32_e32 v179, 16, v191
	v_add_u32_e32 v192, 64, v192
	v_xor_b32_e32 v193, 32, v191
	v_cmp_lt_i32_e32 vcc, v179, v192
	v_lshl_add_u64 v[204:205], s[8:9], 0, v[204:205]
	v_lshl_add_u64 v[204:205], v[204:205], 0, v[174:175]
	v_cndmask_b32_e32 v179, v191, v179, vcc
	v_cmp_lt_i32_e32 vcc, v193, v192
	v_lshlrev_b32_e32 v192, 2, v179
	s_lshl_b32 s18, s63, 2
	v_cndmask_b32_e32 v193, v191, v193, vcc
	v_lshlrev_b32_e32 v179, 2, v193
	s_or_b32 s25, s18, s50
	s_mul_hi_i32 s24, s25, 0x21000
	s_mul_i32 s25, s25, 0x21000
	s_waitcnt vmcnt(0)
	v_lshlrev_b32_e32 v206, 16, v194
	v_and_b32_e32 v207, 0xffff0000, v194
	v_lshlrev_b32_e32 v194, 16, v195
	v_and_b32_e32 v195, 0xffff0000, v195
	v_lshlrev_b32_e32 v208, 16, v196
	v_and_b32_e32 v209, 0xffff0000, v196
	v_lshlrev_b32_e32 v196, 16, v197
	v_and_b32_e32 v197, 0xffff0000, v197
	v_lshlrev_b32_e32 v212, 16, v200
	v_and_b32_e32 v213, 0xffff0000, v200
	v_lshlrev_b32_e32 v200, 16, v201
	v_and_b32_e32 v201, 0xffff0000, v201
	v_pk_add_f32 v[126:127], v[126:127], v[194:195]
	v_pk_add_f32 v[124:125], v[124:125], v[206:207]
	v_pk_add_f32 v[122:123], v[122:123], v[196:197]
	v_pk_add_f32 v[120:121], v[120:121], v[208:209]
	v_lshlrev_b32_e32 v210, 16, v198
	v_and_b32_e32 v211, 0xffff0000, v198
	v_lshlrev_b32_e32 v198, 16, v199
	v_and_b32_e32 v199, 0xffff0000, v199
	v_pk_add_f32 v[194:195], v[114:115], v[200:201]
	v_pk_add_f32 v[196:197], v[112:113], v[212:213]
	v_cvt_pk_bf16_f32 v112, v124, v125
	v_cvt_pk_bf16_f32 v113, v126, v127
	v_mul_f32_e32 v114, v125, v125
	v_mul_f32_e32 v115, v127, v127
	v_mul_f32_e32 v125, v121, v121
	v_mul_f32_e32 v127, v123, v123
	v_pk_add_f32 v[118:119], v[118:119], v[198:199]
	v_pk_add_f32 v[116:117], v[116:117], v[210:211]
	v_fmac_f32_e32 v114, v124, v124
	v_fmac_f32_e32 v115, v126, v126
	v_fmac_f32_e32 v125, v120, v120
	v_fmac_f32_e32 v127, v122, v122
	v_mul_f32_e32 v193, v117, v117
	v_mul_f32_e32 v198, v119, v119
	v_add_f32_e32 v114, v114, v115
	v_add_f32_e32 v115, v125, v127
	v_mul_f32_e32 v124, v197, v197
	v_mul_f32_e32 v125, v195, v195
	v_fmac_f32_e32 v193, v116, v116
	v_fmac_f32_e32 v198, v118, v118
	v_fmac_f32_e32 v124, v196, v196
	v_fmac_f32_e32 v125, v194, v194
	v_add_f32_e32 v114, v114, v115
	v_add_f32_e32 v115, v193, v198
	v_add_f32_e32 v124, v124, v125
	v_add_f32_e32 v115, v115, v124
	v_add_f32_e32 v124, v114, v115
	ds_bpermute_b32 v125, v192, v124
	v_cvt_pk_bf16_f32 v114, v120, v121
	v_cvt_pk_bf16_f32 v115, v122, v123
	global_store_dwordx4 v[204:205], v[112:115], off sc1
	s_waitcnt lgkmcnt(0)
	s_nop 0
	v_add_f32_e32 v112, v124, v125
	ds_bpermute_b32 v113, v179, v112
	v_cvt_pk_bf16_f32 v114, v116, v117
	v_cvt_pk_bf16_f32 v115, v118, v119
	v_cvt_pk_bf16_f32 v116, v196, v197
	v_cvt_pk_bf16_f32 v117, v194, v195
	global_store_dwordx4 v[204:205], v[114:117], off offset:64 sc1
	s_and_saveexec_b64 s[18:19], s[4:5]
	s_cbranch_execz .LBB0_1131
	s_add_u32 s26, s48, s25
	s_addc_u32 s27, s49, s24
	s_waitcnt lgkmcnt(0)
	v_add_f32_e32 v114, v112, v113
	v_lshl_add_u64 v[112:113], v[170:171], 2, s[26:27]
	global_store_dword v[112:113], v114, off
.LBB0_1131:
	s_or_b64 exec, exec, s[18:19]
	v_or_b32_e32 v112, 16, v178
	s_waitcnt lgkmcnt(0)
	v_ashrrev_i32_e32 v113, 31, v112
	v_lshlrev_b64 v[112:113], 11, v[112:113]
	v_lshl_add_u64 v[112:113], s[8:9], 0, v[112:113]
	v_lshl_add_u64 v[120:121], v[112:113], 0, v[174:175]
	global_load_dwordx4 v[116:119], v[120:121], off
	global_load_dwordx4 v[112:115], v[120:121], off offset:64
	v_lshlrev_b32_e32 v124, 16, v157
	v_and_b32_e32 v125, 0xffff0000, v157
	v_lshlrev_b32_e32 v122, 16, v156
	v_and_b32_e32 v123, 0xffff0000, v156
	v_pk_add_f32 v[110:111], v[110:111], v[124:125]
	v_lshlrev_b32_e32 v124, 16, v159
	v_and_b32_e32 v125, 0xffff0000, v159
	v_pk_add_f32 v[108:109], v[108:109], v[122:123]
	v_lshlrev_b32_e32 v122, 16, v158
	v_and_b32_e32 v123, 0xffff0000, v158
	v_pk_add_f32 v[106:107], v[106:107], v[124:125]
	v_lshlrev_b32_e32 v124, 16, v153
	v_and_b32_e32 v125, 0xffff0000, v153
	v_pk_add_f32 v[104:105], v[104:105], v[122:123]
	v_lshlrev_b32_e32 v122, 16, v152
	v_and_b32_e32 v123, 0xffff0000, v152
	v_pk_add_f32 v[102:103], v[102:103], v[124:125]
	v_lshlrev_b32_e32 v124, 16, v155
	v_and_b32_e32 v125, 0xffff0000, v155
	v_pk_add_f32 v[100:101], v[100:101], v[122:123]
	v_lshlrev_b32_e32 v122, 16, v154
	v_and_b32_e32 v123, 0xffff0000, v154
	v_pk_add_f32 v[124:125], v[98:99], v[124:125]
	v_mul_f32_e32 v98, v109, v109
	v_mul_f32_e32 v99, v111, v111
	v_pk_add_f32 v[122:123], v[96:97], v[122:123]
	v_lshl_add_u64 v[96:97], s[8:9], 0, v[182:183]
	v_fmac_f32_e32 v98, v108, v108
	v_fmac_f32_e32 v99, v110, v110
	v_lshl_add_u64 v[126:127], v[96:97], 0, v[174:175]
	v_cvt_pk_bf16_f32 v96, v108, v109
	v_add_f32_e32 v98, v98, v99
	v_mul_f32_e32 v99, v105, v105
	v_mul_f32_e32 v108, v107, v107
	v_fmac_f32_e32 v99, v104, v104
	v_fmac_f32_e32 v108, v106, v106
	v_add_f32_e32 v99, v99, v108
	v_add_f32_e32 v98, v98, v99
	v_mul_f32_e32 v99, v101, v101
	v_mul_f32_e32 v108, v103, v103
	v_fmac_f32_e32 v99, v100, v100
	v_fmac_f32_e32 v108, v102, v102
	v_add_f32_e32 v99, v99, v108
	v_mul_f32_e32 v108, v123, v123
	v_mul_f32_e32 v109, v125, v125
	v_fmac_f32_e32 v108, v122, v122
	v_fmac_f32_e32 v109, v124, v124
	v_add_f32_e32 v108, v108, v109
	v_add_f32_e32 v99, v99, v108
	v_add_f32_e32 v108, v98, v99
	ds_bpermute_b32 v109, v192, v108
	v_cvt_pk_bf16_f32 v97, v110, v111
	v_cvt_pk_bf16_f32 v98, v104, v105
	v_cvt_pk_bf16_f32 v99, v106, v107
	global_store_dwordx4 v[126:127], v[96:99], off sc1
	s_waitcnt lgkmcnt(0)
	s_nop 0
	v_add_f32_e32 v96, v108, v109
	ds_bpermute_b32 v97, v179, v96
	v_cvt_pk_bf16_f32 v98, v100, v101
	v_cvt_pk_bf16_f32 v99, v102, v103
	v_cvt_pk_bf16_f32 v100, v122, v123
	v_cvt_pk_bf16_f32 v101, v124, v125
	global_store_dwordx4 v[126:127], v[98:101], off offset:64 sc1
	s_and_saveexec_b64 s[18:19], s[4:5]
	s_cbranch_execz .LBB0_1133
	s_add_u32 s26, s48, s25
	s_addc_u32 s27, s49, s24
	s_waitcnt lgkmcnt(0)
	v_add_f32_e32 v98, v96, v97
	v_lshl_add_u64 v[96:97], v[170:171], 2, s[26:27]
	global_store_dword v[96:97], v98, off offset:64
.LBB0_1133:
	s_or_b64 exec, exec, s[18:19]
	v_or_b32_e32 v96, 32, v178
	s_waitcnt lgkmcnt(0)
	v_ashrrev_i32_e32 v97, 31, v96
	v_lshlrev_b64 v[96:97], 11, v[96:97]
	v_lshl_add_u64 v[96:97], s[8:9], 0, v[96:97]
	v_lshl_add_u64 v[104:105], v[96:97], 0, v[174:175]
	global_load_dwordx4 v[100:103], v[104:105], off
	global_load_dwordx4 v[96:99], v[104:105], off offset:64
	v_lshlrev_b32_e32 v108, 16, v149
	v_and_b32_e32 v109, 0xffff0000, v149
	v_lshlrev_b32_e32 v106, 16, v148
	v_and_b32_e32 v107, 0xffff0000, v148
	v_pk_add_f32 v[94:95], v[94:95], v[108:109]
	v_lshlrev_b32_e32 v108, 16, v151
	v_and_b32_e32 v109, 0xffff0000, v151
	v_pk_add_f32 v[92:93], v[92:93], v[106:107]
	v_lshlrev_b32_e32 v106, 16, v150
	v_and_b32_e32 v107, 0xffff0000, v150
	v_pk_add_f32 v[90:91], v[90:91], v[108:109]
	v_lshlrev_b32_e32 v108, 16, v145
	v_and_b32_e32 v109, 0xffff0000, v145
	v_pk_add_f32 v[88:89], v[88:89], v[106:107]
	v_lshlrev_b32_e32 v106, 16, v144
	v_and_b32_e32 v107, 0xffff0000, v144
	v_pk_add_f32 v[86:87], v[86:87], v[108:109]
	v_lshlrev_b32_e32 v108, 16, v147
	v_and_b32_e32 v109, 0xffff0000, v147
	v_pk_add_f32 v[84:85], v[84:85], v[106:107]
	v_lshlrev_b32_e32 v106, 16, v146
	v_and_b32_e32 v107, 0xffff0000, v146
	v_pk_add_f32 v[108:109], v[82:83], v[108:109]
	v_mul_f32_e32 v82, v93, v93
	v_mul_f32_e32 v83, v95, v95
	v_pk_add_f32 v[106:107], v[80:81], v[106:107]
	v_lshl_add_u64 v[80:81], s[8:9], 0, v[180:181]
	v_fmac_f32_e32 v82, v92, v92
	v_fmac_f32_e32 v83, v94, v94
	v_lshl_add_u64 v[110:111], v[80:81], 0, v[174:175]
	v_cvt_pk_bf16_f32 v80, v92, v93
	v_add_f32_e32 v82, v82, v83
	v_mul_f32_e32 v83, v89, v89
	v_mul_f32_e32 v92, v91, v91
	v_fmac_f32_e32 v83, v88, v88
	v_fmac_f32_e32 v92, v90, v90
	v_add_f32_e32 v83, v83, v92
	v_add_f32_e32 v82, v82, v83
	v_mul_f32_e32 v83, v85, v85
	v_mul_f32_e32 v92, v87, v87
	v_fmac_f32_e32 v83, v84, v84
	v_fmac_f32_e32 v92, v86, v86
	v_add_f32_e32 v83, v83, v92
	v_mul_f32_e32 v92, v107, v107
	v_mul_f32_e32 v93, v109, v109
	v_fmac_f32_e32 v92, v106, v106
	v_fmac_f32_e32 v93, v108, v108
	v_add_f32_e32 v92, v92, v93
	v_add_f32_e32 v83, v83, v92
	v_add_f32_e32 v92, v82, v83
	ds_bpermute_b32 v93, v192, v92
	v_cvt_pk_bf16_f32 v81, v94, v95
	v_cvt_pk_bf16_f32 v82, v88, v89
	v_cvt_pk_bf16_f32 v83, v90, v91
	global_store_dwordx4 v[110:111], v[80:83], off sc1
	s_waitcnt lgkmcnt(0)
	s_nop 0
	v_add_f32_e32 v80, v92, v93
	ds_bpermute_b32 v81, v179, v80
	v_cvt_pk_bf16_f32 v82, v84, v85
	v_cvt_pk_bf16_f32 v83, v86, v87
	v_cvt_pk_bf16_f32 v84, v106, v107
	v_cvt_pk_bf16_f32 v85, v108, v109
	global_store_dwordx4 v[110:111], v[82:85], off offset:64 sc1
	s_and_saveexec_b64 s[18:19], s[4:5]
	s_cbranch_execz .LBB0_1135
	s_add_u32 s26, s48, s25
	s_addc_u32 s27, s49, s24
	s_waitcnt lgkmcnt(0)
	v_add_f32_e32 v82, v80, v81
	v_lshl_add_u64 v[80:81], v[170:171], 2, s[26:27]
	global_store_dword v[80:81], v82, off offset:128
.LBB0_1135:
	s_or_b64 exec, exec, s[18:19]
	v_or_b32_e32 v80, 48, v178
	s_waitcnt lgkmcnt(0)
	v_ashrrev_i32_e32 v81, 31, v80
	v_lshlrev_b64 v[80:81], 11, v[80:81]
	v_lshl_add_u64 v[80:81], s[8:9], 0, v[80:81]
	v_lshl_add_u64 v[88:89], v[80:81], 0, v[174:175]
	global_load_dwordx4 v[84:87], v[88:89], off
	global_load_dwordx4 v[80:83], v[88:89], off offset:64
	v_lshlrev_b32_e32 v92, 16, v141
	v_and_b32_e32 v93, 0xffff0000, v141
	v_lshlrev_b32_e32 v90, 16, v140
	v_and_b32_e32 v91, 0xffff0000, v140
	v_pk_add_f32 v[78:79], v[78:79], v[92:93]
	v_lshlrev_b32_e32 v92, 16, v143
	v_and_b32_e32 v93, 0xffff0000, v143
	v_pk_add_f32 v[76:77], v[76:77], v[90:91]
	v_lshlrev_b32_e32 v90, 16, v142
	v_and_b32_e32 v91, 0xffff0000, v142
	v_pk_add_f32 v[74:75], v[74:75], v[92:93]
	v_lshlrev_b32_e32 v92, 16, v137
	v_and_b32_e32 v93, 0xffff0000, v137
	v_pk_add_f32 v[72:73], v[72:73], v[90:91]
	v_lshlrev_b32_e32 v90, 16, v136
	v_and_b32_e32 v91, 0xffff0000, v136
	v_pk_add_f32 v[70:71], v[70:71], v[92:93]
	v_lshlrev_b32_e32 v92, 16, v139
	v_and_b32_e32 v93, 0xffff0000, v139
	v_pk_add_f32 v[68:69], v[68:69], v[90:91]
	v_lshlrev_b32_e32 v90, 16, v138
	v_and_b32_e32 v91, 0xffff0000, v138
	v_pk_add_f32 v[92:93], v[66:67], v[92:93]
	v_mul_f32_e32 v66, v77, v77
	v_mul_f32_e32 v67, v79, v79
	v_pk_add_f32 v[90:91], v[64:65], v[90:91]
	v_lshl_add_u64 v[64:65], s[8:9], 0, v[176:177]
	v_fmac_f32_e32 v66, v76, v76
	v_fmac_f32_e32 v67, v78, v78
	v_lshl_add_u64 v[94:95], v[64:65], 0, v[174:175]
	v_cvt_pk_bf16_f32 v64, v76, v77
	v_add_f32_e32 v66, v66, v67
	v_mul_f32_e32 v67, v73, v73
	v_mul_f32_e32 v76, v75, v75
	v_fmac_f32_e32 v67, v72, v72
	v_fmac_f32_e32 v76, v74, v74
	v_add_f32_e32 v67, v67, v76
	v_add_f32_e32 v66, v66, v67
	v_mul_f32_e32 v67, v69, v69
	v_mul_f32_e32 v76, v71, v71
	v_fmac_f32_e32 v67, v68, v68
	v_fmac_f32_e32 v76, v70, v70
	v_add_f32_e32 v67, v67, v76
	v_mul_f32_e32 v76, v91, v91
	v_mul_f32_e32 v77, v93, v93
	v_fmac_f32_e32 v76, v90, v90
	v_fmac_f32_e32 v77, v92, v92
	v_add_f32_e32 v76, v76, v77
	v_add_f32_e32 v67, v67, v76
	v_add_f32_e32 v76, v66, v67
	ds_bpermute_b32 v77, v192, v76
	v_cvt_pk_bf16_f32 v65, v78, v79
	v_cvt_pk_bf16_f32 v66, v72, v73
	v_cvt_pk_bf16_f32 v67, v74, v75
	global_store_dwordx4 v[94:95], v[64:67], off sc1
	s_waitcnt lgkmcnt(0)
	s_nop 0
	v_add_f32_e32 v64, v76, v77
	ds_bpermute_b32 v65, v179, v64
	v_cvt_pk_bf16_f32 v66, v68, v69
	v_cvt_pk_bf16_f32 v67, v70, v71
	v_cvt_pk_bf16_f32 v68, v90, v91
	v_cvt_pk_bf16_f32 v69, v92, v93
	global_store_dwordx4 v[94:95], v[66:69], off offset:64 sc1
	s_and_saveexec_b64 s[18:19], s[4:5]
	s_cbranch_execz .LBB0_1137
	s_add_u32 s26, s48, s25
	s_addc_u32 s27, s49, s24
	s_waitcnt lgkmcnt(0)
	v_add_f32_e32 v66, v64, v65
	v_lshl_add_u64 v[64:65], v[170:171], 2, s[26:27]
	global_store_dword v[64:65], v66, off offset:192
.LBB0_1137:
	s_or_b64 exec, exec, s[18:19]
	v_lshlrev_b32_e32 v66, 16, v133
	v_and_b32_e32 v67, 0xffff0000, v133
	v_pk_add_f32 v[62:63], v[62:63], v[66:67]
	v_lshlrev_b32_e32 v66, 16, v135
	v_and_b32_e32 v67, 0xffff0000, v135
	v_lshlrev_b32_e32 v64, 16, v132
	s_waitcnt lgkmcnt(0)
	v_and_b32_e32 v65, 0xffff0000, v132
	v_pk_add_f32 v[58:59], v[58:59], v[66:67]
	v_lshlrev_b32_e32 v66, 16, v129
	v_and_b32_e32 v67, 0xffff0000, v129
	v_pk_add_f32 v[60:61], v[60:61], v[64:65]
	v_lshlrev_b32_e32 v64, 16, v134
	v_and_b32_e32 v65, 0xffff0000, v134
	v_pk_add_f32 v[54:55], v[54:55], v[66:67]
	v_lshlrev_b32_e32 v66, 16, v131
	v_and_b32_e32 v67, 0xffff0000, v131
	v_pk_add_f32 v[56:57], v[56:57], v[64:65]
	v_lshlrev_b32_e32 v64, 16, v128
	v_and_b32_e32 v65, 0xffff0000, v128
	v_pk_add_f32 v[66:67], v[50:51], v[66:67]
	v_mul_f32_e32 v50, v61, v61
	v_mul_f32_e32 v51, v63, v63
	v_pk_add_f32 v[52:53], v[52:53], v[64:65]
	v_lshlrev_b32_e32 v64, 16, v130
	v_and_b32_e32 v65, 0xffff0000, v130
	v_fmac_f32_e32 v50, v60, v60
	v_fmac_f32_e32 v51, v62, v62
	v_pk_add_f32 v[64:65], v[48:49], v[64:65]
	v_cvt_pk_bf16_f32 v48, v60, v61
	v_add_f32_e32 v50, v50, v51
	v_mul_f32_e32 v51, v57, v57
	v_mul_f32_e32 v60, v59, v59
	v_fmac_f32_e32 v51, v56, v56
	v_fmac_f32_e32 v60, v58, v58
	v_add_f32_e32 v51, v51, v60
	v_add_f32_e32 v50, v50, v51
	v_mul_f32_e32 v51, v53, v53
	v_mul_f32_e32 v60, v55, v55
	v_fmac_f32_e32 v51, v52, v52
	v_fmac_f32_e32 v60, v54, v54
	v_add_f32_e32 v51, v51, v60
	v_mul_f32_e32 v60, v65, v65
	v_mul_f32_e32 v61, v67, v67
	v_fmac_f32_e32 v60, v64, v64
	v_fmac_f32_e32 v61, v66, v66
	v_add_f32_e32 v60, v60, v61
	v_add_f32_e32 v51, v51, v60
	v_add_f32_e32 v60, v50, v51
	ds_bpermute_b32 v61, v192, v60
	v_cvt_pk_bf16_f32 v49, v62, v63
	v_cvt_pk_bf16_f32 v50, v56, v57
	v_cvt_pk_bf16_f32 v51, v58, v59
	global_store_dwordx4 v[172:173], v[48:51], off sc1
	s_waitcnt lgkmcnt(0)
	s_nop 0
	v_add_f32_e32 v48, v60, v61
	ds_bpermute_b32 v49, v179, v48
	v_cvt_pk_bf16_f32 v50, v52, v53
	v_cvt_pk_bf16_f32 v51, v54, v55
	v_cvt_pk_bf16_f32 v52, v64, v65
	v_cvt_pk_bf16_f32 v53, v66, v67
	global_store_dwordx4 v[172:173], v[50:53], off offset:64 sc1
	s_and_saveexec_b64 s[18:19], s[4:5]
	s_cbranch_execz .LBB0_1139
	s_add_u32 s26, s48, s25
	s_addc_u32 s27, s49, s24
	s_waitcnt lgkmcnt(0)
	v_add_f32_e32 v50, v48, v49
	v_lshl_add_u64 v[48:49], v[170:171], 2, s[26:27]
	global_store_dword v[48:49], v50, off offset:512
.LBB0_1139:
	s_or_b64 exec, exec, s[18:19]
	s_waitcnt vmcnt(13)
	v_lshlrev_b32_e32 v50, 16, v117
	v_and_b32_e32 v51, 0xffff0000, v117
	v_pk_add_f32 v[46:47], v[46:47], v[50:51]
	v_lshlrev_b32_e32 v50, 16, v119
	v_and_b32_e32 v51, 0xffff0000, v119
	v_lshlrev_b32_e32 v48, 16, v116
	s_waitcnt lgkmcnt(0)
	v_and_b32_e32 v49, 0xffff0000, v116
	v_pk_add_f32 v[42:43], v[42:43], v[50:51]
	s_waitcnt vmcnt(12)
	v_lshlrev_b32_e32 v50, 16, v113
	v_and_b32_e32 v51, 0xffff0000, v113
	v_pk_add_f32 v[44:45], v[44:45], v[48:49]
	v_lshlrev_b32_e32 v48, 16, v118
	v_and_b32_e32 v49, 0xffff0000, v118
	v_pk_add_f32 v[38:39], v[38:39], v[50:51]
	v_lshlrev_b32_e32 v50, 16, v115
	v_and_b32_e32 v51, 0xffff0000, v115
	v_pk_add_f32 v[40:41], v[40:41], v[48:49]
	v_lshlrev_b32_e32 v48, 16, v112
	v_and_b32_e32 v49, 0xffff0000, v112
	v_pk_add_f32 v[50:51], v[34:35], v[50:51]
	v_mul_f32_e32 v34, v45, v45
	v_mul_f32_e32 v35, v47, v47
	v_pk_add_f32 v[36:37], v[36:37], v[48:49]
	v_lshlrev_b32_e32 v48, 16, v114
	v_and_b32_e32 v49, 0xffff0000, v114
	v_fmac_f32_e32 v34, v44, v44
	v_fmac_f32_e32 v35, v46, v46
	v_pk_add_f32 v[48:49], v[32:33], v[48:49]
	v_cvt_pk_bf16_f32 v32, v44, v45
	v_add_f32_e32 v34, v34, v35
	v_mul_f32_e32 v35, v41, v41
	v_mul_f32_e32 v44, v43, v43
	v_fmac_f32_e32 v35, v40, v40
	v_fmac_f32_e32 v44, v42, v42
	v_add_f32_e32 v35, v35, v44
	v_add_f32_e32 v34, v34, v35
	v_mul_f32_e32 v35, v37, v37
	v_mul_f32_e32 v44, v39, v39
	v_fmac_f32_e32 v35, v36, v36
	v_fmac_f32_e32 v44, v38, v38
	v_add_f32_e32 v35, v35, v44
	v_mul_f32_e32 v44, v49, v49
	v_mul_f32_e32 v45, v51, v51
	v_fmac_f32_e32 v44, v48, v48
	v_fmac_f32_e32 v45, v50, v50
	v_add_f32_e32 v44, v44, v45
	v_add_f32_e32 v35, v35, v44
	v_add_f32_e32 v44, v34, v35
	ds_bpermute_b32 v45, v192, v44
	v_cvt_pk_bf16_f32 v33, v46, v47
	v_cvt_pk_bf16_f32 v34, v40, v41
	v_cvt_pk_bf16_f32 v35, v42, v43
	global_store_dwordx4 v[120:121], v[32:35], off sc1
	s_waitcnt lgkmcnt(0)
	s_nop 0
	v_add_f32_e32 v32, v44, v45
	ds_bpermute_b32 v33, v179, v32
	v_cvt_pk_bf16_f32 v34, v36, v37
	v_cvt_pk_bf16_f32 v35, v38, v39
	v_cvt_pk_bf16_f32 v36, v48, v49
	v_cvt_pk_bf16_f32 v37, v50, v51
	global_store_dwordx4 v[120:121], v[34:37], off offset:64 sc1
	s_and_saveexec_b64 s[18:19], s[4:5]
	s_cbranch_execz .LBB0_1141
	s_add_u32 s26, s48, s25
	s_addc_u32 s27, s49, s24
	s_waitcnt lgkmcnt(0)
	v_add_f32_e32 v34, v32, v33
	v_lshl_add_u64 v[32:33], v[170:171], 2, s[26:27]
	global_store_dword v[32:33], v34, off offset:576
.LBB0_1141:
	s_or_b64 exec, exec, s[18:19]
	s_waitcnt vmcnt(11)
	v_lshlrev_b32_e32 v34, 16, v101
	v_and_b32_e32 v35, 0xffff0000, v101
	v_pk_add_f32 v[30:31], v[30:31], v[34:35]
	v_lshlrev_b32_e32 v34, 16, v103
	v_and_b32_e32 v35, 0xffff0000, v103
	v_lshlrev_b32_e32 v32, 16, v100
	s_waitcnt lgkmcnt(0)
	v_and_b32_e32 v33, 0xffff0000, v100
	v_pk_add_f32 v[26:27], v[26:27], v[34:35]
	s_waitcnt vmcnt(10)
	v_lshlrev_b32_e32 v34, 16, v97
	v_and_b32_e32 v35, 0xffff0000, v97
	v_pk_add_f32 v[28:29], v[28:29], v[32:33]
	v_lshlrev_b32_e32 v32, 16, v102
	v_and_b32_e32 v33, 0xffff0000, v102
	v_pk_add_f32 v[22:23], v[22:23], v[34:35]
	v_lshlrev_b32_e32 v34, 16, v99
	v_and_b32_e32 v35, 0xffff0000, v99
	v_pk_add_f32 v[24:25], v[24:25], v[32:33]
	v_lshlrev_b32_e32 v32, 16, v96
	v_and_b32_e32 v33, 0xffff0000, v96
	v_pk_add_f32 v[34:35], v[18:19], v[34:35]
	v_mul_f32_e32 v18, v29, v29
	v_mul_f32_e32 v19, v31, v31
	v_pk_add_f32 v[20:21], v[20:21], v[32:33]
	v_lshlrev_b32_e32 v32, 16, v98
	v_and_b32_e32 v33, 0xffff0000, v98
	v_fmac_f32_e32 v18, v28, v28
	v_fmac_f32_e32 v19, v30, v30
	v_pk_add_f32 v[32:33], v[16:17], v[32:33]
	v_cvt_pk_bf16_f32 v16, v28, v29
	v_add_f32_e32 v18, v18, v19
	v_mul_f32_e32 v19, v25, v25
	v_mul_f32_e32 v28, v27, v27
	v_fmac_f32_e32 v19, v24, v24
	v_fmac_f32_e32 v28, v26, v26
	v_add_f32_e32 v19, v19, v28
	v_add_f32_e32 v18, v18, v19
	v_mul_f32_e32 v19, v21, v21
	v_mul_f32_e32 v28, v23, v23
	v_fmac_f32_e32 v19, v20, v20
	v_fmac_f32_e32 v28, v22, v22
	v_add_f32_e32 v19, v19, v28
	v_mul_f32_e32 v28, v33, v33
	v_mul_f32_e32 v29, v35, v35
	v_fmac_f32_e32 v28, v32, v32
	v_fmac_f32_e32 v29, v34, v34
	v_add_f32_e32 v28, v28, v29
	v_add_f32_e32 v19, v19, v28
	v_add_f32_e32 v28, v18, v19
	ds_bpermute_b32 v29, v192, v28
	v_cvt_pk_bf16_f32 v17, v30, v31
	v_cvt_pk_bf16_f32 v18, v24, v25
	v_cvt_pk_bf16_f32 v19, v26, v27
	global_store_dwordx4 v[104:105], v[16:19], off sc1
	s_waitcnt lgkmcnt(0)
	s_nop 0
	v_add_f32_e32 v16, v28, v29
	ds_bpermute_b32 v17, v179, v16
	v_cvt_pk_bf16_f32 v18, v20, v21
	v_cvt_pk_bf16_f32 v19, v22, v23
	v_cvt_pk_bf16_f32 v20, v32, v33
	v_cvt_pk_bf16_f32 v21, v34, v35
	global_store_dwordx4 v[104:105], v[18:21], off offset:64 sc1
	s_and_saveexec_b64 s[18:19], s[4:5]
	s_cbranch_execz .LBB0_1143
	s_add_u32 s26, s48, s25
	s_addc_u32 s27, s49, s24
	s_waitcnt lgkmcnt(0)
	v_add_f32_e32 v18, v16, v17
	v_lshl_add_u64 v[16:17], v[170:171], 2, s[26:27]
	global_store_dword v[16:17], v18, off offset:640
.LBB0_1143:
	s_or_b64 exec, exec, s[18:19]
	s_waitcnt vmcnt(9)
	v_lshlrev_b32_e32 v18, 16, v85
	v_and_b32_e32 v19, 0xffff0000, v85
	v_pk_add_f32 v[14:15], v[14:15], v[18:19]
	v_lshlrev_b32_e32 v18, 16, v87
	v_and_b32_e32 v19, 0xffff0000, v87
	v_lshlrev_b32_e32 v16, 16, v84
	s_waitcnt lgkmcnt(0)
	v_and_b32_e32 v17, 0xffff0000, v84
	v_pk_add_f32 v[10:11], v[10:11], v[18:19]
	s_waitcnt vmcnt(8)
	v_lshlrev_b32_e32 v18, 16, v81
	v_and_b32_e32 v19, 0xffff0000, v81
	v_pk_add_f32 v[12:13], v[12:13], v[16:17]
	v_lshlrev_b32_e32 v16, 16, v86
	v_and_b32_e32 v17, 0xffff0000, v86
	v_pk_add_f32 v[6:7], v[6:7], v[18:19]
	v_lshlrev_b32_e32 v18, 16, v83
	v_and_b32_e32 v19, 0xffff0000, v83
	v_pk_add_f32 v[8:9], v[8:9], v[16:17]
	v_lshlrev_b32_e32 v16, 16, v80
	v_and_b32_e32 v17, 0xffff0000, v80
	v_pk_add_f32 v[18:19], v[2:3], v[18:19]
	v_mul_f32_e32 v2, v13, v13
	v_mul_f32_e32 v3, v15, v15
	v_pk_add_f32 v[4:5], v[4:5], v[16:17]
	v_lshlrev_b32_e32 v16, 16, v82
	v_and_b32_e32 v17, 0xffff0000, v82
	v_fmac_f32_e32 v2, v12, v12
	v_fmac_f32_e32 v3, v14, v14
	v_pk_add_f32 v[16:17], v[0:1], v[16:17]
	v_cvt_pk_bf16_f32 v0, v12, v13
	v_add_f32_e32 v2, v2, v3
	v_mul_f32_e32 v3, v9, v9
	v_mul_f32_e32 v12, v11, v11
	v_fmac_f32_e32 v3, v8, v8
	v_fmac_f32_e32 v12, v10, v10
	v_add_f32_e32 v3, v3, v12
	v_add_f32_e32 v2, v2, v3
	v_mul_f32_e32 v3, v5, v5
	v_mul_f32_e32 v12, v7, v7
	v_fmac_f32_e32 v3, v4, v4
	v_fmac_f32_e32 v12, v6, v6
	v_add_f32_e32 v3, v3, v12
	v_mul_f32_e32 v12, v17, v17
	v_mul_f32_e32 v13, v19, v19
	v_fmac_f32_e32 v12, v16, v16
	v_fmac_f32_e32 v13, v18, v18
	v_add_f32_e32 v12, v12, v13
	v_add_f32_e32 v3, v3, v12
	v_add_f32_e32 v12, v2, v3
	ds_bpermute_b32 v13, v192, v12
	v_cvt_pk_bf16_f32 v1, v14, v15
	v_cvt_pk_bf16_f32 v2, v8, v9
	v_cvt_pk_bf16_f32 v3, v10, v11
	global_store_dwordx4 v[88:89], v[0:3], off sc1
	s_waitcnt lgkmcnt(0)
	s_nop 0
	v_add_f32_e32 v0, v12, v13
	ds_bpermute_b32 v1, v179, v0
	v_cvt_pk_bf16_f32 v2, v4, v5
	v_cvt_pk_bf16_f32 v3, v6, v7
	v_cvt_pk_bf16_f32 v4, v16, v17
	v_cvt_pk_bf16_f32 v5, v18, v19
	global_store_dwordx4 v[88:89], v[2:5], off offset:64 sc1
	s_and_saveexec_b64 s[18:19], s[4:5]
	s_cbranch_execz .LBB0_1122
	s_add_u32 s26, s48, s25
	s_addc_u32 s27, s49, s24
	s_waitcnt lgkmcnt(0)
	v_add_f32_e32 v2, v0, v1
	v_lshl_add_u64 v[0:1], v[170:171], 2, s[26:27]
	global_store_dword v[0:1], v2, off offset:704
	s_branch .LBB0_1122

.LBB0_1243:
	ds_read_b128 v[170:173], v162
	ds_read_b128 v[174:177], v162 offset:1024
	ds_read_b128 v[178:181], v162 offset:2048
	ds_read_b128 v[182:185], v162 offset:3072
	s_add_u32 s34, s30, 0xfffc0080
	s_addc_u32 s35, s31, -1
	s_cmp_eq_u32 s41, 12
	s_cselect_b32 s37, s11, s35
	s_cselect_b32 s36, s17, s34
	s_cselect_b32 s35, s29, s40
	s_cselect_b32 s34, s38, s39
	v_lshl_add_u64 v[144:145], s[30:31], 0, v[134:135]
	s_add_i32 m0, s48, 0xc000
	ds_read_b128 v[186:189], v163
	ds_read_b128 v[190:193], v163 offset:1024
	ds_read_b128 v[194:197], v163 offset:2048
	ds_read_b128 v[198:201], v163 offset:3072
	ds_read_b128 v[204:207], v163 offset:4096
	ds_read_b128 v[208:211], v163 offset:5120
	ds_read_b128 v[212:215], v163 offset:6144
	ds_read_b128 v[216:219], v163 offset:7168
	global_load_lds_dwordx4 v[144:145], off
	v_lshl_add_u64 v[144:145], s[30:31], 0, v[136:137]
	s_add_i32 m0, s48, 0xe000
	s_nop 0
	global_load_lds_dwordx4 v[144:145], off
	ds_read_b128 v[220:223], v164
	ds_read_b128 v[224:227], v164 offset:1024
	ds_read_b128 v[228:231], v164 offset:2048
	ds_read_b128 v[232:235], v164 offset:3072
	s_waitcnt lgkmcnt(0)
	s_waitcnt vmcnt(8)
	s_barrier
	s_setprio 1
	v_mfma_f32_16x16x32_bf16 v[124:127], v[170:173], v[186:189], v[124:127]
	v_mfma_f32_16x16x32_bf16 v[120:123], v[178:181], v[186:189], v[120:123]
	v_mfma_f32_16x16x32_bf16 v[112:115], v[170:173], v[194:197], v[112:115]
	v_mfma_f32_16x16x32_bf16 v[104:107], v[178:181], v[194:197], v[104:107]
	v_mfma_f32_16x16x32_bf16 v[96:99], v[170:173], v[204:207], v[96:99]
	v_mfma_f32_16x16x32_bf16 v[88:91], v[178:181], v[204:207], v[88:91]
	v_mfma_f32_16x16x32_bf16 v[80:83], v[170:173], v[212:215], v[80:83]
	v_mfma_f32_16x16x32_bf16 v[72:75], v[178:181], v[212:215], v[72:75]
	v_mfma_f32_16x16x32_bf16 v[124:127], v[174:177], v[190:193], v[124:127]
	v_mfma_f32_16x16x32_bf16 v[120:123], v[182:185], v[190:193], v[120:123]
	v_mfma_f32_16x16x32_bf16 v[112:115], v[174:177], v[198:201], v[112:115]
	v_mfma_f32_16x16x32_bf16 v[104:107], v[182:185], v[198:201], v[104:107]
	v_mfma_f32_16x16x32_bf16 v[96:99], v[174:177], v[208:211], v[96:99]
	v_mfma_f32_16x16x32_bf16 v[88:91], v[182:185], v[208:211], v[88:91]
	v_mfma_f32_16x16x32_bf16 v[80:83], v[174:177], v[216:219], v[80:83]
	v_mfma_f32_16x16x32_bf16 v[72:75], v[182:185], v[216:219], v[72:75]
	v_mfma_f32_16x16x32_bf16 v[116:119], v[220:223], v[186:189], v[116:119]
	v_mfma_f32_16x16x32_bf16 v[108:111], v[228:231], v[186:189], v[108:111]
	v_mfma_f32_16x16x32_bf16 v[100:103], v[220:223], v[194:197], v[100:103]
	v_mfma_f32_16x16x32_bf16 v[92:95], v[228:231], v[194:197], v[92:95]
	v_mfma_f32_16x16x32_bf16 v[84:87], v[220:223], v[204:207], v[84:87]
	v_mfma_f32_16x16x32_bf16 v[76:79], v[228:231], v[204:207], v[76:79]
	v_mfma_f32_16x16x32_bf16 v[68:71], v[220:223], v[212:215], v[68:71]
	v_mfma_f32_16x16x32_bf16 v[64:67], v[228:231], v[212:215], v[64:67]
	v_mfma_f32_16x16x32_bf16 v[116:119], v[224:227], v[190:193], v[116:119]
	v_mfma_f32_16x16x32_bf16 v[108:111], v[232:235], v[190:193], v[108:111]
	v_mfma_f32_16x16x32_bf16 v[100:103], v[224:227], v[198:201], v[100:103]
	v_mfma_f32_16x16x32_bf16 v[92:95], v[232:235], v[198:201], v[92:95]
	v_mfma_f32_16x16x32_bf16 v[84:87], v[224:227], v[208:211], v[84:87]
	v_mfma_f32_16x16x32_bf16 v[76:79], v[232:235], v[208:211], v[76:79]
	v_mfma_f32_16x16x32_bf16 v[68:71], v[224:227], v[216:219], v[68:71]
	v_mfma_f32_16x16x32_bf16 v[64:67], v[232:235], v[216:219], v[64:67]
	s_setprio 0
	s_barrier
	ds_read_b128 v[186:189], v163 offset:16384
	ds_read_b128 v[190:193], v163 offset:17408
	ds_read_b128 v[194:197], v163 offset:18432
	ds_read_b128 v[198:201], v163 offset:19456
	ds_read_b128 v[204:207], v163 offset:20480
	ds_read_b128 v[208:211], v163 offset:21504
	ds_read_b128 v[212:215], v163 offset:22528
	ds_read_b128 v[216:219], v163 offset:23552
	s_mov_b32 m0, s46
	v_lshl_add_u64 v[144:145], s[34:35], 0, v[128:129]
	global_load_lds_dwordx4 v[144:145], off
	v_lshl_add_u64 v[236:237], s[34:35], 0, v[130:131]
	s_mov_b32 m0, s47
	s_nop 0
	global_load_lds_dwordx4 v[236:237], off
	s_mov_b32 m0, s48
	v_lshl_add_u64 v[238:239], s[36:37], 0, v[128:129]
	global_load_lds_dwordx4 v[238:239], off
	v_lshl_add_u64 v[240:241], s[36:37], 0, v[130:131]
	s_mov_b32 m0, s49
	s_nop 0
	global_load_lds_dwordx4 v[240:241], off
	s_add_u32 s72, s34, 0x40000
	s_addc_u32 s73, s35, 0
	s_mov_b32 m0, s50
	v_lshl_add_u64 v[248:249], s[72:73], 0, v[128:129]
	global_load_lds_dwordx4 v[248:249], off
	v_lshl_add_u64 v[248:249], s[72:73], 0, v[130:131]
	s_mov_b32 m0, s51
	s_nop 0
	global_load_lds_dwordx4 v[248:249], off
	s_waitcnt lgkmcnt(0)
	s_waitcnt vmcnt(8)
	s_barrier
	s_setprio 1
	v_mfma_f32_16x16x32_bf16 v[60:63], v[170:173], v[186:189], v[60:63]
	v_mfma_f32_16x16x32_bf16 v[56:59], v[178:181], v[186:189], v[56:59]
	v_mfma_f32_16x16x32_bf16 v[48:51], v[170:173], v[194:197], v[48:51]
	v_mfma_f32_16x16x32_bf16 v[40:43], v[178:181], v[194:197], v[40:43]
	v_mfma_f32_16x16x32_bf16 v[32:35], v[170:173], v[204:207], v[32:35]
	v_mfma_f32_16x16x32_bf16 v[24:27], v[178:181], v[204:207], v[24:27]
	v_mfma_f32_16x16x32_bf16 v[16:19], v[170:173], v[212:215], v[16:19]
	v_mfma_f32_16x16x32_bf16 v[8:11], v[178:181], v[212:215], v[8:11]
	v_mfma_f32_16x16x32_bf16 v[60:63], v[174:177], v[190:193], v[60:63]
	v_mfma_f32_16x16x32_bf16 v[56:59], v[182:185], v[190:193], v[56:59]
	v_mfma_f32_16x16x32_bf16 v[48:51], v[174:177], v[198:201], v[48:51]
	v_mfma_f32_16x16x32_bf16 v[40:43], v[182:185], v[198:201], v[40:43]
	v_mfma_f32_16x16x32_bf16 v[32:35], v[174:177], v[208:211], v[32:35]
	v_mfma_f32_16x16x32_bf16 v[24:27], v[182:185], v[208:211], v[24:27]
	v_mfma_f32_16x16x32_bf16 v[16:19], v[174:177], v[216:219], v[16:19]
	v_mfma_f32_16x16x32_bf16 v[8:11], v[182:185], v[216:219], v[8:11]
	v_mfma_f32_16x16x32_bf16 v[52:55], v[220:223], v[186:189], v[52:55]
	v_mfma_f32_16x16x32_bf16 v[44:47], v[228:231], v[186:189], v[44:47]
	v_mfma_f32_16x16x32_bf16 v[36:39], v[220:223], v[194:197], v[36:39]
	v_mfma_f32_16x16x32_bf16 v[28:31], v[228:231], v[194:197], v[28:31]
	v_mfma_f32_16x16x32_bf16 v[20:23], v[220:223], v[204:207], v[20:23]
	v_mfma_f32_16x16x32_bf16 v[12:15], v[228:231], v[204:207], v[12:15]
	v_mfma_f32_16x16x32_bf16 v[4:7], v[220:223], v[212:215], v[4:7]
	v_mfma_f32_16x16x32_bf16 v[0:3], v[228:231], v[212:215], v[0:3]
	v_mfma_f32_16x16x32_bf16 v[52:55], v[224:227], v[190:193], v[52:55]
	v_mfma_f32_16x16x32_bf16 v[44:47], v[232:235], v[190:193], v[44:47]
	v_mfma_f32_16x16x32_bf16 v[36:39], v[224:227], v[198:201], v[36:39]
	v_mfma_f32_16x16x32_bf16 v[28:31], v[232:235], v[198:201], v[28:31]
	v_mfma_f32_16x16x32_bf16 v[20:23], v[224:227], v[208:211], v[20:23]
	v_mfma_f32_16x16x32_bf16 v[12:15], v[232:235], v[208:211], v[12:15]
	v_mfma_f32_16x16x32_bf16 v[4:7], v[224:227], v[216:219], v[4:7]
	v_mfma_f32_16x16x32_bf16 v[0:3], v[232:235], v[216:219], v[0:3]
	s_setprio 0
	s_barrier
	ds_read_b128 v[170:173], v165
	ds_read_b128 v[174:177], v165 offset:1024
	ds_read_b128 v[178:181], v165 offset:2048
	ds_read_b128 v[182:185], v165 offset:3072
	s_add_u32 s36, s36, 0x40000
	s_addc_u32 s37, s37, 0
	s_mov_b32 m0, s52
	v_lshl_add_u64 v[220:221], s[36:37], 0, v[128:129]
	ds_read_b128 v[186:189], v163 offset:32768
	ds_read_b128 v[190:193], v163 offset:33792
	ds_read_b128 v[194:197], v163 offset:34816
	ds_read_b128 v[198:201], v163 offset:35840
	ds_read_b128 v[204:207], v163 offset:36864
	ds_read_b128 v[208:211], v163 offset:37888
	ds_read_b128 v[212:215], v163 offset:38912
	ds_read_b128 v[216:219], v163 offset:39936
	global_load_lds_dwordx4 v[220:221], off
	v_lshl_add_u64 v[220:221], s[36:37], 0, v[130:131]
	s_mov_b32 m0, s53
	s_nop 0
	global_load_lds_dwordx4 v[220:221], off
	ds_read_b128 v[220:223], v166
	ds_read_b128 v[224:227], v166 offset:1024
	ds_read_b128 v[228:231], v166 offset:2048
	ds_read_b128 v[232:235], v166 offset:3072
	s_waitcnt lgkmcnt(0)
	s_waitcnt vmcnt(8)
	s_barrier
	s_setprio 1
	v_mfma_f32_16x16x32_bf16 v[124:127], v[170:173], v[186:189], v[124:127]
	v_mfma_f32_16x16x32_bf16 v[120:123], v[178:181], v[186:189], v[120:123]
	v_mfma_f32_16x16x32_bf16 v[112:115], v[170:173], v[194:197], v[112:115]
	v_mfma_f32_16x16x32_bf16 v[104:107], v[178:181], v[194:197], v[104:107]
	v_mfma_f32_16x16x32_bf16 v[96:99], v[170:173], v[204:207], v[96:99]
	v_mfma_f32_16x16x32_bf16 v[88:91], v[178:181], v[204:207], v[88:91]
	v_mfma_f32_16x16x32_bf16 v[80:83], v[170:173], v[212:215], v[80:83]
	v_mfma_f32_16x16x32_bf16 v[72:75], v[178:181], v[212:215], v[72:75]
	v_mfma_f32_16x16x32_bf16 v[124:127], v[174:177], v[190:193], v[124:127]
	v_mfma_f32_16x16x32_bf16 v[120:123], v[182:185], v[190:193], v[120:123]
	v_mfma_f32_16x16x32_bf16 v[112:115], v[174:177], v[198:201], v[112:115]
	v_mfma_f32_16x16x32_bf16 v[104:107], v[182:185], v[198:201], v[104:107]
	v_mfma_f32_16x16x32_bf16 v[96:99], v[174:177], v[208:211], v[96:99]
	v_mfma_f32_16x16x32_bf16 v[88:91], v[182:185], v[208:211], v[88:91]
	v_mfma_f32_16x16x32_bf16 v[80:83], v[174:177], v[216:219], v[80:83]
	v_mfma_f32_16x16x32_bf16 v[72:75], v[182:185], v[216:219], v[72:75]
	v_mfma_f32_16x16x32_bf16 v[116:119], v[220:223], v[186:189], v[116:119]
	v_mfma_f32_16x16x32_bf16 v[108:111], v[228:231], v[186:189], v[108:111]
	v_mfma_f32_16x16x32_bf16 v[100:103], v[220:223], v[194:197], v[100:103]
	v_mfma_f32_16x16x32_bf16 v[92:95], v[228:231], v[194:197], v[92:95]
	v_mfma_f32_16x16x32_bf16 v[84:87], v[220:223], v[204:207], v[84:87]
	v_mfma_f32_16x16x32_bf16 v[76:79], v[228:231], v[204:207], v[76:79]
	v_mfma_f32_16x16x32_bf16 v[68:71], v[220:223], v[212:215], v[68:71]
	v_mfma_f32_16x16x32_bf16 v[64:67], v[228:231], v[212:215], v[64:67]
	v_mfma_f32_16x16x32_bf16 v[116:119], v[224:227], v[190:193], v[116:119]
	v_mfma_f32_16x16x32_bf16 v[108:111], v[232:235], v[190:193], v[108:111]
	v_mfma_f32_16x16x32_bf16 v[100:103], v[224:227], v[198:201], v[100:103]
	v_mfma_f32_16x16x32_bf16 v[92:95], v[232:235], v[198:201], v[92:95]
	v_mfma_f32_16x16x32_bf16 v[84:87], v[224:227], v[208:211], v[84:87]
	v_mfma_f32_16x16x32_bf16 v[76:79], v[232:235], v[208:211], v[76:79]
	v_mfma_f32_16x16x32_bf16 v[68:71], v[224:227], v[216:219], v[68:71]
	v_mfma_f32_16x16x32_bf16 v[64:67], v[232:235], v[216:219], v[64:67]
	s_setprio 0
	s_barrier
	ds_read_b128 v[186:189], v163 offset:49152
	ds_read_b128 v[190:193], v163 offset:50176
	ds_read_b128 v[194:197], v163 offset:51200
	ds_read_b128 v[198:201], v163 offset:52224
	ds_read_b128 v[204:207], v163 offset:53248
	ds_read_b128 v[208:211], v163 offset:54272
	ds_read_b128 v[212:215], v163 offset:55296
	ds_read_b128 v[216:219], v163 offset:56320
	s_mov_b32 m0, s54
	v_lshl_add_u64 v[144:145], v[144:145], 0, s[12:13]
	global_load_lds_dwordx4 v[144:145], off
	v_lshl_add_u64 v[144:145], v[236:237], 0, s[12:13]
	s_mov_b32 m0, s55
	s_nop 0
	global_load_lds_dwordx4 v[144:145], off
	s_mov_b32 m0, s56
	v_lshl_add_u64 v[144:145], v[238:239], 0, s[12:13]
	global_load_lds_dwordx4 v[144:145], off
	v_lshl_add_u64 v[144:145], v[240:241], 0, s[12:13]
	s_mov_b32 m0, s57
	s_nop 0
	global_load_lds_dwordx4 v[144:145], off
	s_add_u32 s34, s34, 0x40080
	s_addc_u32 s35, s35, 0
	s_mov_b32 m0, s58
	v_lshl_add_u64 v[144:145], s[34:35], 0, v[128:129]
	global_load_lds_dwordx4 v[144:145], off
	v_lshl_add_u64 v[144:145], s[34:35], 0, v[130:131]
	s_mov_b32 m0, s59
	s_nop 0
	global_load_lds_dwordx4 v[144:145], off
	s_waitcnt lgkmcnt(0)
	s_waitcnt vmcnt(8)
	s_barrier
	s_setprio 1
	v_mfma_f32_16x16x32_bf16 v[60:63], v[170:173], v[186:189], v[60:63]
	v_mfma_f32_16x16x32_bf16 v[56:59], v[178:181], v[186:189], v[56:59]
	v_mfma_f32_16x16x32_bf16 v[48:51], v[170:173], v[194:197], v[48:51]
	v_mfma_f32_16x16x32_bf16 v[40:43], v[178:181], v[194:197], v[40:43]
	v_mfma_f32_16x16x32_bf16 v[32:35], v[170:173], v[204:207], v[32:35]
	v_mfma_f32_16x16x32_bf16 v[24:27], v[178:181], v[204:207], v[24:27]
	v_mfma_f32_16x16x32_bf16 v[16:19], v[170:173], v[212:215], v[16:19]
	v_mfma_f32_16x16x32_bf16 v[8:11], v[178:181], v[212:215], v[8:11]
	v_mfma_f32_16x16x32_bf16 v[60:63], v[174:177], v[190:193], v[60:63]
	v_mfma_f32_16x16x32_bf16 v[56:59], v[182:185], v[190:193], v[56:59]
	v_mfma_f32_16x16x32_bf16 v[48:51], v[174:177], v[198:201], v[48:51]
	v_mfma_f32_16x16x32_bf16 v[40:43], v[182:185], v[198:201], v[40:43]
	v_mfma_f32_16x16x32_bf16 v[32:35], v[174:177], v[208:211], v[32:35]
	v_mfma_f32_16x16x32_bf16 v[24:27], v[182:185], v[208:211], v[24:27]
	v_mfma_f32_16x16x32_bf16 v[16:19], v[174:177], v[216:219], v[16:19]
	v_mfma_f32_16x16x32_bf16 v[8:11], v[182:185], v[216:219], v[8:11]
	v_mfma_f32_16x16x32_bf16 v[52:55], v[220:223], v[186:189], v[52:55]
	v_mfma_f32_16x16x32_bf16 v[44:47], v[228:231], v[186:189], v[44:47]
	v_mfma_f32_16x16x32_bf16 v[36:39], v[220:223], v[194:197], v[36:39]
	v_mfma_f32_16x16x32_bf16 v[28:31], v[228:231], v[194:197], v[28:31]
	v_mfma_f32_16x16x32_bf16 v[20:23], v[220:223], v[204:207], v[20:23]
	v_mfma_f32_16x16x32_bf16 v[12:15], v[228:231], v[204:207], v[12:15]
	v_mfma_f32_16x16x32_bf16 v[4:7], v[220:223], v[212:215], v[4:7]
	v_mfma_f32_16x16x32_bf16 v[0:3], v[228:231], v[212:215], v[0:3]
	v_mfma_f32_16x16x32_bf16 v[52:55], v[224:227], v[190:193], v[52:55]
	v_mfma_f32_16x16x32_bf16 v[44:47], v[232:235], v[190:193], v[44:47]
	v_mfma_f32_16x16x32_bf16 v[36:39], v[224:227], v[198:201], v[36:39]
	v_mfma_f32_16x16x32_bf16 v[28:31], v[232:235], v[198:201], v[28:31]
	v_mfma_f32_16x16x32_bf16 v[20:23], v[224:227], v[208:211], v[20:23]
	v_mfma_f32_16x16x32_bf16 v[12:15], v[232:235], v[208:211], v[12:15]
	v_mfma_f32_16x16x32_bf16 v[4:7], v[224:227], v[216:219], v[4:7]
	v_mfma_f32_16x16x32_bf16 v[0:3], v[232:235], v[216:219], v[0:3]
	s_setprio 0
	s_add_i32 s41, s41, 2
	s_add_u32 s30, s30, 0x100
	s_addc_u32 s31, s31, 0
	s_add_u32 s39, s39, 0x100
	s_addc_u32 s40, s40, 0
	s_cmp_gt_u32 s41, 13
	s_barrier
	s_cbranch_scc0 .LBB0_1243
	v_lshl_add_u32 v144, s42, 8, v160
	v_ashrrev_i32_e32 v145, 31, v144
	v_lshl_add_u64 v[170:171], v[144:145], 2, v[132:133]
	v_add_co_u32_e32 v172, vcc, s60, v170
	v_and_b32_e32 v145, 64, v167
	s_nop 0
	v_addc_co_u32_e32 v173, vcc, 0, v171, vcc
	v_add_co_u32_e32 v174, vcc, s66, v170
	v_xor_b32_e32 v146, 16, v167
	s_nop 0
	v_addc_co_u32_e32 v175, vcc, 0, v171, vcc
	v_add_co_u32_e32 v176, vcc, s67, v170
	v_add_u32_e32 v150, 64, v145
	s_nop 0
	v_addc_co_u32_e32 v177, vcc, 0, v171, vcc
	global_load_dword v178, v[172:173], off
	global_load_dword v180, v[172:173], off offset:64
	global_load_dword v182, v[172:173], off offset:128
	global_load_dword v184, v[172:173], off offset:192
	global_load_dword v186, v[172:173], off offset:512
	global_load_dword v188, v[172:173], off offset:576
	global_load_dword v191, v[174:175], off
	global_load_dword v193, v[174:175], off offset:64
	global_load_dword v195, v[174:175], off offset:128
	global_load_dword v197, v[174:175], off offset:192
	global_load_dword v199, v[174:175], off offset:512
	global_load_dword v201, v[174:175], off offset:576
	global_load_dword v179, v[176:177], off
	global_load_dword v181, v[176:177], off offset:64
	global_load_dword v183, v[176:177], off offset:128
	global_load_dword v185, v[176:177], off offset:192
	global_load_dword v187, v[176:177], off offset:512
	global_load_dword v189, v[176:177], off offset:576
	global_load_dword v190, v[170:171], off
	global_load_dword v192, v[170:171], off offset:64
	global_load_dword v194, v[170:171], off offset:128
	global_load_dword v196, v[170:171], off offset:192
	global_load_dword v198, v[170:171], off offset:512
	global_load_dword v200, v[170:171], off offset:576
	global_load_dword v204, v[170:171], off offset:640
	s_nop 0
	global_load_dword v170, v[170:171], off offset:704
	s_nop 0
	global_load_dword v205, v[174:175], off offset:640
	global_load_dword v207, v[176:177], off offset:640
	global_load_dword v206, v[172:173], off offset:640
	s_nop 0
	global_load_dword v172, v[172:173], off offset:704
	s_nop 0
	global_load_dword v171, v[174:175], off offset:704
	global_load_dword v173, v[176:177], off offset:704
	v_cmp_lt_i32_e32 vcc, v146, v150
	v_xor_b32_e32 v148, 32, v167
	v_add_u32_e32 v145, 0x80, v144
	v_cndmask_b32_e32 v146, v167, v146, vcc
	v_cmp_lt_i32_e32 vcc, v148, v150
	v_lshlrev_b32_e32 v146, 2, v146
	s_cmpk_lt_i32 s42, 0x80
	v_cndmask_b32_e32 v148, v167, v148, vcc
	v_lshlrev_b32_e32 v148, 2, v148
	s_waitcnt vmcnt(0)
	v_pk_add_f32 v[174:175], v[190:191], v[178:179]
	v_pk_add_f32 v[176:177], v[192:193], v[180:181]
	v_pk_add_f32 v[178:179], v[194:195], v[182:183]
	v_pk_add_f32 v[180:181], v[196:197], v[184:185]
	v_pk_add_f32 v[182:183], v[198:199], v[186:187]
	v_add_f32_e32 v150, v174, v175
	v_add_f32_e32 v152, v176, v177
	v_add_f32_e32 v154, v178, v179
	v_add_f32_e32 v156, v180, v181
	v_add_f32_e32 v169, v182, v183
	ds_bpermute_b32 v174, v146, v150
	ds_bpermute_b32 v176, v146, v152
	ds_bpermute_b32 v177, v146, v154
	ds_bpermute_b32 v178, v146, v156
	ds_bpermute_b32 v179, v146, v169
	s_waitcnt lgkmcnt(0)
	v_add_f32_e32 v150, v150, v174
	v_pk_add_f32 v[184:185], v[200:201], v[188:189]
	v_add_f32_e32 v152, v152, v176
	v_add_f32_e32 v154, v154, v177
	v_add_f32_e32 v156, v156, v178
	v_add_f32_e32 v169, v169, v179
	ds_bpermute_b32 v174, v148, v150
	v_add_f32_e32 v175, v184, v185
	ds_bpermute_b32 v176, v148, v152
	ds_bpermute_b32 v177, v148, v154
	ds_bpermute_b32 v178, v148, v156
	ds_bpermute_b32 v179, v148, v169
	ds_bpermute_b32 v180, v146, v175
	s_waitcnt lgkmcnt(5)
	v_add_f32_e32 v150, v150, v174
	s_waitcnt lgkmcnt(4)
	v_add_f32_e32 v152, v152, v176
	s_waitcnt lgkmcnt(3)
	v_add_f32_e32 v154, v154, v177
	s_waitcnt lgkmcnt(2)
	v_add_f32_e32 v156, v156, v178
	s_waitcnt lgkmcnt(1)
	v_add_f32_e32 v169, v169, v179
	v_fmamk_f32 v150, v150, 0x3a800000, v168
	v_pk_add_f32 v[178:179], v[204:205], v[206:207]
	v_fmamk_f32 v152, v152, 0x3a800000, v168
	v_fmamk_f32 v154, v154, 0x3a800000, v168
	v_fmamk_f32 v177, v156, 0x3a800000, v168
	v_fmamk_f32 v169, v169, 0x3a800000, v168
	v_rsq_f32_e32 v174, v150
	s_waitcnt lgkmcnt(0)
	v_add_f32_e32 v150, v175, v180
	v_add_f32_e32 v175, v178, v179
	v_rsq_f32_e32 v176, v152
	v_rsq_f32_e32 v156, v154
	v_rsq_f32_e32 v154, v177
	v_rsq_f32_e32 v152, v169
	ds_bpermute_b32 v169, v148, v150
	ds_bpermute_b32 v177, v146, v175
	v_pk_add_f32 v[170:171], v[170:171], v[172:173]
	v_pk_mul_f32 v[124:125], v[124:125], v[174:175] op_sel_hi:[1,0]
	v_add_f32_e32 v170, v170, v171
	ds_bpermute_b32 v146, v146, v170
	s_waitcnt lgkmcnt(2)
	v_add_f32_e32 v150, v150, v169
	s_waitcnt lgkmcnt(1)
	v_add_f32_e32 v169, v175, v177
	ds_bpermute_b32 v171, v148, v169
	v_mul_f32_e32 v172, 0xbfb8aa3b, v125
	s_waitcnt lgkmcnt(1)
	v_add_f32_e32 v146, v170, v146
	ds_bpermute_b32 v170, v148, v146
	v_exp_f32_e32 v173, v172
	s_waitcnt lgkmcnt(1)
	v_add_f32_e32 v148, v169, v171
	v_mul_f32_e32 v169, 0xbfb8aa3b, v124
	v_exp_f32_e32 v169, v169
	v_pk_mul_f32 v[126:127], v[126:127], v[174:175] op_sel_hi:[1,0]
	v_pk_mul_f32 v[118:119], v[118:119], v[174:175] op_sel_hi:[1,0]
	s_waitcnt lgkmcnt(0)
	v_add_f32_e32 v146, v146, v170
	v_add_f32_e32 v169, 1.0, v169
	v_rcp_f32_e32 v172, v169
	v_add_f32_e32 v169, 1.0, v173
	v_mul_f32_e32 v173, 0xbfb8aa3b, v126
	v_exp_f32_e32 v175, v173
	v_mul_f32_e32 v173, 0xbfb8aa3b, v127
	v_exp_f32_e32 v177, v173
	v_rcp_f32_e32 v173, v169
	v_add_f32_e32 v169, 1.0, v175
	v_rcp_f32_e32 v178, v169
	v_add_f32_e32 v169, 1.0, v177
	v_rcp_f32_e32 v179, v169
	v_pk_mul_f32 v[116:117], v[116:117], v[174:175] op_sel_hi:[1,0]
	v_pk_mul_f32 v[124:125], v[124:125], v[172:173]
	v_pk_mul_f32 v[120:121], v[120:121], v[174:175] op_sel_hi:[1,0]
	v_pk_mul_f32 v[116:117], v[116:117], v[124:125]
	v_pk_mul_f32 v[124:125], v[126:127], v[178:179]
	v_pk_mul_f32 v[122:123], v[122:123], v[174:175] op_sel_hi:[1,0]
	v_pk_mul_f32 v[118:119], v[118:119], v[124:125]
	v_mul_f32_e32 v124, 0xbfb8aa3b, v120
	v_mul_f32_e32 v125, 0xbfb8aa3b, v121
	v_exp_f32_e32 v124, v124
	v_exp_f32_e32 v125, v125
	v_mul_f32_e32 v126, 0xbfb8aa3b, v122
	v_mul_f32_e32 v127, 0xbfb8aa3b, v123
	v_exp_f32_e32 v126, v126
	v_exp_f32_e32 v127, v127
	v_add_f32_e32 v124, 1.0, v124
	v_add_f32_e32 v125, 1.0, v125
	v_rcp_f32_e32 v124, v124
	v_rcp_f32_e32 v125, v125
	v_add_f32_e32 v126, 1.0, v126
	v_add_f32_e32 v127, 1.0, v127
	v_rcp_f32_e32 v126, v126
	v_rcp_f32_e32 v127, v127
	v_pk_mul_f32 v[108:109], v[108:109], v[174:175] op_sel_hi:[1,0]
	v_pk_mul_f32 v[120:121], v[120:121], v[124:125]
	v_lshl_or_b32 v170, s28, 7, v161
	v_pk_mul_f32 v[110:111], v[110:111], v[174:175] op_sel_hi:[1,0]
	v_pk_mul_f32 v[108:109], v[108:109], v[120:121]
	v_pk_mul_f32 v[120:121], v[122:123], v[126:127]
	v_ashrrev_i32_e32 v171, 31, v170
	v_pk_mul_f32 v[110:111], v[110:111], v[120:121]
	v_cvt_pk_bf16_f32 v116, v116, v117
	v_cvt_pk_bf16_f32 v117, v118, v119
	v_cvt_pk_bf16_f32 v118, v108, v109
	v_mov_b64_e32 v[108:109], s[6:7]
	v_cvt_pk_bf16_f32 v119, v110, v111
	v_mad_i64_i32 v[120:121], s[28:29], v144, s68, v[108:109]
	v_lshlrev_b64 v[110:111], 1, v[170:171]
	v_lshl_add_u64 v[120:121], v[120:121], 0, v[110:111]
	v_pk_mul_f32 v[112:113], v[112:113], v[176:177] op_sel_hi:[1,0]
	global_store_dwordx4 v[120:121], v[116:119], off sc1
	v_pk_mul_f32 v[114:115], v[114:115], v[176:177] op_sel_hi:[1,0]
	v_pk_mul_f32 v[100:101], v[100:101], v[176:177] op_sel_hi:[1,0]
	v_mul_f32_e32 v116, 0xbfb8aa3b, v112
	v_mul_f32_e32 v117, 0xbfb8aa3b, v113
	v_exp_f32_e32 v116, v116
	v_exp_f32_e32 v117, v117
	v_mul_f32_e32 v118, 0xbfb8aa3b, v114
	v_mul_f32_e32 v119, 0xbfb8aa3b, v115
	v_exp_f32_e32 v118, v118
	v_exp_f32_e32 v119, v119
	v_add_f32_e32 v116, 1.0, v116
	v_add_f32_e32 v117, 1.0, v117
	v_rcp_f32_e32 v116, v116
	v_rcp_f32_e32 v117, v117
	v_add_f32_e32 v118, 1.0, v118
	v_add_f32_e32 v119, 1.0, v119
	v_rcp_f32_e32 v118, v118
	v_rcp_f32_e32 v119, v119
	v_pk_mul_f32 v[112:113], v[112:113], v[116:117]
	v_pk_mul_f32 v[102:103], v[102:103], v[176:177] op_sel_hi:[1,0]
	v_pk_mul_f32 v[100:101], v[100:101], v[112:113]
	v_pk_mul_f32 v[112:113], v[114:115], v[118:119]
	v_pk_mul_f32 v[104:105], v[104:105], v[176:177] op_sel_hi:[1,0]
	v_pk_mul_f32 v[102:103], v[102:103], v[112:113]
	v_pk_mul_f32 v[106:107], v[106:107], v[176:177] op_sel_hi:[1,0]
	v_mul_f32_e32 v112, 0xbfb8aa3b, v104
	v_mul_f32_e32 v113, 0xbfb8aa3b, v105
	v_exp_f32_e32 v112, v112
	v_exp_f32_e32 v113, v113
	v_mul_f32_e32 v114, 0xbfb8aa3b, v106
	v_mul_f32_e32 v115, 0xbfb8aa3b, v107
	v_exp_f32_e32 v114, v114
	v_exp_f32_e32 v115, v115
	v_add_f32_e32 v112, 1.0, v112
	v_add_f32_e32 v113, 1.0, v113
	v_rcp_f32_e32 v112, v112
	v_rcp_f32_e32 v113, v113
	v_add_f32_e32 v114, 1.0, v114
	v_add_f32_e32 v115, 1.0, v115
	v_rcp_f32_e32 v114, v114
	v_rcp_f32_e32 v115, v115
	v_pk_mul_f32 v[92:93], v[92:93], v[176:177] op_sel_hi:[1,0]
	v_pk_mul_f32 v[104:105], v[104:105], v[112:113]
	v_pk_mul_f32 v[94:95], v[94:95], v[176:177] op_sel_hi:[1,0]
	v_pk_mul_f32 v[104:105], v[92:93], v[104:105]
	v_pk_mul_f32 v[92:93], v[106:107], v[114:115]
	v_or_b32_e32 v112, 16, v144
	v_pk_mul_f32 v[106:107], v[94:95], v[92:93]
	v_cvt_pk_bf16_f32 v92, v100, v101
	v_mad_i64_i32 v[100:101], s[28:29], v112, s68, v[108:109]
	v_cvt_pk_bf16_f32 v93, v102, v103
	v_cvt_pk_bf16_f32 v94, v104, v105
	v_cvt_pk_bf16_f32 v95, v106, v107
	v_lshl_add_u64 v[100:101], v[100:101], 0, v[110:111]
	global_store_dwordx4 v[100:101], v[92:95], off sc1
	v_pk_mul_f32 v[86:87], v[86:87], v[156:157] op_sel_hi:[1,0]
	v_pk_mul_f32 v[88:89], v[88:89], v[156:157] op_sel_hi:[1,0]
	v_pk_mul_f32 v[92:93], v[98:99], v[156:157] op_sel_hi:[1,0]
	v_pk_mul_f32 v[94:95], v[96:97], v[156:157] op_sel_hi:[1,0]
	v_mul_f32_e32 v98, 0xbfb8aa3b, v92
	v_mul_f32_e32 v99, 0xbfb8aa3b, v93
	v_mul_f32_e32 v96, 0xbfb8aa3b, v94
	v_mul_f32_e32 v97, 0xbfb8aa3b, v95
	v_exp_f32_e32 v98, v98
	v_exp_f32_e32 v99, v99
	v_exp_f32_e32 v96, v96
	v_exp_f32_e32 v97, v97
	v_add_f32_e32 v98, 1.0, v98
	v_add_f32_e32 v99, 1.0, v99
	v_add_f32_e32 v96, 1.0, v96
	v_add_f32_e32 v97, 1.0, v97
	v_rcp_f32_e32 v98, v98
	v_rcp_f32_e32 v99, v99
	v_rcp_f32_e32 v96, v96
	v_rcp_f32_e32 v97, v97
	v_pk_mul_f32 v[84:85], v[84:85], v[156:157] op_sel_hi:[1,0]
	v_pk_mul_f32 v[92:93], v[92:93], v[98:99]
	v_pk_mul_f32 v[90:91], v[90:91], v[156:157] op_sel_hi:[1,0]
	v_pk_mul_f32 v[94:95], v[94:95], v[96:97]
	v_pk_mul_f32 v[86:87], v[86:87], v[92:93]
	v_mul_f32_e32 v92, 0xbfb8aa3b, v88
	v_mul_f32_e32 v93, 0xbfb8aa3b, v89
	v_pk_mul_f32 v[84:85], v[84:85], v[94:95]
	v_exp_f32_e32 v92, v92
	v_exp_f32_e32 v93, v93
	v_mul_f32_e32 v94, 0xbfb8aa3b, v90
	v_mul_f32_e32 v95, 0xbfb8aa3b, v91
	v_exp_f32_e32 v94, v94
	v_exp_f32_e32 v95, v95
	v_add_f32_e32 v92, 1.0, v92
	v_add_f32_e32 v93, 1.0, v93
	v_rcp_f32_e32 v92, v92
	v_rcp_f32_e32 v93, v93
	v_add_f32_e32 v94, 1.0, v94
	v_add_f32_e32 v95, 1.0, v95
	v_rcp_f32_e32 v94, v94
	v_rcp_f32_e32 v95, v95
	v_pk_mul_f32 v[76:77], v[76:77], v[156:157] op_sel_hi:[1,0]
	v_pk_mul_f32 v[88:89], v[88:89], v[92:93]
	v_pk_mul_f32 v[78:79], v[78:79], v[156:157] op_sel_hi:[1,0]
	v_pk_mul_f32 v[88:89], v[76:77], v[88:89]
	v_pk_mul_f32 v[76:77], v[90:91], v[94:95]
	v_or_b32_e32 v92, 32, v144
	v_pk_mul_f32 v[90:91], v[78:79], v[76:77]
	v_cvt_pk_bf16_f32 v76, v84, v85
	v_mad_i64_i32 v[84:85], s[28:29], v92, s68, v[108:109]
	v_cvt_pk_bf16_f32 v77, v86, v87
	v_cvt_pk_bf16_f32 v78, v88, v89
	v_cvt_pk_bf16_f32 v79, v90, v91
	v_lshl_add_u64 v[84:85], v[84:85], 0, v[110:111]
	global_store_dwordx4 v[84:85], v[76:79], off sc1
	v_pk_mul_f32 v[70:71], v[70:71], v[154:155] op_sel_hi:[1,0]
	v_pk_mul_f32 v[72:73], v[72:73], v[154:155] op_sel_hi:[1,0]
	v_pk_mul_f32 v[76:77], v[82:83], v[154:155] op_sel_hi:[1,0]
	v_pk_mul_f32 v[78:79], v[80:81], v[154:155] op_sel_hi:[1,0]
	v_mul_f32_e32 v82, 0xbfb8aa3b, v76
	v_mul_f32_e32 v83, 0xbfb8aa3b, v77
	v_mul_f32_e32 v80, 0xbfb8aa3b, v78
	v_mul_f32_e32 v81, 0xbfb8aa3b, v79
	v_exp_f32_e32 v82, v82
	v_exp_f32_e32 v83, v83
	v_exp_f32_e32 v80, v80
	v_exp_f32_e32 v81, v81
	v_add_f32_e32 v82, 1.0, v82
	v_add_f32_e32 v83, 1.0, v83
	v_add_f32_e32 v80, 1.0, v80
	v_add_f32_e32 v81, 1.0, v81
	v_rcp_f32_e32 v82, v82
	v_rcp_f32_e32 v83, v83
	v_rcp_f32_e32 v80, v80
	v_rcp_f32_e32 v81, v81
	v_pk_mul_f32 v[68:69], v[68:69], v[154:155] op_sel_hi:[1,0]
	v_pk_mul_f32 v[76:77], v[76:77], v[82:83]
	v_pk_mul_f32 v[74:75], v[74:75], v[154:155] op_sel_hi:[1,0]
	v_pk_mul_f32 v[78:79], v[78:79], v[80:81]
	v_pk_mul_f32 v[70:71], v[70:71], v[76:77]
	v_mul_f32_e32 v76, 0xbfb8aa3b, v72
	v_mul_f32_e32 v77, 0xbfb8aa3b, v73
	v_pk_mul_f32 v[68:69], v[68:69], v[78:79]
	v_exp_f32_e32 v76, v76
	v_exp_f32_e32 v77, v77
	v_mul_f32_e32 v78, 0xbfb8aa3b, v74
	v_mul_f32_e32 v79, 0xbfb8aa3b, v75
	v_exp_f32_e32 v78, v78
	v_exp_f32_e32 v79, v79
	v_add_f32_e32 v76, 1.0, v76
	v_add_f32_e32 v77, 1.0, v77
	v_rcp_f32_e32 v76, v76
	v_rcp_f32_e32 v77, v77
	v_add_f32_e32 v78, 1.0, v78
	v_add_f32_e32 v79, 1.0, v79
	v_rcp_f32_e32 v78, v78
	v_rcp_f32_e32 v79, v79
	v_pk_mul_f32 v[64:65], v[64:65], v[154:155] op_sel_hi:[1,0]
	v_pk_mul_f32 v[72:73], v[72:73], v[76:77]
	v_pk_mul_f32 v[66:67], v[66:67], v[154:155] op_sel_hi:[1,0]
	v_pk_mul_f32 v[72:73], v[64:65], v[72:73]
	v_pk_mul_f32 v[64:65], v[74:75], v[78:79]
	v_or_b32_e32 v76, 48, v144
	v_pk_mul_f32 v[74:75], v[66:67], v[64:65]
	v_cvt_pk_bf16_f32 v64, v68, v69
	v_mad_i64_i32 v[68:69], s[28:29], v76, s68, v[108:109]
	v_cvt_pk_bf16_f32 v65, v70, v71
	v_cvt_pk_bf16_f32 v66, v72, v73
	v_cvt_pk_bf16_f32 v67, v74, v75
	v_lshl_add_u64 v[68:69], v[68:69], 0, v[110:111]
	v_pk_mul_f32 v[60:61], v[60:61], v[152:153] op_sel_hi:[1,0]
	global_store_dwordx4 v[68:69], v[64:67], off sc1
	v_pk_mul_f32 v[62:63], v[62:63], v[152:153] op_sel_hi:[1,0]
	v_pk_mul_f32 v[52:53], v[52:53], v[152:153] op_sel_hi:[1,0]
	v_mul_f32_e32 v64, 0xbfb8aa3b, v60
	v_mul_f32_e32 v65, 0xbfb8aa3b, v61
	v_exp_f32_e32 v64, v64
	v_exp_f32_e32 v65, v65
	v_mul_f32_e32 v66, 0xbfb8aa3b, v62
	v_mul_f32_e32 v67, 0xbfb8aa3b, v63
	v_exp_f32_e32 v66, v66
	v_exp_f32_e32 v67, v67
	v_add_f32_e32 v64, 1.0, v64
	v_add_f32_e32 v65, 1.0, v65
	v_rcp_f32_e32 v64, v64
	v_rcp_f32_e32 v65, v65
	v_add_f32_e32 v66, 1.0, v66
	v_add_f32_e32 v67, 1.0, v67
	v_rcp_f32_e32 v66, v66
	v_rcp_f32_e32 v67, v67
	v_pk_mul_f32 v[60:61], v[60:61], v[64:65]
	v_pk_mul_f32 v[54:55], v[54:55], v[152:153] op_sel_hi:[1,0]
	v_pk_mul_f32 v[52:53], v[52:53], v[60:61]
	v_pk_mul_f32 v[60:61], v[62:63], v[66:67]
	v_pk_mul_f32 v[56:57], v[56:57], v[152:153] op_sel_hi:[1,0]
	v_pk_mul_f32 v[54:55], v[54:55], v[60:61]
	v_pk_mul_f32 v[58:59], v[58:59], v[152:153] op_sel_hi:[1,0]
	v_mul_f32_e32 v60, 0xbfb8aa3b, v56
	v_mul_f32_e32 v61, 0xbfb8aa3b, v57
	v_exp_f32_e32 v60, v60
	v_exp_f32_e32 v61, v61
	v_mul_f32_e32 v62, 0xbfb8aa3b, v58
	v_mul_f32_e32 v63, 0xbfb8aa3b, v59
	v_exp_f32_e32 v62, v62
	v_exp_f32_e32 v63, v63
	v_add_f32_e32 v60, 1.0, v60
	v_add_f32_e32 v61, 1.0, v61
	v_rcp_f32_e32 v60, v60
	v_rcp_f32_e32 v61, v61
	v_add_f32_e32 v62, 1.0, v62
	v_add_f32_e32 v63, 1.0, v63
	v_rcp_f32_e32 v62, v62
	v_rcp_f32_e32 v63, v63
	v_fmamk_f32 v150, v150, 0x3a800000, v168
	v_rsq_f32_e32 v150, v150
	v_pk_mul_f32 v[44:45], v[44:45], v[152:153] op_sel_hi:[1,0]
	v_pk_mul_f32 v[56:57], v[56:57], v[60:61]
	v_pk_mul_f32 v[46:47], v[46:47], v[152:153] op_sel_hi:[1,0]
	v_pk_mul_f32 v[56:57], v[44:45], v[56:57]
	v_pk_mul_f32 v[44:45], v[58:59], v[62:63]
	v_pk_mul_f32 v[38:39], v[38:39], v[150:151] op_sel_hi:[1,0]
	v_pk_mul_f32 v[58:59], v[46:47], v[44:45]
	v_cvt_pk_bf16_f32 v44, v52, v53
	v_mad_i64_i32 v[52:53], s[28:29], v145, s68, v[108:109]
	v_cvt_pk_bf16_f32 v45, v54, v55
	v_cvt_pk_bf16_f32 v46, v56, v57
	v_cvt_pk_bf16_f32 v47, v58, v59
	v_lshl_add_u64 v[52:53], v[52:53], 0, v[110:111]
	global_store_dwordx4 v[52:53], v[44:47], off sc1
	v_pk_mul_f32 v[40:41], v[40:41], v[150:151] op_sel_hi:[1,0]
	v_pk_mul_f32 v[36:37], v[36:37], v[150:151] op_sel_hi:[1,0]
	v_pk_mul_f32 v[44:45], v[50:51], v[150:151] op_sel_hi:[1,0]
	v_pk_mul_f32 v[46:47], v[48:49], v[150:151] op_sel_hi:[1,0]
	v_mul_f32_e32 v50, 0xbfb8aa3b, v44
	v_mul_f32_e32 v51, 0xbfb8aa3b, v45
	v_mul_f32_e32 v48, 0xbfb8aa3b, v46
	v_mul_f32_e32 v49, 0xbfb8aa3b, v47
	v_exp_f32_e32 v50, v50
	v_exp_f32_e32 v51, v51
	v_exp_f32_e32 v48, v48
	v_exp_f32_e32 v49, v49
	v_add_f32_e32 v50, 1.0, v50
	v_add_f32_e32 v51, 1.0, v51
	v_add_f32_e32 v48, 1.0, v48
	v_add_f32_e32 v49, 1.0, v49
	v_rcp_f32_e32 v50, v50
	v_rcp_f32_e32 v51, v51
	v_rcp_f32_e32 v48, v48
	v_rcp_f32_e32 v49, v49
	v_pk_mul_f32 v[42:43], v[42:43], v[150:151] op_sel_hi:[1,0]
	v_pk_mul_f32 v[44:45], v[44:45], v[50:51]
	v_fmamk_f32 v148, v148, 0x3a800000, v168
	v_pk_mul_f32 v[46:47], v[46:47], v[48:49]
	v_pk_mul_f32 v[38:39], v[38:39], v[44:45]
	v_mul_f32_e32 v44, 0xbfb8aa3b, v40
	v_mul_f32_e32 v45, 0xbfb8aa3b, v41
	v_pk_mul_f32 v[36:37], v[36:37], v[46:47]
	v_exp_f32_e32 v44, v44
	v_exp_f32_e32 v45, v45
	v_mul_f32_e32 v46, 0xbfb8aa3b, v42
	v_mul_f32_e32 v47, 0xbfb8aa3b, v43
	v_exp_f32_e32 v46, v46
	v_exp_f32_e32 v47, v47
	v_add_f32_e32 v44, 1.0, v44
	v_add_f32_e32 v45, 1.0, v45
	v_rcp_f32_e32 v44, v44
	v_rcp_f32_e32 v45, v45
	v_add_f32_e32 v46, 1.0, v46
	v_add_f32_e32 v47, 1.0, v47
	v_rcp_f32_e32 v46, v46
	v_rcp_f32_e32 v47, v47
	v_rsq_f32_e32 v148, v148
	v_pk_mul_f32 v[28:29], v[28:29], v[150:151] op_sel_hi:[1,0]
	v_pk_mul_f32 v[40:41], v[40:41], v[44:45]
	v_pk_mul_f32 v[30:31], v[30:31], v[150:151] op_sel_hi:[1,0]
	v_pk_mul_f32 v[40:41], v[28:29], v[40:41]
	v_pk_mul_f32 v[28:29], v[42:43], v[46:47]
	v_add_u32_e32 v44, 0x90, v144
	v_pk_mul_f32 v[42:43], v[30:31], v[28:29]
	v_cvt_pk_bf16_f32 v28, v36, v37
	v_mad_i64_i32 v[36:37], s[28:29], v44, s68, v[108:109]
	v_cvt_pk_bf16_f32 v29, v38, v39
	v_cvt_pk_bf16_f32 v30, v40, v41
	v_cvt_pk_bf16_f32 v31, v42, v43
	v_lshl_add_u64 v[36:37], v[36:37], 0, v[110:111]
	global_store_dwordx4 v[36:37], v[28:31], off sc1
	v_pk_mul_f32 v[22:23], v[22:23], v[148:149] op_sel_hi:[1,0]
	v_pk_mul_f32 v[24:25], v[24:25], v[148:149] op_sel_hi:[1,0]
	v_pk_mul_f32 v[28:29], v[34:35], v[148:149] op_sel_hi:[1,0]
	v_pk_mul_f32 v[30:31], v[32:33], v[148:149] op_sel_hi:[1,0]
	v_mul_f32_e32 v34, 0xbfb8aa3b, v28
	v_mul_f32_e32 v35, 0xbfb8aa3b, v29
	v_mul_f32_e32 v32, 0xbfb8aa3b, v30
	v_mul_f32_e32 v33, 0xbfb8aa3b, v31
	v_exp_f32_e32 v34, v34
	v_exp_f32_e32 v35, v35
	v_exp_f32_e32 v32, v32
	v_exp_f32_e32 v33, v33
	v_add_f32_e32 v34, 1.0, v34
	v_add_f32_e32 v35, 1.0, v35
	v_add_f32_e32 v32, 1.0, v32
	v_add_f32_e32 v33, 1.0, v33
	v_rcp_f32_e32 v34, v34
	v_rcp_f32_e32 v35, v35
	v_rcp_f32_e32 v32, v32
	v_rcp_f32_e32 v33, v33
	v_pk_mul_f32 v[20:21], v[20:21], v[148:149] op_sel_hi:[1,0]
	v_pk_mul_f32 v[28:29], v[28:29], v[34:35]
	v_pk_mul_f32 v[26:27], v[26:27], v[148:149] op_sel_hi:[1,0]
	v_pk_mul_f32 v[30:31], v[30:31], v[32:33]
	v_pk_mul_f32 v[22:23], v[22:23], v[28:29]
	v_mul_f32_e32 v28, 0xbfb8aa3b, v24
	v_mul_f32_e32 v29, 0xbfb8aa3b, v25
	v_pk_mul_f32 v[20:21], v[20:21], v[30:31]
	v_exp_f32_e32 v28, v28
	v_exp_f32_e32 v29, v29
	v_mul_f32_e32 v30, 0xbfb8aa3b, v26
	v_mul_f32_e32 v31, 0xbfb8aa3b, v27
	v_exp_f32_e32 v30, v30
	v_exp_f32_e32 v31, v31
	v_add_f32_e32 v28, 1.0, v28
	v_add_f32_e32 v29, 1.0, v29
	v_rcp_f32_e32 v28, v28
	v_rcp_f32_e32 v29, v29
	v_add_f32_e32 v30, 1.0, v30
	v_add_f32_e32 v31, 1.0, v31
	v_rcp_f32_e32 v30, v30
	v_rcp_f32_e32 v31, v31
	v_fmamk_f32 v146, v146, 0x3a800000, v168
	v_rsq_f32_e32 v146, v146
	v_pk_mul_f32 v[12:13], v[12:13], v[148:149] op_sel_hi:[1,0]
	v_pk_mul_f32 v[24:25], v[24:25], v[28:29]
	v_pk_mul_f32 v[14:15], v[14:15], v[148:149] op_sel_hi:[1,0]
	v_pk_mul_f32 v[24:25], v[12:13], v[24:25]
	v_pk_mul_f32 v[12:13], v[26:27], v[30:31]
	v_add_u32_e32 v28, 0xa0, v144
	v_pk_mul_f32 v[26:27], v[14:15], v[12:13]
	v_cvt_pk_bf16_f32 v12, v20, v21
	v_mad_i64_i32 v[20:21], s[28:29], v28, s68, v[108:109]
	v_cvt_pk_bf16_f32 v13, v22, v23
	v_cvt_pk_bf16_f32 v14, v24, v25
	v_cvt_pk_bf16_f32 v15, v26, v27
	v_lshl_add_u64 v[20:21], v[20:21], 0, v[110:111]
	global_store_dwordx4 v[20:21], v[12:15], off sc1
	v_pk_mul_f32 v[6:7], v[6:7], v[146:147] op_sel_hi:[1,0]
	v_pk_mul_f32 v[8:9], v[8:9], v[146:147] op_sel_hi:[1,0]
	v_pk_mul_f32 v[12:13], v[18:19], v[146:147] op_sel_hi:[1,0]
	v_pk_mul_f32 v[14:15], v[16:17], v[146:147] op_sel_hi:[1,0]
	v_mul_f32_e32 v18, 0xbfb8aa3b, v12
	v_mul_f32_e32 v19, 0xbfb8aa3b, v13
	v_mul_f32_e32 v16, 0xbfb8aa3b, v14
	v_mul_f32_e32 v17, 0xbfb8aa3b, v15
	v_exp_f32_e32 v18, v18
	v_exp_f32_e32 v19, v19
	v_exp_f32_e32 v16, v16
	v_exp_f32_e32 v17, v17
	v_add_f32_e32 v18, 1.0, v18
	v_add_f32_e32 v19, 1.0, v19
	v_add_f32_e32 v16, 1.0, v16
	v_add_f32_e32 v17, 1.0, v17
	v_rcp_f32_e32 v18, v18
	v_rcp_f32_e32 v19, v19
	v_rcp_f32_e32 v16, v16
	v_rcp_f32_e32 v17, v17
	v_pk_mul_f32 v[4:5], v[4:5], v[146:147] op_sel_hi:[1,0]
	v_pk_mul_f32 v[12:13], v[12:13], v[18:19]
	v_pk_mul_f32 v[10:11], v[10:11], v[146:147] op_sel_hi:[1,0]
	v_pk_mul_f32 v[14:15], v[14:15], v[16:17]
	v_pk_mul_f32 v[6:7], v[6:7], v[12:13]
	v_mul_f32_e32 v12, 0xbfb8aa3b, v8
	v_mul_f32_e32 v13, 0xbfb8aa3b, v9
	v_pk_mul_f32 v[4:5], v[4:5], v[14:15]
	v_exp_f32_e32 v12, v12
	v_exp_f32_e32 v13, v13
	v_mul_f32_e32 v14, 0xbfb8aa3b, v10
	v_mul_f32_e32 v15, 0xbfb8aa3b, v11
	v_exp_f32_e32 v14, v14
	v_exp_f32_e32 v15, v15
	v_add_f32_e32 v12, 1.0, v12
	v_add_f32_e32 v13, 1.0, v13
	v_rcp_f32_e32 v12, v12
	v_rcp_f32_e32 v13, v13
	v_add_f32_e32 v14, 1.0, v14
	v_add_f32_e32 v15, 1.0, v15
	v_rcp_f32_e32 v14, v14
	v_rcp_f32_e32 v15, v15
	v_pk_mul_f32 v[0:1], v[0:1], v[146:147] op_sel_hi:[1,0]
	v_pk_mul_f32 v[8:9], v[8:9], v[12:13]
	v_pk_mul_f32 v[2:3], v[2:3], v[146:147] op_sel_hi:[1,0]
	v_pk_mul_f32 v[8:9], v[0:1], v[8:9]
	v_pk_mul_f32 v[0:1], v[10:11], v[14:15]
	v_add_u32_e32 v12, 0xb0, v144
	v_pk_mul_f32 v[10:11], v[2:3], v[0:1]
	v_cvt_pk_bf16_f32 v0, v4, v5
	v_mad_i64_i32 v[4:5], s[28:29], v12, s68, v[108:109]
	v_cvt_pk_bf16_f32 v1, v6, v7
	v_cvt_pk_bf16_f32 v2, v8, v9
	v_cvt_pk_bf16_f32 v3, v10, v11
	v_lshl_add_u64 v[4:5], v[4:5], 0, v[110:111]
	global_store_dwordx4 v[4:5], v[0:3], off sc1
	s_cbranch_scc1 .LBB0_1226
	s_waitcnt vmcnt(0)
	buffer_wbl2 sc1
	s_waitcnt vmcnt(0)
	s_waitcnt vmcnt(0)
	s_and_saveexec_b64 s[28:29], s[4:5]
	s_cbranch_execz .LBB0_1225
	s_mov_b64 s[30:31], exec
	v_mbcnt_lo_u32_b32 v0, s30, 0
	v_mbcnt_hi_u32_b32 v0, s31, v0
	v_cmp_eq_u32_e32 vcc, 0, v0
	s_and_b64 s[34:35], exec, vcc
	s_mov_b64 exec, s[34:35]
	s_cbranch_execz .LBB0_1225
	s_bcnt1_i32_b64 s11, s[30:31]
	v_mov_b32_e32 v0, s11
	global_atomic_add v129, v0, s[8:9]
	s_branch .LBB0_1225
